# GLA state/out phases: per-token log-gate values computed once and kept in registers for the second pass (both 32-step loops unrolled)
# speedup vs baseline: 1.0145x; 1.0044x over previous
; DEVI float logsigf_(float x) { return fminf(x, 0.f) - __logf(1.f + __expf(-fabsf(x))); }
; DEVI float gla_la(const float* gl, int t, const float* w2r, float gb) { float x = gb;
; #pragma unroll
;     for (int r = 0; r < 16; ++r) x += gl[t * 16 + r] * w2r[r];
;     return logsigf_(x) * (1.f / 16.f); }
; template <int KIND>
; DEVI void mix_state_phase(unsigned char* smem, const MixArgs a) {
;     ...
;             const int ch = tid & 127, sg = tid >> 7; float w2r[16];
; #pragma unroll
;             for (int r = 0; r < 16; ++r) w2r[r] = a.w2[r * 512 + h * 128 + ch];
;             const float gb = a.gateb[h * 128 + ch]; float ssum = 0.f;
;             for (int t = sg * 32; t < sg * 32 + 32; ++t) ssum += gla_la(gl, t, w2r, gb);
.LBB0_514:
	v_add_u32_e32 v123, s0, v99
	ds_read_b128 v[124:127], v123
	ds_read_b128 v[128:131], v123 offset:16
	ds_read_b128 v[132:135], v123 offset:32
	ds_read_b128 v[136:139], v123 offset:48
	ds_read_b128 v[176:179], v123 offset:64
	ds_read_b128 v[180:183], v123 offset:80
	ds_read_b128 v[184:187], v123 offset:96
	ds_read_b128 v[188:191], v123 offset:112
	s_addk_i32 s0, 0x80
	s_waitcnt vmcnt(1) lgkmcnt(7)
	v_fma_f32 v140, v119, v124, v8
	v_fmac_f32_e32 v140, v120, v125
	v_fmac_f32_e32 v140, v116, v126
	v_fmac_f32_e32 v140, v121, v127
	s_waitcnt lgkmcnt(6)
	v_fmac_f32_e32 v140, v117, v128
	v_fmac_f32_e32 v140, v118, v129
	v_pk_mul_f32 v[124:125], v[50:51], v[130:131]
	v_add_f32_e32 v124, v140, v124
	v_add_f32_e32 v126, v124, v125
	s_waitcnt lgkmcnt(5)
	v_pk_mul_f32 v[124:125], v[52:53], v[132:133]
	s_nop 0
	v_add_f32_e32 v124, v126, v124
	v_add_f32_e32 v126, v124, v125
	v_pk_mul_f32 v[124:125], v[88:89], v[134:135]
	s_nop 0
	v_add_f32_e32 v124, v126, v124
	v_add_f32_e32 v126, v124, v125
	s_waitcnt lgkmcnt(4)
	v_pk_mul_f32 v[124:125], v[90:91], v[136:137]
	s_nop 0
	v_add_f32_e32 v124, v126, v124
	v_add_f32_e32 v126, v124, v125
	s_waitcnt vmcnt(0)
	v_pk_mul_f32 v[124:125], v[92:93], v[138:139]
	s_nop 0
	v_add_f32_e32 v124, v126, v124
	v_add_f32_e32 v124, v124, v125
	v_min_f32_e32 v125, 0, v124
	v_mul_f32_e64 v124, |v124|, s73
	v_exp_f32_e32 v124, v124
	s_nop 0
	v_add_f32_e32 v124, 1.0, v124
	v_cmp_gt_f32_e32 vcc, s94, v124
	s_nop 1
	v_cndmask_b32_e64 v126, 0, 32, vcc
	v_ldexp_f32 v124, v124, v126
	v_log_f32_e32 v124, v124
	s_nop 0
	v_mul_f32_e32 v126, 0x3f317217, v124
	v_fma_f32 v126, v124, s97, -v126
	v_fmac_f32_e32 v126, 0x3377d1cf, v124
	v_fmac_f32_e32 v126, 0x3f317217, v124
	v_cmp_lt_f32_e64 s[12:13], |v124|, s23
	s_nop 1
	v_cndmask_b32_e64 v124, v124, v126, s[12:13]
	v_cndmask_b32_e32 v126, 0, v211, vcc
	v_sub_f32_e32 v124, v124, v126
	v_sub_f32_e32 v124, v125, v124
	v_fmac_f32_e32 v122, 0x3d800000, v124
	v_mov_b32_e32 v192, v124
	s_waitcnt lgkmcnt(0)
	v_fma_f32 v128, v119, v176, v8
	v_fmac_f32_e32 v128, v120, v177
	v_fmac_f32_e32 v128, v116, v178
	v_fmac_f32_e32 v128, v121, v179
	v_fmac_f32_e32 v128, v117, v180
	v_fmac_f32_e32 v128, v118, v181
	v_pk_mul_f32 v[124:125], v[50:51], v[182:183]
	s_nop 0
	v_add_f32_e32 v124, v128, v124
	v_add_f32_e32 v128, v124, v125
	v_pk_mul_f32 v[124:125], v[52:53], v[184:185]
	s_nop 0
	v_add_f32_e32 v124, v128, v124
	v_add_f32_e32 v128, v124, v125
	v_pk_mul_f32 v[124:125], v[88:89], v[186:187]
	s_nop 0
	v_add_f32_e32 v124, v128, v124
	v_add_f32_e32 v128, v124, v125
	v_pk_mul_f32 v[124:125], v[90:91], v[188:189]
	s_nop 0
	v_add_f32_e32 v123, v128, v124
	v_add_f32_e32 v123, v123, v125
	v_pk_mul_f32 v[124:125], v[92:93], v[190:191]
	s_nop 0
	v_add_f32_e32 v123, v123, v124
	v_add_f32_e32 v123, v123, v125
	v_min_f32_e32 v124, 0, v123
	v_mul_f32_e64 v123, |v123|, s73
	v_exp_f32_e32 v123, v123
	s_nop 0
	v_add_f32_e32 v123, 1.0, v123
	v_cmp_gt_f32_e32 vcc, s94, v123
	s_nop 1
	v_cndmask_b32_e64 v125, 0, 32, vcc
	v_ldexp_f32 v123, v123, v125
	v_log_f32_e32 v123, v123
	s_nop 0
	v_mul_f32_e32 v125, 0x3f317217, v123
	v_fma_f32 v125, v123, s97, -v125
	v_fmac_f32_e32 v125, 0x3377d1cf, v123
	v_fmac_f32_e32 v125, 0x3f317217, v123
	v_cmp_lt_f32_e64 s[12:13], |v123|, s23
	s_nop 1
	v_cndmask_b32_e64 v123, v123, v125, s[12:13]
	v_cndmask_b32_e32 v125, 0, v211, vcc
	v_sub_f32_e32 v123, v123, v125
	v_sub_f32_e32 v123, v124, v123
	v_fmac_f32_e32 v122, 0x3d800000, v123
	v_mov_b32_e32 v193, v123
	v_add_u32_e32 v123, s0, v99
	ds_read_b128 v[124:127], v123
	ds_read_b128 v[128:131], v123 offset:16
	ds_read_b128 v[132:135], v123 offset:32
	ds_read_b128 v[136:139], v123 offset:48
	ds_read_b128 v[176:179], v123 offset:64
	ds_read_b128 v[180:183], v123 offset:80
	ds_read_b128 v[184:187], v123 offset:96
	ds_read_b128 v[188:191], v123 offset:112
	s_addk_i32 s0, 0x80
	s_waitcnt vmcnt(1) lgkmcnt(7)
	v_fma_f32 v140, v119, v124, v8
	v_fmac_f32_e32 v140, v120, v125
	v_fmac_f32_e32 v140, v116, v126
	v_fmac_f32_e32 v140, v121, v127
	s_waitcnt lgkmcnt(6)
	v_fmac_f32_e32 v140, v117, v128
	v_fmac_f32_e32 v140, v118, v129
	v_pk_mul_f32 v[124:125], v[50:51], v[130:131]
	v_add_f32_e32 v124, v140, v124
	v_add_f32_e32 v126, v124, v125
	s_waitcnt lgkmcnt(5)
	v_pk_mul_f32 v[124:125], v[52:53], v[132:133]
	s_nop 0
	v_add_f32_e32 v124, v126, v124
	v_add_f32_e32 v126, v124, v125
	v_pk_mul_f32 v[124:125], v[88:89], v[134:135]
	s_nop 0
	v_add_f32_e32 v124, v126, v124
	v_add_f32_e32 v126, v124, v125
	s_waitcnt lgkmcnt(4)
	v_pk_mul_f32 v[124:125], v[90:91], v[136:137]
	s_nop 0
	v_add_f32_e32 v124, v126, v124
	v_add_f32_e32 v126, v124, v125
	s_waitcnt vmcnt(0)
	v_pk_mul_f32 v[124:125], v[92:93], v[138:139]
	s_nop 0
	v_add_f32_e32 v124, v126, v124
	v_add_f32_e32 v124, v124, v125
	v_min_f32_e32 v125, 0, v124
	v_mul_f32_e64 v124, |v124|, s73
	v_exp_f32_e32 v124, v124
	s_nop 0
	v_add_f32_e32 v124, 1.0, v124
	v_cmp_gt_f32_e32 vcc, s94, v124
	s_nop 1
	v_cndmask_b32_e64 v126, 0, 32, vcc
	v_ldexp_f32 v124, v124, v126
	v_log_f32_e32 v124, v124
	s_nop 0
	v_mul_f32_e32 v126, 0x3f317217, v124
	v_fma_f32 v126, v124, s97, -v126
	v_fmac_f32_e32 v126, 0x3377d1cf, v124
	v_fmac_f32_e32 v126, 0x3f317217, v124
	v_cmp_lt_f32_e64 s[12:13], |v124|, s23
	s_nop 1
	v_cndmask_b32_e64 v124, v124, v126, s[12:13]
	v_cndmask_b32_e32 v126, 0, v211, vcc
	v_sub_f32_e32 v124, v124, v126
	v_sub_f32_e32 v124, v125, v124
	v_fmac_f32_e32 v122, 0x3d800000, v124
	v_mov_b32_e32 v194, v124
	s_waitcnt lgkmcnt(0)
; DEVI float logsigf_(float x) { return fminf(x, 0.f) - __logf(1.f + __expf(-fabsf(x))); }
; DEVI float gla_la(const float* gl, int t, const float* w2r, float gb) { float x = gb;
; #pragma unroll
;     for (int r = 0; r < 16; ++r) x += gl[t * 16 + r] * w2r[r];
;     return logsigf_(x) * (1.f / 16.f); }
; template <int KIND>
; DEVI void mix_state_phase(unsigned char* smem, const MixArgs a) {
;     ...
;             const int ch = tid & 127, sg = tid >> 7; float w2r[16];
; #pragma unroll
;             for (int r = 0; r < 16; ++r) w2r[r] = a.w2[r * 512 + h * 128 + ch];
;             const float gb = a.gateb[h * 128 + ch]; float ssum = 0.f;
;             for (int t = sg * 32; t < sg * 32 + 32; ++t) ssum += gla_la(gl, t, w2r, gb);
	v_fma_f32 v128, v119, v176, v8
	v_fmac_f32_e32 v128, v120, v177
	v_fmac_f32_e32 v128, v116, v178
	v_fmac_f32_e32 v128, v121, v179
	v_fmac_f32_e32 v128, v117, v180
	v_fmac_f32_e32 v128, v118, v181
	v_pk_mul_f32 v[124:125], v[50:51], v[182:183]
	s_nop 0
	v_add_f32_e32 v124, v128, v124
	v_add_f32_e32 v128, v124, v125
	v_pk_mul_f32 v[124:125], v[52:53], v[184:185]
	s_nop 0
	v_add_f32_e32 v124, v128, v124
	v_add_f32_e32 v128, v124, v125
	v_pk_mul_f32 v[124:125], v[88:89], v[186:187]
	s_nop 0
	v_add_f32_e32 v124, v128, v124
	v_add_f32_e32 v128, v124, v125
	v_pk_mul_f32 v[124:125], v[90:91], v[188:189]
	s_nop 0
	v_add_f32_e32 v123, v128, v124
	v_add_f32_e32 v123, v123, v125
	v_pk_mul_f32 v[124:125], v[92:93], v[190:191]
	s_nop 0
	v_add_f32_e32 v123, v123, v124
	v_add_f32_e32 v123, v123, v125
	v_min_f32_e32 v124, 0, v123
	v_mul_f32_e64 v123, |v123|, s73
	v_exp_f32_e32 v123, v123
	s_nop 0
	v_add_f32_e32 v123, 1.0, v123
	v_cmp_gt_f32_e32 vcc, s94, v123
	s_nop 1
	v_cndmask_b32_e64 v125, 0, 32, vcc
	v_ldexp_f32 v123, v123, v125
	v_log_f32_e32 v123, v123
	s_nop 0
	v_mul_f32_e32 v125, 0x3f317217, v123
	v_fma_f32 v125, v123, s97, -v125
	v_fmac_f32_e32 v125, 0x3377d1cf, v123
	v_fmac_f32_e32 v125, 0x3f317217, v123
	v_cmp_lt_f32_e64 s[12:13], |v123|, s23
	s_nop 1
	v_cndmask_b32_e64 v123, v123, v125, s[12:13]
	v_cndmask_b32_e32 v125, 0, v211, vcc
	v_sub_f32_e32 v123, v123, v125
	v_sub_f32_e32 v123, v124, v123
	v_fmac_f32_e32 v122, 0x3d800000, v123
	v_mov_b32_e32 v195, v123
	v_add_u32_e32 v123, s0, v99
	ds_read_b128 v[124:127], v123
	ds_read_b128 v[128:131], v123 offset:16
	ds_read_b128 v[132:135], v123 offset:32
	ds_read_b128 v[136:139], v123 offset:48
	ds_read_b128 v[176:179], v123 offset:64
	ds_read_b128 v[180:183], v123 offset:80
	ds_read_b128 v[184:187], v123 offset:96
	ds_read_b128 v[188:191], v123 offset:112
	s_addk_i32 s0, 0x80
	s_waitcnt vmcnt(1) lgkmcnt(7)
	v_fma_f32 v140, v119, v124, v8
	v_fmac_f32_e32 v140, v120, v125
	v_fmac_f32_e32 v140, v116, v126
	v_fmac_f32_e32 v140, v121, v127
	s_waitcnt lgkmcnt(6)
	v_fmac_f32_e32 v140, v117, v128
	v_fmac_f32_e32 v140, v118, v129
	v_pk_mul_f32 v[124:125], v[50:51], v[130:131]
	v_add_f32_e32 v124, v140, v124
	v_add_f32_e32 v126, v124, v125
	s_waitcnt lgkmcnt(5)
	v_pk_mul_f32 v[124:125], v[52:53], v[132:133]
	s_nop 0
	v_add_f32_e32 v124, v126, v124
	v_add_f32_e32 v126, v124, v125
	v_pk_mul_f32 v[124:125], v[88:89], v[134:135]
	s_nop 0
	v_add_f32_e32 v124, v126, v124
	v_add_f32_e32 v126, v124, v125
	s_waitcnt lgkmcnt(4)
	v_pk_mul_f32 v[124:125], v[90:91], v[136:137]
	s_nop 0
	v_add_f32_e32 v124, v126, v124
	v_add_f32_e32 v126, v124, v125
	s_waitcnt vmcnt(0)
	v_pk_mul_f32 v[124:125], v[92:93], v[138:139]
	s_nop 0
	v_add_f32_e32 v124, v126, v124
	v_add_f32_e32 v124, v124, v125
	v_min_f32_e32 v125, 0, v124
	v_mul_f32_e64 v124, |v124|, s73
	v_exp_f32_e32 v124, v124
	s_nop 0
	v_add_f32_e32 v124, 1.0, v124
	v_cmp_gt_f32_e32 vcc, s94, v124
	s_nop 1
	v_cndmask_b32_e64 v126, 0, 32, vcc
	v_ldexp_f32 v124, v124, v126
	v_log_f32_e32 v124, v124
	s_nop 0
	v_mul_f32_e32 v126, 0x3f317217, v124
	v_fma_f32 v126, v124, s97, -v126
	v_fmac_f32_e32 v126, 0x3377d1cf, v124
	v_fmac_f32_e32 v126, 0x3f317217, v124
	v_cmp_lt_f32_e64 s[12:13], |v124|, s23
	s_nop 1
	v_cndmask_b32_e64 v124, v124, v126, s[12:13]
	v_cndmask_b32_e32 v126, 0, v211, vcc
	v_sub_f32_e32 v124, v124, v126
	v_sub_f32_e32 v124, v125, v124
	v_fmac_f32_e32 v122, 0x3d800000, v124
	v_mov_b32_e32 v196, v124
	s_waitcnt lgkmcnt(0)
	v_fma_f32 v128, v119, v176, v8
	v_fmac_f32_e32 v128, v120, v177
	v_fmac_f32_e32 v128, v116, v178
	v_fmac_f32_e32 v128, v121, v179
	v_fmac_f32_e32 v128, v117, v180
	v_fmac_f32_e32 v128, v118, v181
	v_pk_mul_f32 v[124:125], v[50:51], v[182:183]
	s_nop 0
	v_add_f32_e32 v124, v128, v124
	v_add_f32_e32 v128, v124, v125
	v_pk_mul_f32 v[124:125], v[52:53], v[184:185]
	s_nop 0
	v_add_f32_e32 v124, v128, v124
	v_add_f32_e32 v128, v124, v125
	v_pk_mul_f32 v[124:125], v[88:89], v[186:187]
	s_nop 0
	v_add_f32_e32 v124, v128, v124
	v_add_f32_e32 v128, v124, v125
	v_pk_mul_f32 v[124:125], v[90:91], v[188:189]
	s_nop 0
	v_add_f32_e32 v123, v128, v124
	v_add_f32_e32 v123, v123, v125
	v_pk_mul_f32 v[124:125], v[92:93], v[190:191]
	s_nop 0
	v_add_f32_e32 v123, v123, v124
	v_add_f32_e32 v123, v123, v125
	v_min_f32_e32 v124, 0, v123
	v_mul_f32_e64 v123, |v123|, s73
	v_exp_f32_e32 v123, v123
	s_nop 0
	v_add_f32_e32 v123, 1.0, v123
	v_cmp_gt_f32_e32 vcc, s94, v123
	s_nop 1
	v_cndmask_b32_e64 v125, 0, 32, vcc
	v_ldexp_f32 v123, v123, v125
	v_log_f32_e32 v123, v123
	s_nop 0
	v_mul_f32_e32 v125, 0x3f317217, v123
	v_fma_f32 v125, v123, s97, -v125
	v_fmac_f32_e32 v125, 0x3377d1cf, v123
	v_fmac_f32_e32 v125, 0x3f317217, v123
	v_cmp_lt_f32_e64 s[12:13], |v123|, s23
	s_nop 1
	v_cndmask_b32_e64 v123, v123, v125, s[12:13]
	v_cndmask_b32_e32 v125, 0, v211, vcc
	v_sub_f32_e32 v123, v123, v125
	v_sub_f32_e32 v123, v124, v123
	v_fmac_f32_e32 v122, 0x3d800000, v123
	v_mov_b32_e32 v197, v123
	v_add_u32_e32 v123, s0, v99
	ds_read_b128 v[124:127], v123
	ds_read_b128 v[128:131], v123 offset:16
	ds_read_b128 v[132:135], v123 offset:32
	ds_read_b128 v[136:139], v123 offset:48
	ds_read_b128 v[176:179], v123 offset:64
	ds_read_b128 v[180:183], v123 offset:80
	ds_read_b128 v[184:187], v123 offset:96
	ds_read_b128 v[188:191], v123 offset:112
	s_addk_i32 s0, 0x80
	s_waitcnt vmcnt(1) lgkmcnt(7)
	v_fma_f32 v140, v119, v124, v8
	v_fmac_f32_e32 v140, v120, v125
	v_fmac_f32_e32 v140, v116, v126
	v_fmac_f32_e32 v140, v121, v127
	s_waitcnt lgkmcnt(6)
	v_fmac_f32_e32 v140, v117, v128
	v_fmac_f32_e32 v140, v118, v129
	v_pk_mul_f32 v[124:125], v[50:51], v[130:131]
	v_add_f32_e32 v124, v140, v124
	v_add_f32_e32 v126, v124, v125
	s_waitcnt lgkmcnt(5)
; DEVI float logsigf_(float x) { return fminf(x, 0.f) - __logf(1.f + __expf(-fabsf(x))); }
; DEVI float gla_la(const float* gl, int t, const float* w2r, float gb) { float x = gb;
; #pragma unroll
;     for (int r = 0; r < 16; ++r) x += gl[t * 16 + r] * w2r[r];
;     return logsigf_(x) * (1.f / 16.f); }
; template <int KIND>
; DEVI void mix_state_phase(unsigned char* smem, const MixArgs a) {
;     ...
;             const int ch = tid & 127, sg = tid >> 7; float w2r[16];
; #pragma unroll
;             for (int r = 0; r < 16; ++r) w2r[r] = a.w2[r * 512 + h * 128 + ch];
;             const float gb = a.gateb[h * 128 + ch]; float ssum = 0.f;
;             for (int t = sg * 32; t < sg * 32 + 32; ++t) ssum += gla_la(gl, t, w2r, gb);
	v_pk_mul_f32 v[124:125], v[52:53], v[132:133]
	s_nop 0
	v_add_f32_e32 v124, v126, v124
	v_add_f32_e32 v126, v124, v125
	v_pk_mul_f32 v[124:125], v[88:89], v[134:135]
	s_nop 0
	v_add_f32_e32 v124, v126, v124
	v_add_f32_e32 v126, v124, v125
	s_waitcnt lgkmcnt(4)
	v_pk_mul_f32 v[124:125], v[90:91], v[136:137]
	s_nop 0
	v_add_f32_e32 v124, v126, v124
	v_add_f32_e32 v126, v124, v125
	s_waitcnt vmcnt(0)
	v_pk_mul_f32 v[124:125], v[92:93], v[138:139]
	s_nop 0
	v_add_f32_e32 v124, v126, v124
	v_add_f32_e32 v124, v124, v125
	v_min_f32_e32 v125, 0, v124
	v_mul_f32_e64 v124, |v124|, s73
	v_exp_f32_e32 v124, v124
	s_nop 0
	v_add_f32_e32 v124, 1.0, v124
	v_cmp_gt_f32_e32 vcc, s94, v124
	s_nop 1
	v_cndmask_b32_e64 v126, 0, 32, vcc
	v_ldexp_f32 v124, v124, v126
	v_log_f32_e32 v124, v124
	s_nop 0
	v_mul_f32_e32 v126, 0x3f317217, v124
	v_fma_f32 v126, v124, s97, -v126
	v_fmac_f32_e32 v126, 0x3377d1cf, v124
	v_fmac_f32_e32 v126, 0x3f317217, v124
	v_cmp_lt_f32_e64 s[12:13], |v124|, s23
	s_nop 1
	v_cndmask_b32_e64 v124, v124, v126, s[12:13]
	v_cndmask_b32_e32 v126, 0, v211, vcc
	v_sub_f32_e32 v124, v124, v126
	v_sub_f32_e32 v124, v125, v124
	v_fmac_f32_e32 v122, 0x3d800000, v124
	v_mov_b32_e32 v198, v124
	s_waitcnt lgkmcnt(0)
	v_fma_f32 v128, v119, v176, v8
	v_fmac_f32_e32 v128, v120, v177
	v_fmac_f32_e32 v128, v116, v178
	v_fmac_f32_e32 v128, v121, v179
	v_fmac_f32_e32 v128, v117, v180
	v_fmac_f32_e32 v128, v118, v181
	v_pk_mul_f32 v[124:125], v[50:51], v[182:183]
	s_nop 0
	v_add_f32_e32 v124, v128, v124
	v_add_f32_e32 v128, v124, v125
	v_pk_mul_f32 v[124:125], v[52:53], v[184:185]
	s_nop 0
	v_add_f32_e32 v124, v128, v124
	v_add_f32_e32 v128, v124, v125
	v_pk_mul_f32 v[124:125], v[88:89], v[186:187]
	s_nop 0
	v_add_f32_e32 v124, v128, v124
	v_add_f32_e32 v128, v124, v125
	v_pk_mul_f32 v[124:125], v[90:91], v[188:189]
	s_nop 0
	v_add_f32_e32 v123, v128, v124
	v_add_f32_e32 v123, v123, v125
	v_pk_mul_f32 v[124:125], v[92:93], v[190:191]
	s_nop 0
	v_add_f32_e32 v123, v123, v124
	v_add_f32_e32 v123, v123, v125
	v_min_f32_e32 v124, 0, v123
	v_mul_f32_e64 v123, |v123|, s73
	v_exp_f32_e32 v123, v123
	s_nop 0
	v_add_f32_e32 v123, 1.0, v123
	v_cmp_gt_f32_e32 vcc, s94, v123
	s_nop 1
	v_cndmask_b32_e64 v125, 0, 32, vcc
	v_ldexp_f32 v123, v123, v125
	v_log_f32_e32 v123, v123
	s_nop 0
	v_mul_f32_e32 v125, 0x3f317217, v123
	v_fma_f32 v125, v123, s97, -v125
	v_fmac_f32_e32 v125, 0x3377d1cf, v123
	v_fmac_f32_e32 v125, 0x3f317217, v123
	v_cmp_lt_f32_e64 s[12:13], |v123|, s23
	s_nop 1
	v_cndmask_b32_e64 v123, v123, v125, s[12:13]
	v_cndmask_b32_e32 v125, 0, v211, vcc
	v_sub_f32_e32 v123, v123, v125
	v_sub_f32_e32 v123, v124, v123
	v_fmac_f32_e32 v122, 0x3d800000, v123
	v_mov_b32_e32 v199, v123
	v_add_u32_e32 v123, s0, v99
	ds_read_b128 v[124:127], v123
	ds_read_b128 v[128:131], v123 offset:16
	ds_read_b128 v[132:135], v123 offset:32
	ds_read_b128 v[136:139], v123 offset:48
	ds_read_b128 v[176:179], v123 offset:64
	ds_read_b128 v[180:183], v123 offset:80
	ds_read_b128 v[184:187], v123 offset:96
	ds_read_b128 v[188:191], v123 offset:112
	s_addk_i32 s0, 0x80
	s_waitcnt vmcnt(1) lgkmcnt(7)
	v_fma_f32 v140, v119, v124, v8
	v_fmac_f32_e32 v140, v120, v125
	v_fmac_f32_e32 v140, v116, v126
	v_fmac_f32_e32 v140, v121, v127
	s_waitcnt lgkmcnt(6)
	v_fmac_f32_e32 v140, v117, v128
	v_fmac_f32_e32 v140, v118, v129
	v_pk_mul_f32 v[124:125], v[50:51], v[130:131]
	v_add_f32_e32 v124, v140, v124
	v_add_f32_e32 v126, v124, v125
	s_waitcnt lgkmcnt(5)
	v_pk_mul_f32 v[124:125], v[52:53], v[132:133]
	s_nop 0
	v_add_f32_e32 v124, v126, v124
	v_add_f32_e32 v126, v124, v125
	v_pk_mul_f32 v[124:125], v[88:89], v[134:135]
	s_nop 0
	v_add_f32_e32 v124, v126, v124
	v_add_f32_e32 v126, v124, v125
	s_waitcnt lgkmcnt(4)
	v_pk_mul_f32 v[124:125], v[90:91], v[136:137]
	s_nop 0
	v_add_f32_e32 v124, v126, v124
	v_add_f32_e32 v126, v124, v125
	s_waitcnt vmcnt(0)
	v_pk_mul_f32 v[124:125], v[92:93], v[138:139]
	s_nop 0
	v_add_f32_e32 v124, v126, v124
	v_add_f32_e32 v124, v124, v125
	v_min_f32_e32 v125, 0, v124
	v_mul_f32_e64 v124, |v124|, s73
	v_exp_f32_e32 v124, v124
	s_nop 0
	v_add_f32_e32 v124, 1.0, v124
	v_cmp_gt_f32_e32 vcc, s94, v124
	s_nop 1
	v_cndmask_b32_e64 v126, 0, 32, vcc
	v_ldexp_f32 v124, v124, v126
	v_log_f32_e32 v124, v124
	s_nop 0
	v_mul_f32_e32 v126, 0x3f317217, v124
	v_fma_f32 v126, v124, s97, -v126
	v_fmac_f32_e32 v126, 0x3377d1cf, v124
	v_fmac_f32_e32 v126, 0x3f317217, v124
	v_cmp_lt_f32_e64 s[12:13], |v124|, s23
	s_nop 1
	v_cndmask_b32_e64 v124, v124, v126, s[12:13]
	v_cndmask_b32_e32 v126, 0, v211, vcc
	v_sub_f32_e32 v124, v124, v126
	v_sub_f32_e32 v124, v125, v124
	v_fmac_f32_e32 v122, 0x3d800000, v124
	v_mov_b32_e32 v200, v124
	s_waitcnt lgkmcnt(0)
	v_fma_f32 v128, v119, v176, v8
	v_fmac_f32_e32 v128, v120, v177
	v_fmac_f32_e32 v128, v116, v178
	v_fmac_f32_e32 v128, v121, v179
	v_fmac_f32_e32 v128, v117, v180
	v_fmac_f32_e32 v128, v118, v181
	v_pk_mul_f32 v[124:125], v[50:51], v[182:183]
	s_nop 0
	v_add_f32_e32 v124, v128, v124
	v_add_f32_e32 v128, v124, v125
	v_pk_mul_f32 v[124:125], v[52:53], v[184:185]
	s_nop 0
	v_add_f32_e32 v124, v128, v124
	v_add_f32_e32 v128, v124, v125
	v_pk_mul_f32 v[124:125], v[88:89], v[186:187]
	s_nop 0
	v_add_f32_e32 v124, v128, v124
	v_add_f32_e32 v128, v124, v125
	v_pk_mul_f32 v[124:125], v[90:91], v[188:189]
	s_nop 0
	v_add_f32_e32 v123, v128, v124
	v_add_f32_e32 v123, v123, v125
	v_pk_mul_f32 v[124:125], v[92:93], v[190:191]
	s_nop 0
	v_add_f32_e32 v123, v123, v124
	v_add_f32_e32 v123, v123, v125
	v_min_f32_e32 v124, 0, v123
	v_mul_f32_e64 v123, |v123|, s73
	v_exp_f32_e32 v123, v123
	s_nop 0
	v_add_f32_e32 v123, 1.0, v123
	v_cmp_gt_f32_e32 vcc, s94, v123
	s_nop 1
	v_cndmask_b32_e64 v125, 0, 32, vcc
	v_ldexp_f32 v123, v123, v125
	v_log_f32_e32 v123, v123
	s_nop 0
	v_mul_f32_e32 v125, 0x3f317217, v123
	v_fma_f32 v125, v123, s97, -v125
	v_fmac_f32_e32 v125, 0x3377d1cf, v123
	v_fmac_f32_e32 v125, 0x3f317217, v123
	v_cmp_lt_f32_e64 s[12:13], |v123|, s23
	s_nop 1
	v_cndmask_b32_e64 v123, v123, v125, s[12:13]
	v_cndmask_b32_e32 v125, 0, v211, vcc
	v_sub_f32_e32 v123, v123, v125
	v_sub_f32_e32 v123, v124, v123
	v_fmac_f32_e32 v122, 0x3d800000, v123
	v_mov_b32_e32 v201, v123
	v_add_u32_e32 v123, s0, v99
	ds_read_b128 v[124:127], v123
	ds_read_b128 v[128:131], v123 offset:16
	ds_read_b128 v[132:135], v123 offset:32
	ds_read_b128 v[136:139], v123 offset:48
	ds_read_b128 v[176:179], v123 offset:64
	ds_read_b128 v[180:183], v123 offset:80
	ds_read_b128 v[184:187], v123 offset:96
	ds_read_b128 v[188:191], v123 offset:112
	s_addk_i32 s0, 0x80
	s_waitcnt vmcnt(1) lgkmcnt(7)
; DEVI float logsigf_(float x) { return fminf(x, 0.f) - __logf(1.f + __expf(-fabsf(x))); }
; DEVI float gla_la(const float* gl, int t, const float* w2r, float gb) { float x = gb;
; #pragma unroll
;     for (int r = 0; r < 16; ++r) x += gl[t * 16 + r] * w2r[r];
;     return logsigf_(x) * (1.f / 16.f); }
; template <int KIND>
; DEVI void mix_state_phase(unsigned char* smem, const MixArgs a) {
;     ...
;             const int ch = tid & 127, sg = tid >> 7; float w2r[16];
; #pragma unroll
;             for (int r = 0; r < 16; ++r) w2r[r] = a.w2[r * 512 + h * 128 + ch];
;             const float gb = a.gateb[h * 128 + ch]; float ssum = 0.f;
;             for (int t = sg * 32; t < sg * 32 + 32; ++t) ssum += gla_la(gl, t, w2r, gb);
	v_fma_f32 v140, v119, v124, v8
	v_fmac_f32_e32 v140, v120, v125
	v_fmac_f32_e32 v140, v116, v126
	v_fmac_f32_e32 v140, v121, v127
	s_waitcnt lgkmcnt(6)
	v_fmac_f32_e32 v140, v117, v128
	v_fmac_f32_e32 v140, v118, v129
	v_pk_mul_f32 v[124:125], v[50:51], v[130:131]
	v_add_f32_e32 v124, v140, v124
	v_add_f32_e32 v126, v124, v125
	s_waitcnt lgkmcnt(5)
	v_pk_mul_f32 v[124:125], v[52:53], v[132:133]
	s_nop 0
	v_add_f32_e32 v124, v126, v124
	v_add_f32_e32 v126, v124, v125
	v_pk_mul_f32 v[124:125], v[88:89], v[134:135]
	s_nop 0
	v_add_f32_e32 v124, v126, v124
	v_add_f32_e32 v126, v124, v125
	s_waitcnt lgkmcnt(4)
	v_pk_mul_f32 v[124:125], v[90:91], v[136:137]
	s_nop 0
	v_add_f32_e32 v124, v126, v124
	v_add_f32_e32 v126, v124, v125
	s_waitcnt vmcnt(0)
	v_pk_mul_f32 v[124:125], v[92:93], v[138:139]
	s_nop 0
	v_add_f32_e32 v124, v126, v124
	v_add_f32_e32 v124, v124, v125
	v_min_f32_e32 v125, 0, v124
	v_mul_f32_e64 v124, |v124|, s73
	v_exp_f32_e32 v124, v124
	s_nop 0
	v_add_f32_e32 v124, 1.0, v124
	v_cmp_gt_f32_e32 vcc, s94, v124
	s_nop 1
	v_cndmask_b32_e64 v126, 0, 32, vcc
	v_ldexp_f32 v124, v124, v126
	v_log_f32_e32 v124, v124
	s_nop 0
	v_mul_f32_e32 v126, 0x3f317217, v124
	v_fma_f32 v126, v124, s97, -v126
	v_fmac_f32_e32 v126, 0x3377d1cf, v124
	v_fmac_f32_e32 v126, 0x3f317217, v124
	v_cmp_lt_f32_e64 s[12:13], |v124|, s23
	s_nop 1
	v_cndmask_b32_e64 v124, v124, v126, s[12:13]
	v_cndmask_b32_e32 v126, 0, v211, vcc
	v_sub_f32_e32 v124, v124, v126
	v_sub_f32_e32 v124, v125, v124
	v_fmac_f32_e32 v122, 0x3d800000, v124
	v_mov_b32_e32 v202, v124
	s_waitcnt lgkmcnt(0)
	v_fma_f32 v128, v119, v176, v8
	v_fmac_f32_e32 v128, v120, v177
	v_fmac_f32_e32 v128, v116, v178
	v_fmac_f32_e32 v128, v121, v179
	v_fmac_f32_e32 v128, v117, v180
	v_fmac_f32_e32 v128, v118, v181
	v_pk_mul_f32 v[124:125], v[50:51], v[182:183]
	s_nop 0
	v_add_f32_e32 v124, v128, v124
	v_add_f32_e32 v128, v124, v125
	v_pk_mul_f32 v[124:125], v[52:53], v[184:185]
	s_nop 0
	v_add_f32_e32 v124, v128, v124
	v_add_f32_e32 v128, v124, v125
	v_pk_mul_f32 v[124:125], v[88:89], v[186:187]
	s_nop 0
	v_add_f32_e32 v124, v128, v124
	v_add_f32_e32 v128, v124, v125
	v_pk_mul_f32 v[124:125], v[90:91], v[188:189]
	s_nop 0
	v_add_f32_e32 v123, v128, v124
	v_add_f32_e32 v123, v123, v125
	v_pk_mul_f32 v[124:125], v[92:93], v[190:191]
	s_nop 0
	v_add_f32_e32 v123, v123, v124
	v_add_f32_e32 v123, v123, v125
	v_min_f32_e32 v124, 0, v123
	v_mul_f32_e64 v123, |v123|, s73
	v_exp_f32_e32 v123, v123
	s_nop 0
	v_add_f32_e32 v123, 1.0, v123
	v_cmp_gt_f32_e32 vcc, s94, v123
	s_nop 1
	v_cndmask_b32_e64 v125, 0, 32, vcc
	v_ldexp_f32 v123, v123, v125
	v_log_f32_e32 v123, v123
	s_nop 0
	v_mul_f32_e32 v125, 0x3f317217, v123
	v_fma_f32 v125, v123, s97, -v125
	v_fmac_f32_e32 v125, 0x3377d1cf, v123
	v_fmac_f32_e32 v125, 0x3f317217, v123
	v_cmp_lt_f32_e64 s[12:13], |v123|, s23
	s_nop 1
	v_cndmask_b32_e64 v123, v123, v125, s[12:13]
	v_cndmask_b32_e32 v125, 0, v211, vcc
	v_sub_f32_e32 v123, v123, v125
	v_sub_f32_e32 v123, v124, v123
	v_fmac_f32_e32 v122, 0x3d800000, v123
	v_mov_b32_e32 v203, v123
	v_add_u32_e32 v123, s0, v99
	ds_read_b128 v[124:127], v123
	ds_read_b128 v[128:131], v123 offset:16
	ds_read_b128 v[132:135], v123 offset:32
	ds_read_b128 v[136:139], v123 offset:48
	ds_read_b128 v[176:179], v123 offset:64
	ds_read_b128 v[180:183], v123 offset:80
	ds_read_b128 v[184:187], v123 offset:96
	ds_read_b128 v[188:191], v123 offset:112
	s_addk_i32 s0, 0x80
	s_waitcnt vmcnt(1) lgkmcnt(7)
	v_fma_f32 v140, v119, v124, v8
	v_fmac_f32_e32 v140, v120, v125
	v_fmac_f32_e32 v140, v116, v126
	v_fmac_f32_e32 v140, v121, v127
	s_waitcnt lgkmcnt(6)
	v_fmac_f32_e32 v140, v117, v128
	v_fmac_f32_e32 v140, v118, v129
	v_pk_mul_f32 v[124:125], v[50:51], v[130:131]
	v_add_f32_e32 v124, v140, v124
	v_add_f32_e32 v126, v124, v125
	s_waitcnt lgkmcnt(5)
	v_pk_mul_f32 v[124:125], v[52:53], v[132:133]
	s_nop 0
	v_add_f32_e32 v124, v126, v124
	v_add_f32_e32 v126, v124, v125
	v_pk_mul_f32 v[124:125], v[88:89], v[134:135]
	s_nop 0
	v_add_f32_e32 v124, v126, v124
	v_add_f32_e32 v126, v124, v125
	s_waitcnt lgkmcnt(4)
	v_pk_mul_f32 v[124:125], v[90:91], v[136:137]
	s_nop 0
	v_add_f32_e32 v124, v126, v124
	v_add_f32_e32 v126, v124, v125
	s_waitcnt vmcnt(0)
	v_pk_mul_f32 v[124:125], v[92:93], v[138:139]
	s_nop 0
	v_add_f32_e32 v124, v126, v124
	v_add_f32_e32 v124, v124, v125
	v_min_f32_e32 v125, 0, v124
	v_mul_f32_e64 v124, |v124|, s73
	v_exp_f32_e32 v124, v124
	s_nop 0
	v_add_f32_e32 v124, 1.0, v124
	v_cmp_gt_f32_e32 vcc, s94, v124
	s_nop 1
	v_cndmask_b32_e64 v126, 0, 32, vcc
	v_ldexp_f32 v124, v124, v126
	v_log_f32_e32 v124, v124
	s_nop 0
	v_mul_f32_e32 v126, 0x3f317217, v124
	v_fma_f32 v126, v124, s97, -v126
	v_fmac_f32_e32 v126, 0x3377d1cf, v124
	v_fmac_f32_e32 v126, 0x3f317217, v124
	v_cmp_lt_f32_e64 s[12:13], |v124|, s23
	s_nop 1
	v_cndmask_b32_e64 v124, v124, v126, s[12:13]
	v_cndmask_b32_e32 v126, 0, v211, vcc
	v_sub_f32_e32 v124, v124, v126
	v_sub_f32_e32 v124, v125, v124
	v_fmac_f32_e32 v122, 0x3d800000, v124
	v_mov_b32_e32 v204, v124
	s_waitcnt lgkmcnt(0)
; DEVI float logsigf_(float x) { return fminf(x, 0.f) - __logf(1.f + __expf(-fabsf(x))); }
; DEVI float gla_la(const float* gl, int t, const float* w2r, float gb) { float x = gb;
; #pragma unroll
;     for (int r = 0; r < 16; ++r) x += gl[t * 16 + r] * w2r[r];
;     return logsigf_(x) * (1.f / 16.f); }
; template <int KIND>
; DEVI void mix_state_phase(unsigned char* smem, const MixArgs a) {
;     ...
;             const int ch = tid & 127, sg = tid >> 7; float w2r[16];
; #pragma unroll
;             for (int r = 0; r < 16; ++r) w2r[r] = a.w2[r * 512 + h * 128 + ch];
;             const float gb = a.gateb[h * 128 + ch]; float ssum = 0.f;
;             for (int t = sg * 32; t < sg * 32 + 32; ++t) ssum += gla_la(gl, t, w2r, gb);
	v_fma_f32 v128, v119, v176, v8
	v_fmac_f32_e32 v128, v120, v177
	v_fmac_f32_e32 v128, v116, v178
	v_fmac_f32_e32 v128, v121, v179
	v_fmac_f32_e32 v128, v117, v180
	v_fmac_f32_e32 v128, v118, v181
	v_pk_mul_f32 v[124:125], v[50:51], v[182:183]
	s_nop 0
	v_add_f32_e32 v124, v128, v124
	v_add_f32_e32 v128, v124, v125
	v_pk_mul_f32 v[124:125], v[52:53], v[184:185]
	s_nop 0
	v_add_f32_e32 v124, v128, v124
	v_add_f32_e32 v128, v124, v125
	v_pk_mul_f32 v[124:125], v[88:89], v[186:187]
	s_nop 0
	v_add_f32_e32 v124, v128, v124
	v_add_f32_e32 v128, v124, v125
	v_pk_mul_f32 v[124:125], v[90:91], v[188:189]
	s_nop 0
	v_add_f32_e32 v123, v128, v124
	v_add_f32_e32 v123, v123, v125
	v_pk_mul_f32 v[124:125], v[92:93], v[190:191]
	s_nop 0
	v_add_f32_e32 v123, v123, v124
	v_add_f32_e32 v123, v123, v125
	v_min_f32_e32 v124, 0, v123
	v_mul_f32_e64 v123, |v123|, s73
	v_exp_f32_e32 v123, v123
	s_nop 0
	v_add_f32_e32 v123, 1.0, v123
	v_cmp_gt_f32_e32 vcc, s94, v123
	s_nop 1
	v_cndmask_b32_e64 v125, 0, 32, vcc
	v_ldexp_f32 v123, v123, v125
	v_log_f32_e32 v123, v123
	s_nop 0
	v_mul_f32_e32 v125, 0x3f317217, v123
	v_fma_f32 v125, v123, s97, -v125
	v_fmac_f32_e32 v125, 0x3377d1cf, v123
	v_fmac_f32_e32 v125, 0x3f317217, v123
	v_cmp_lt_f32_e64 s[12:13], |v123|, s23
	s_nop 1
	v_cndmask_b32_e64 v123, v123, v125, s[12:13]
	v_cndmask_b32_e32 v125, 0, v211, vcc
	v_sub_f32_e32 v123, v123, v125
	v_sub_f32_e32 v123, v124, v123
	v_fmac_f32_e32 v122, 0x3d800000, v123
	v_mov_b32_e32 v205, v123
	v_add_u32_e32 v123, s0, v99
	ds_read_b128 v[124:127], v123
	ds_read_b128 v[128:131], v123 offset:16
	ds_read_b128 v[132:135], v123 offset:32
	ds_read_b128 v[136:139], v123 offset:48
	ds_read_b128 v[176:179], v123 offset:64
	ds_read_b128 v[180:183], v123 offset:80
	ds_read_b128 v[184:187], v123 offset:96
	ds_read_b128 v[188:191], v123 offset:112
	s_addk_i32 s0, 0x80
	s_waitcnt vmcnt(1) lgkmcnt(7)
	v_fma_f32 v140, v119, v124, v8
	v_fmac_f32_e32 v140, v120, v125
	v_fmac_f32_e32 v140, v116, v126
	v_fmac_f32_e32 v140, v121, v127
	s_waitcnt lgkmcnt(6)
	v_fmac_f32_e32 v140, v117, v128
	v_fmac_f32_e32 v140, v118, v129
	v_pk_mul_f32 v[124:125], v[50:51], v[130:131]
	v_add_f32_e32 v124, v140, v124
	v_add_f32_e32 v126, v124, v125
	s_waitcnt lgkmcnt(5)
	v_pk_mul_f32 v[124:125], v[52:53], v[132:133]
	s_nop 0
	v_add_f32_e32 v124, v126, v124
	v_add_f32_e32 v126, v124, v125
	v_pk_mul_f32 v[124:125], v[88:89], v[134:135]
	s_nop 0
	v_add_f32_e32 v124, v126, v124
	v_add_f32_e32 v126, v124, v125
	s_waitcnt lgkmcnt(4)
	v_pk_mul_f32 v[124:125], v[90:91], v[136:137]
	s_nop 0
	v_add_f32_e32 v124, v126, v124
	v_add_f32_e32 v126, v124, v125
	s_waitcnt vmcnt(0)
	v_pk_mul_f32 v[124:125], v[92:93], v[138:139]
	s_nop 0
	v_add_f32_e32 v124, v126, v124
	v_add_f32_e32 v124, v124, v125
	v_min_f32_e32 v125, 0, v124
	v_mul_f32_e64 v124, |v124|, s73
	v_exp_f32_e32 v124, v124
	s_nop 0
	v_add_f32_e32 v124, 1.0, v124
	v_cmp_gt_f32_e32 vcc, s94, v124
	s_nop 1
	v_cndmask_b32_e64 v126, 0, 32, vcc
	v_ldexp_f32 v124, v124, v126
	v_log_f32_e32 v124, v124
	s_nop 0
	v_mul_f32_e32 v126, 0x3f317217, v124
	v_fma_f32 v126, v124, s97, -v126
	v_fmac_f32_e32 v126, 0x3377d1cf, v124
	v_fmac_f32_e32 v126, 0x3f317217, v124
	v_cmp_lt_f32_e64 s[12:13], |v124|, s23
	s_nop 1
	v_cndmask_b32_e64 v124, v124, v126, s[12:13]
	v_cndmask_b32_e32 v126, 0, v211, vcc
	v_sub_f32_e32 v124, v124, v126
	v_sub_f32_e32 v124, v125, v124
	v_fmac_f32_e32 v122, 0x3d800000, v124
	v_mov_b32_e32 v206, v124
	s_waitcnt lgkmcnt(0)
	v_fma_f32 v128, v119, v176, v8
	v_fmac_f32_e32 v128, v120, v177
	v_fmac_f32_e32 v128, v116, v178
	v_fmac_f32_e32 v128, v121, v179
	v_fmac_f32_e32 v128, v117, v180
	v_fmac_f32_e32 v128, v118, v181
	v_pk_mul_f32 v[124:125], v[50:51], v[182:183]
	s_nop 0
	v_add_f32_e32 v124, v128, v124
	v_add_f32_e32 v128, v124, v125
	v_pk_mul_f32 v[124:125], v[52:53], v[184:185]
	s_nop 0
	v_add_f32_e32 v124, v128, v124
	v_add_f32_e32 v128, v124, v125
	v_pk_mul_f32 v[124:125], v[88:89], v[186:187]
	s_nop 0
	v_add_f32_e32 v124, v128, v124
	v_add_f32_e32 v128, v124, v125
	v_pk_mul_f32 v[124:125], v[90:91], v[188:189]
	s_nop 0
	v_add_f32_e32 v123, v128, v124
	v_add_f32_e32 v123, v123, v125
	v_pk_mul_f32 v[124:125], v[92:93], v[190:191]
	s_nop 0
	v_add_f32_e32 v123, v123, v124
	v_add_f32_e32 v123, v123, v125
	v_min_f32_e32 v124, 0, v123
	v_mul_f32_e64 v123, |v123|, s73
	v_exp_f32_e32 v123, v123
	s_nop 0
	v_add_f32_e32 v123, 1.0, v123
	v_cmp_gt_f32_e32 vcc, s94, v123
	s_nop 1
	v_cndmask_b32_e64 v125, 0, 32, vcc
	v_ldexp_f32 v123, v123, v125
	v_log_f32_e32 v123, v123
	s_nop 0
	v_mul_f32_e32 v125, 0x3f317217, v123
	v_fma_f32 v125, v123, s97, -v125
	v_fmac_f32_e32 v125, 0x3377d1cf, v123
	v_fmac_f32_e32 v125, 0x3f317217, v123
	v_cmp_lt_f32_e64 s[12:13], |v123|, s23
	s_nop 1
	v_cndmask_b32_e64 v123, v123, v125, s[12:13]
	v_cndmask_b32_e32 v125, 0, v211, vcc
	v_sub_f32_e32 v123, v123, v125
	v_sub_f32_e32 v123, v124, v123
	v_fmac_f32_e32 v122, 0x3d800000, v123
	v_mov_b32_e32 v207, v123
	v_add_u32_e32 v123, s0, v99
	ds_read_b128 v[124:127], v123
	ds_read_b128 v[128:131], v123 offset:16
	ds_read_b128 v[132:135], v123 offset:32
	ds_read_b128 v[136:139], v123 offset:48
	ds_read_b128 v[176:179], v123 offset:64
	ds_read_b128 v[180:183], v123 offset:80
	ds_read_b128 v[184:187], v123 offset:96
	ds_read_b128 v[188:191], v123 offset:112
	s_addk_i32 s0, 0x80
	s_waitcnt vmcnt(1) lgkmcnt(7)
	v_fma_f32 v140, v119, v124, v8
	v_fmac_f32_e32 v140, v120, v125
	v_fmac_f32_e32 v140, v116, v126
	v_fmac_f32_e32 v140, v121, v127
	s_waitcnt lgkmcnt(6)
	v_fmac_f32_e32 v140, v117, v128
	v_fmac_f32_e32 v140, v118, v129
	v_pk_mul_f32 v[124:125], v[50:51], v[130:131]
	v_add_f32_e32 v124, v140, v124
	v_add_f32_e32 v126, v124, v125
	s_waitcnt lgkmcnt(5)
; DEVI float logsigf_(float x) { return fminf(x, 0.f) - __logf(1.f + __expf(-fabsf(x))); }
; DEVI float gla_la(const float* gl, int t, const float* w2r, float gb) { float x = gb;
; #pragma unroll
;     for (int r = 0; r < 16; ++r) x += gl[t * 16 + r] * w2r[r];
;     return logsigf_(x) * (1.f / 16.f); }
; template <int KIND>
; DEVI void mix_state_phase(unsigned char* smem, const MixArgs a) {
;     ...
;             const int ch = tid & 127, sg = tid >> 7; float w2r[16];
; #pragma unroll
;             for (int r = 0; r < 16; ++r) w2r[r] = a.w2[r * 512 + h * 128 + ch];
;             const float gb = a.gateb[h * 128 + ch]; float ssum = 0.f;
;             for (int t = sg * 32; t < sg * 32 + 32; ++t) ssum += gla_la(gl, t, w2r, gb);
	v_pk_mul_f32 v[124:125], v[52:53], v[132:133]
	s_nop 0
	v_add_f32_e32 v124, v126, v124
	v_add_f32_e32 v126, v124, v125
	v_pk_mul_f32 v[124:125], v[88:89], v[134:135]
	s_nop 0
	v_add_f32_e32 v124, v126, v124
	v_add_f32_e32 v126, v124, v125
	s_waitcnt lgkmcnt(4)
	v_pk_mul_f32 v[124:125], v[90:91], v[136:137]
	s_nop 0
	v_add_f32_e32 v124, v126, v124
	v_add_f32_e32 v126, v124, v125
	s_waitcnt vmcnt(0)
	v_pk_mul_f32 v[124:125], v[92:93], v[138:139]
	s_nop 0
	v_add_f32_e32 v124, v126, v124
	v_add_f32_e32 v124, v124, v125
	v_min_f32_e32 v125, 0, v124
	v_mul_f32_e64 v124, |v124|, s73
	v_exp_f32_e32 v124, v124
	s_nop 0
	v_add_f32_e32 v124, 1.0, v124
	v_cmp_gt_f32_e32 vcc, s94, v124
	s_nop 1
	v_cndmask_b32_e64 v126, 0, 32, vcc
	v_ldexp_f32 v124, v124, v126
	v_log_f32_e32 v124, v124
	s_nop 0
	v_mul_f32_e32 v126, 0x3f317217, v124
	v_fma_f32 v126, v124, s97, -v126
	v_fmac_f32_e32 v126, 0x3377d1cf, v124
	v_fmac_f32_e32 v126, 0x3f317217, v124
	v_cmp_lt_f32_e64 s[12:13], |v124|, s23
	s_nop 1
	v_cndmask_b32_e64 v124, v124, v126, s[12:13]
	v_cndmask_b32_e32 v126, 0, v211, vcc
	v_sub_f32_e32 v124, v124, v126
	v_sub_f32_e32 v124, v125, v124
	v_fmac_f32_e32 v122, 0x3d800000, v124
	v_mov_b32_e32 v213, v124
	s_waitcnt lgkmcnt(0)
	v_fma_f32 v128, v119, v176, v8
	v_fmac_f32_e32 v128, v120, v177
	v_fmac_f32_e32 v128, v116, v178
	v_fmac_f32_e32 v128, v121, v179
	v_fmac_f32_e32 v128, v117, v180
	v_fmac_f32_e32 v128, v118, v181
	v_pk_mul_f32 v[124:125], v[50:51], v[182:183]
	s_nop 0
	v_add_f32_e32 v124, v128, v124
	v_add_f32_e32 v128, v124, v125
	v_pk_mul_f32 v[124:125], v[52:53], v[184:185]
	s_nop 0
	v_add_f32_e32 v124, v128, v124
	v_add_f32_e32 v128, v124, v125
	v_pk_mul_f32 v[124:125], v[88:89], v[186:187]
	s_nop 0
	v_add_f32_e32 v124, v128, v124
	v_add_f32_e32 v128, v124, v125
	v_pk_mul_f32 v[124:125], v[90:91], v[188:189]
	s_nop 0
	v_add_f32_e32 v123, v128, v124
	v_add_f32_e32 v123, v123, v125
	v_pk_mul_f32 v[124:125], v[92:93], v[190:191]
	s_nop 0
	v_add_f32_e32 v123, v123, v124
	v_add_f32_e32 v123, v123, v125
	v_min_f32_e32 v124, 0, v123
	v_mul_f32_e64 v123, |v123|, s73
	v_exp_f32_e32 v123, v123
	s_nop 0
	v_add_f32_e32 v123, 1.0, v123
	v_cmp_gt_f32_e32 vcc, s94, v123
	s_nop 1
	v_cndmask_b32_e64 v125, 0, 32, vcc
	v_ldexp_f32 v123, v123, v125
	v_log_f32_e32 v123, v123
	s_nop 0
	v_mul_f32_e32 v125, 0x3f317217, v123
	v_fma_f32 v125, v123, s97, -v125
	v_fmac_f32_e32 v125, 0x3377d1cf, v123
	v_fmac_f32_e32 v125, 0x3f317217, v123
	v_cmp_lt_f32_e64 s[12:13], |v123|, s23
	s_nop 1
	v_cndmask_b32_e64 v123, v123, v125, s[12:13]
	v_cndmask_b32_e32 v125, 0, v211, vcc
	v_sub_f32_e32 v123, v123, v125
	v_sub_f32_e32 v123, v124, v123
	v_fmac_f32_e32 v122, 0x3d800000, v123
	v_mov_b32_e32 v214, v123
	v_add_u32_e32 v123, s0, v99
	ds_read_b128 v[124:127], v123
	ds_read_b128 v[128:131], v123 offset:16
	ds_read_b128 v[132:135], v123 offset:32
	ds_read_b128 v[136:139], v123 offset:48
	ds_read_b128 v[176:179], v123 offset:64
	ds_read_b128 v[180:183], v123 offset:80
	ds_read_b128 v[184:187], v123 offset:96
	ds_read_b128 v[188:191], v123 offset:112
	s_addk_i32 s0, 0x80
	s_waitcnt vmcnt(1) lgkmcnt(7)
	v_fma_f32 v140, v119, v124, v8
	v_fmac_f32_e32 v140, v120, v125
	v_fmac_f32_e32 v140, v116, v126
	v_fmac_f32_e32 v140, v121, v127
	s_waitcnt lgkmcnt(6)
	v_fmac_f32_e32 v140, v117, v128
	v_fmac_f32_e32 v140, v118, v129
	v_pk_mul_f32 v[124:125], v[50:51], v[130:131]
	v_add_f32_e32 v124, v140, v124
	v_add_f32_e32 v126, v124, v125
	s_waitcnt lgkmcnt(5)
	v_pk_mul_f32 v[124:125], v[52:53], v[132:133]
	s_nop 0
	v_add_f32_e32 v124, v126, v124
	v_add_f32_e32 v126, v124, v125
	v_pk_mul_f32 v[124:125], v[88:89], v[134:135]
	s_nop 0
	v_add_f32_e32 v124, v126, v124
	v_add_f32_e32 v126, v124, v125
	s_waitcnt lgkmcnt(4)
	v_pk_mul_f32 v[124:125], v[90:91], v[136:137]
	s_nop 0
	v_add_f32_e32 v124, v126, v124
	v_add_f32_e32 v126, v124, v125
	s_waitcnt vmcnt(0)
	v_pk_mul_f32 v[124:125], v[92:93], v[138:139]
	s_nop 0
	v_add_f32_e32 v124, v126, v124
	v_add_f32_e32 v124, v124, v125
	v_min_f32_e32 v125, 0, v124
	v_mul_f32_e64 v124, |v124|, s73
	v_exp_f32_e32 v124, v124
	s_nop 0
	v_add_f32_e32 v124, 1.0, v124
	v_cmp_gt_f32_e32 vcc, s94, v124
	s_nop 1
	v_cndmask_b32_e64 v126, 0, 32, vcc
	v_ldexp_f32 v124, v124, v126
	v_log_f32_e32 v124, v124
	s_nop 0
	v_mul_f32_e32 v126, 0x3f317217, v124
	v_fma_f32 v126, v124, s97, -v126
	v_fmac_f32_e32 v126, 0x3377d1cf, v124
	v_fmac_f32_e32 v126, 0x3f317217, v124
	v_cmp_lt_f32_e64 s[12:13], |v124|, s23
	s_nop 1
	v_cndmask_b32_e64 v124, v124, v126, s[12:13]
	v_cndmask_b32_e32 v126, 0, v211, vcc
	v_sub_f32_e32 v124, v124, v126
	v_sub_f32_e32 v124, v125, v124
	v_fmac_f32_e32 v122, 0x3d800000, v124
	v_mov_b32_e32 v215, v124
	s_waitcnt lgkmcnt(0)
	v_fma_f32 v128, v119, v176, v8
	v_fmac_f32_e32 v128, v120, v177
	v_fmac_f32_e32 v128, v116, v178
	v_fmac_f32_e32 v128, v121, v179
	v_fmac_f32_e32 v128, v117, v180
	v_fmac_f32_e32 v128, v118, v181
	v_pk_mul_f32 v[124:125], v[50:51], v[182:183]
	s_nop 0
	v_add_f32_e32 v124, v128, v124
	v_add_f32_e32 v128, v124, v125
	v_pk_mul_f32 v[124:125], v[52:53], v[184:185]
	s_nop 0
	v_add_f32_e32 v124, v128, v124
	v_add_f32_e32 v128, v124, v125
	v_pk_mul_f32 v[124:125], v[88:89], v[186:187]
	s_nop 0
	v_add_f32_e32 v124, v128, v124
	v_add_f32_e32 v128, v124, v125
	v_pk_mul_f32 v[124:125], v[90:91], v[188:189]
	s_nop 0
	v_add_f32_e32 v123, v128, v124
	v_add_f32_e32 v123, v123, v125
	v_pk_mul_f32 v[124:125], v[92:93], v[190:191]
	s_nop 0
	v_add_f32_e32 v123, v123, v124
	v_add_f32_e32 v123, v123, v125
	v_min_f32_e32 v124, 0, v123
	v_mul_f32_e64 v123, |v123|, s73
	v_exp_f32_e32 v123, v123
	s_nop 0
	v_add_f32_e32 v123, 1.0, v123
	v_cmp_gt_f32_e32 vcc, s94, v123
	s_nop 1
	v_cndmask_b32_e64 v125, 0, 32, vcc
	v_ldexp_f32 v123, v123, v125
	v_log_f32_e32 v123, v123
	s_nop 0
	v_mul_f32_e32 v125, 0x3f317217, v123
	v_fma_f32 v125, v123, s97, -v125
	v_fmac_f32_e32 v125, 0x3377d1cf, v123
	v_fmac_f32_e32 v125, 0x3f317217, v123
	v_cmp_lt_f32_e64 s[12:13], |v123|, s23
	s_nop 1
	v_cndmask_b32_e64 v123, v123, v125, s[12:13]
	v_cndmask_b32_e32 v125, 0, v211, vcc
	v_sub_f32_e32 v123, v123, v125
	v_sub_f32_e32 v123, v124, v123
	v_fmac_f32_e32 v122, 0x3d800000, v123
	v_mov_b32_e32 v216, v123
	v_add_u32_e32 v123, s0, v99
	ds_read_b128 v[124:127], v123
	ds_read_b128 v[128:131], v123 offset:16
	ds_read_b128 v[132:135], v123 offset:32
	ds_read_b128 v[136:139], v123 offset:48
	ds_read_b128 v[176:179], v123 offset:64
	ds_read_b128 v[180:183], v123 offset:80
	ds_read_b128 v[184:187], v123 offset:96
	ds_read_b128 v[188:191], v123 offset:112
	s_addk_i32 s0, 0x80
	s_waitcnt vmcnt(1) lgkmcnt(7)
; DEVI float logsigf_(float x) { return fminf(x, 0.f) - __logf(1.f + __expf(-fabsf(x))); }
; DEVI float gla_la(const float* gl, int t, const float* w2r, float gb) { float x = gb;
; #pragma unroll
;     for (int r = 0; r < 16; ++r) x += gl[t * 16 + r] * w2r[r];
;     return logsigf_(x) * (1.f / 16.f); }
; template <int KIND>
; DEVI void mix_state_phase(unsigned char* smem, const MixArgs a) {
;     ...
;             const int ch = tid & 127, sg = tid >> 7; float w2r[16];
; #pragma unroll
;             for (int r = 0; r < 16; ++r) w2r[r] = a.w2[r * 512 + h * 128 + ch];
;             const float gb = a.gateb[h * 128 + ch]; float ssum = 0.f;
;             for (int t = sg * 32; t < sg * 32 + 32; ++t) ssum += gla_la(gl, t, w2r, gb);
	v_fma_f32 v140, v119, v124, v8
	v_fmac_f32_e32 v140, v120, v125
	v_fmac_f32_e32 v140, v116, v126
	v_fmac_f32_e32 v140, v121, v127
	s_waitcnt lgkmcnt(6)
	v_fmac_f32_e32 v140, v117, v128
	v_fmac_f32_e32 v140, v118, v129
	v_pk_mul_f32 v[124:125], v[50:51], v[130:131]
	v_add_f32_e32 v124, v140, v124
	v_add_f32_e32 v126, v124, v125
	s_waitcnt lgkmcnt(5)
	v_pk_mul_f32 v[124:125], v[52:53], v[132:133]
	s_nop 0
	v_add_f32_e32 v124, v126, v124
	v_add_f32_e32 v126, v124, v125
	v_pk_mul_f32 v[124:125], v[88:89], v[134:135]
	s_nop 0
	v_add_f32_e32 v124, v126, v124
	v_add_f32_e32 v126, v124, v125
	s_waitcnt lgkmcnt(4)
	v_pk_mul_f32 v[124:125], v[90:91], v[136:137]
	s_nop 0
	v_add_f32_e32 v124, v126, v124
	v_add_f32_e32 v126, v124, v125
	s_waitcnt vmcnt(0)
	v_pk_mul_f32 v[124:125], v[92:93], v[138:139]
	s_nop 0
	v_add_f32_e32 v124, v126, v124
	v_add_f32_e32 v124, v124, v125
	v_min_f32_e32 v125, 0, v124
	v_mul_f32_e64 v124, |v124|, s73
	v_exp_f32_e32 v124, v124
	s_nop 0
	v_add_f32_e32 v124, 1.0, v124
	v_cmp_gt_f32_e32 vcc, s94, v124
	s_nop 1
	v_cndmask_b32_e64 v126, 0, 32, vcc
	v_ldexp_f32 v124, v124, v126
	v_log_f32_e32 v124, v124
	s_nop 0
	v_mul_f32_e32 v126, 0x3f317217, v124
	v_fma_f32 v126, v124, s97, -v126
	v_fmac_f32_e32 v126, 0x3377d1cf, v124
	v_fmac_f32_e32 v126, 0x3f317217, v124
	v_cmp_lt_f32_e64 s[12:13], |v124|, s23
	s_nop 1
	v_cndmask_b32_e64 v124, v124, v126, s[12:13]
	v_cndmask_b32_e32 v126, 0, v211, vcc
	v_sub_f32_e32 v124, v124, v126
	v_sub_f32_e32 v124, v125, v124
	v_fmac_f32_e32 v122, 0x3d800000, v124
	v_mov_b32_e32 v217, v124
	s_waitcnt lgkmcnt(0)
	v_fma_f32 v128, v119, v176, v8
	v_fmac_f32_e32 v128, v120, v177
	v_fmac_f32_e32 v128, v116, v178
	v_fmac_f32_e32 v128, v121, v179
	v_fmac_f32_e32 v128, v117, v180
	v_fmac_f32_e32 v128, v118, v181
	v_pk_mul_f32 v[124:125], v[50:51], v[182:183]
	s_nop 0
	v_add_f32_e32 v124, v128, v124
	v_add_f32_e32 v128, v124, v125
	v_pk_mul_f32 v[124:125], v[52:53], v[184:185]
	s_nop 0
	v_add_f32_e32 v124, v128, v124
	v_add_f32_e32 v128, v124, v125
	v_pk_mul_f32 v[124:125], v[88:89], v[186:187]
	s_nop 0
	v_add_f32_e32 v124, v128, v124
	v_add_f32_e32 v128, v124, v125
	v_pk_mul_f32 v[124:125], v[90:91], v[188:189]
	s_nop 0
	v_add_f32_e32 v123, v128, v124
	v_add_f32_e32 v123, v123, v125
	v_pk_mul_f32 v[124:125], v[92:93], v[190:191]
	s_nop 0
	v_add_f32_e32 v123, v123, v124
	v_add_f32_e32 v123, v123, v125
	v_min_f32_e32 v124, 0, v123
	v_mul_f32_e64 v123, |v123|, s73
	v_exp_f32_e32 v123, v123
	s_nop 0
	v_add_f32_e32 v123, 1.0, v123
	v_cmp_gt_f32_e32 vcc, s94, v123
	s_nop 1
	v_cndmask_b32_e64 v125, 0, 32, vcc
	v_ldexp_f32 v123, v123, v125
	v_log_f32_e32 v123, v123
	s_nop 0
	v_mul_f32_e32 v125, 0x3f317217, v123
	v_fma_f32 v125, v123, s97, -v125
	v_fmac_f32_e32 v125, 0x3377d1cf, v123
	v_fmac_f32_e32 v125, 0x3f317217, v123
	v_cmp_lt_f32_e64 s[12:13], |v123|, s23
	s_nop 1
	v_cndmask_b32_e64 v123, v123, v125, s[12:13]
	v_cndmask_b32_e32 v125, 0, v211, vcc
	v_sub_f32_e32 v123, v123, v125
	v_sub_f32_e32 v123, v124, v123
	v_fmac_f32_e32 v122, 0x3d800000, v123
	v_mov_b32_e32 v218, v123
	v_add_u32_e32 v123, s0, v99
	ds_read_b128 v[124:127], v123
	ds_read_b128 v[128:131], v123 offset:16
	ds_read_b128 v[132:135], v123 offset:32
	ds_read_b128 v[136:139], v123 offset:48
	ds_read_b128 v[176:179], v123 offset:64
	ds_read_b128 v[180:183], v123 offset:80
	ds_read_b128 v[184:187], v123 offset:96
	ds_read_b128 v[188:191], v123 offset:112
	s_addk_i32 s0, 0x80
	s_waitcnt vmcnt(1) lgkmcnt(7)
	v_fma_f32 v140, v119, v124, v8
	v_fmac_f32_e32 v140, v120, v125
	v_fmac_f32_e32 v140, v116, v126
	v_fmac_f32_e32 v140, v121, v127
	s_waitcnt lgkmcnt(6)
	v_fmac_f32_e32 v140, v117, v128
	v_fmac_f32_e32 v140, v118, v129
	v_pk_mul_f32 v[124:125], v[50:51], v[130:131]
	v_add_f32_e32 v124, v140, v124
	v_add_f32_e32 v126, v124, v125
	s_waitcnt lgkmcnt(5)
	v_pk_mul_f32 v[124:125], v[52:53], v[132:133]
	s_nop 0
	v_add_f32_e32 v124, v126, v124
	v_add_f32_e32 v126, v124, v125
	v_pk_mul_f32 v[124:125], v[88:89], v[134:135]
	s_nop 0
	v_add_f32_e32 v124, v126, v124
	v_add_f32_e32 v126, v124, v125
	s_waitcnt lgkmcnt(4)
	v_pk_mul_f32 v[124:125], v[90:91], v[136:137]
	s_nop 0
	v_add_f32_e32 v124, v126, v124
	v_add_f32_e32 v126, v124, v125
	s_waitcnt vmcnt(0)
	v_pk_mul_f32 v[124:125], v[92:93], v[138:139]
	s_nop 0
	v_add_f32_e32 v124, v126, v124
	v_add_f32_e32 v124, v124, v125
	v_min_f32_e32 v125, 0, v124
	v_mul_f32_e64 v124, |v124|, s73
	v_exp_f32_e32 v124, v124
	s_nop 0
	v_add_f32_e32 v124, 1.0, v124
	v_cmp_gt_f32_e32 vcc, s94, v124
	s_nop 1
	v_cndmask_b32_e64 v126, 0, 32, vcc
	v_ldexp_f32 v124, v124, v126
	v_log_f32_e32 v124, v124
	s_nop 0
	v_mul_f32_e32 v126, 0x3f317217, v124
	v_fma_f32 v126, v124, s97, -v126
	v_fmac_f32_e32 v126, 0x3377d1cf, v124
	v_fmac_f32_e32 v126, 0x3f317217, v124
	v_cmp_lt_f32_e64 s[12:13], |v124|, s23
	s_nop 1
	v_cndmask_b32_e64 v124, v124, v126, s[12:13]
	v_cndmask_b32_e32 v126, 0, v211, vcc
	v_sub_f32_e32 v124, v124, v126
	v_sub_f32_e32 v124, v125, v124
	v_fmac_f32_e32 v122, 0x3d800000, v124
	v_mov_b32_e32 v219, v124
	s_waitcnt lgkmcnt(0)
; DEVI float logsigf_(float x) { return fminf(x, 0.f) - __logf(1.f + __expf(-fabsf(x))); }
; DEVI float gla_la(const float* gl, int t, const float* w2r, float gb) { float x = gb;
; #pragma unroll
;     for (int r = 0; r < 16; ++r) x += gl[t * 16 + r] * w2r[r];
;     return logsigf_(x) * (1.f / 16.f); }
; template <int KIND>
; DEVI void mix_state_phase(unsigned char* smem, const MixArgs a) {
;     ...
;             const int ch = tid & 127, sg = tid >> 7; float w2r[16];
; #pragma unroll
;             for (int r = 0; r < 16; ++r) w2r[r] = a.w2[r * 512 + h * 128 + ch];
;             const float gb = a.gateb[h * 128 + ch]; float ssum = 0.f;
;             for (int t = sg * 32; t < sg * 32 + 32; ++t) ssum += gla_la(gl, t, w2r, gb);
	v_fma_f32 v128, v119, v176, v8
	v_fmac_f32_e32 v128, v120, v177
	v_fmac_f32_e32 v128, v116, v178
	v_fmac_f32_e32 v128, v121, v179
	v_fmac_f32_e32 v128, v117, v180
	v_fmac_f32_e32 v128, v118, v181
	v_pk_mul_f32 v[124:125], v[50:51], v[182:183]
	s_nop 0
	v_add_f32_e32 v124, v128, v124
	v_add_f32_e32 v128, v124, v125
	v_pk_mul_f32 v[124:125], v[52:53], v[184:185]
	s_nop 0
	v_add_f32_e32 v124, v128, v124
	v_add_f32_e32 v128, v124, v125
	v_pk_mul_f32 v[124:125], v[88:89], v[186:187]
	s_nop 0
	v_add_f32_e32 v124, v128, v124
	v_add_f32_e32 v128, v124, v125
	v_pk_mul_f32 v[124:125], v[90:91], v[188:189]
	s_nop 0
	v_add_f32_e32 v123, v128, v124
	v_add_f32_e32 v123, v123, v125
	v_pk_mul_f32 v[124:125], v[92:93], v[190:191]
	s_nop 0
	v_add_f32_e32 v123, v123, v124
	v_add_f32_e32 v123, v123, v125
	v_min_f32_e32 v124, 0, v123
	v_mul_f32_e64 v123, |v123|, s73
	v_exp_f32_e32 v123, v123
	s_nop 0
	v_add_f32_e32 v123, 1.0, v123
	v_cmp_gt_f32_e32 vcc, s94, v123
	s_nop 1
	v_cndmask_b32_e64 v125, 0, 32, vcc
	v_ldexp_f32 v123, v123, v125
	v_log_f32_e32 v123, v123
	s_nop 0
	v_mul_f32_e32 v125, 0x3f317217, v123
	v_fma_f32 v125, v123, s97, -v125
	v_fmac_f32_e32 v125, 0x3377d1cf, v123
	v_fmac_f32_e32 v125, 0x3f317217, v123
	v_cmp_lt_f32_e64 s[12:13], |v123|, s23
	s_nop 1
	v_cndmask_b32_e64 v123, v123, v125, s[12:13]
	v_cndmask_b32_e32 v125, 0, v211, vcc
	v_sub_f32_e32 v123, v123, v125
	v_sub_f32_e32 v123, v124, v123
	v_fmac_f32_e32 v122, 0x3d800000, v123
	v_mov_b32_e32 v220, v123
	v_add_u32_e32 v123, s0, v99
	ds_read_b128 v[124:127], v123
	ds_read_b128 v[128:131], v123 offset:16
	ds_read_b128 v[132:135], v123 offset:32
	ds_read_b128 v[136:139], v123 offset:48
	ds_read_b128 v[176:179], v123 offset:64
	ds_read_b128 v[180:183], v123 offset:80
	ds_read_b128 v[184:187], v123 offset:96
	ds_read_b128 v[188:191], v123 offset:112
	s_addk_i32 s0, 0x80
	s_waitcnt vmcnt(1) lgkmcnt(7)
	v_fma_f32 v140, v119, v124, v8
	v_fmac_f32_e32 v140, v120, v125
	v_fmac_f32_e32 v140, v116, v126
	v_fmac_f32_e32 v140, v121, v127
	s_waitcnt lgkmcnt(6)
	v_fmac_f32_e32 v140, v117, v128
	v_fmac_f32_e32 v140, v118, v129
	v_pk_mul_f32 v[124:125], v[50:51], v[130:131]
	v_add_f32_e32 v124, v140, v124
	v_add_f32_e32 v126, v124, v125
	s_waitcnt lgkmcnt(5)
	v_pk_mul_f32 v[124:125], v[52:53], v[132:133]
	s_nop 0
	v_add_f32_e32 v124, v126, v124
	v_add_f32_e32 v126, v124, v125
	v_pk_mul_f32 v[124:125], v[88:89], v[134:135]
	s_nop 0
	v_add_f32_e32 v124, v126, v124
	v_add_f32_e32 v126, v124, v125
	s_waitcnt lgkmcnt(4)
	v_pk_mul_f32 v[124:125], v[90:91], v[136:137]
	s_nop 0
	v_add_f32_e32 v124, v126, v124
	v_add_f32_e32 v126, v124, v125
	s_waitcnt vmcnt(0)
	v_pk_mul_f32 v[124:125], v[92:93], v[138:139]
	s_nop 0
	v_add_f32_e32 v124, v126, v124
	v_add_f32_e32 v124, v124, v125
	v_min_f32_e32 v125, 0, v124
	v_mul_f32_e64 v124, |v124|, s73
	v_exp_f32_e32 v124, v124
	s_nop 0
	v_add_f32_e32 v124, 1.0, v124
	v_cmp_gt_f32_e32 vcc, s94, v124
	s_nop 1
	v_cndmask_b32_e64 v126, 0, 32, vcc
	v_ldexp_f32 v124, v124, v126
	v_log_f32_e32 v124, v124
	s_nop 0
	v_mul_f32_e32 v126, 0x3f317217, v124
	v_fma_f32 v126, v124, s97, -v126
	v_fmac_f32_e32 v126, 0x3377d1cf, v124
	v_fmac_f32_e32 v126, 0x3f317217, v124
	v_cmp_lt_f32_e64 s[12:13], |v124|, s23
	s_nop 1
	v_cndmask_b32_e64 v124, v124, v126, s[12:13]
	v_cndmask_b32_e32 v126, 0, v211, vcc
	v_sub_f32_e32 v124, v124, v126
	v_sub_f32_e32 v124, v125, v124
	v_fmac_f32_e32 v122, 0x3d800000, v124
	v_mov_b32_e32 v221, v124
	s_waitcnt lgkmcnt(0)
	v_fma_f32 v128, v119, v176, v8
	v_fmac_f32_e32 v128, v120, v177
	v_fmac_f32_e32 v128, v116, v178
	v_fmac_f32_e32 v128, v121, v179
	v_fmac_f32_e32 v128, v117, v180
	v_fmac_f32_e32 v128, v118, v181
	v_pk_mul_f32 v[124:125], v[50:51], v[182:183]
	s_nop 0
	v_add_f32_e32 v124, v128, v124
	v_add_f32_e32 v128, v124, v125
	v_pk_mul_f32 v[124:125], v[52:53], v[184:185]
	s_nop 0
	v_add_f32_e32 v124, v128, v124
	v_add_f32_e32 v128, v124, v125
	v_pk_mul_f32 v[124:125], v[88:89], v[186:187]
	s_nop 0
	v_add_f32_e32 v124, v128, v124
	v_add_f32_e32 v128, v124, v125
	v_pk_mul_f32 v[124:125], v[90:91], v[188:189]
	s_nop 0
	v_add_f32_e32 v123, v128, v124
	v_add_f32_e32 v123, v123, v125
	v_pk_mul_f32 v[124:125], v[92:93], v[190:191]
	s_nop 0
	v_add_f32_e32 v123, v123, v124
	v_add_f32_e32 v123, v123, v125
	v_min_f32_e32 v124, 0, v123
	v_mul_f32_e64 v123, |v123|, s73
	v_exp_f32_e32 v123, v123
	s_nop 0
	v_add_f32_e32 v123, 1.0, v123
	v_cmp_gt_f32_e32 vcc, s94, v123
	s_nop 1
	v_cndmask_b32_e64 v125, 0, 32, vcc
	v_ldexp_f32 v123, v123, v125
	v_log_f32_e32 v123, v123
	s_nop 0
	v_mul_f32_e32 v125, 0x3f317217, v123
	v_fma_f32 v125, v123, s97, -v125
	v_fmac_f32_e32 v125, 0x3377d1cf, v123
	v_fmac_f32_e32 v125, 0x3f317217, v123
	v_cmp_lt_f32_e64 s[12:13], |v123|, s23
	s_nop 1
	v_cndmask_b32_e64 v123, v123, v125, s[12:13]
	v_cndmask_b32_e32 v125, 0, v211, vcc
	v_sub_f32_e32 v123, v123, v125
	v_sub_f32_e32 v123, v124, v123
	v_fmac_f32_e32 v122, 0x3d800000, v123
	v_mov_b32_e32 v222, v123
	v_add_u32_e32 v123, s0, v99
	ds_read_b128 v[124:127], v123
	ds_read_b128 v[128:131], v123 offset:16
	ds_read_b128 v[132:135], v123 offset:32
	ds_read_b128 v[136:139], v123 offset:48
	ds_read_b128 v[176:179], v123 offset:64
	ds_read_b128 v[180:183], v123 offset:80
	ds_read_b128 v[184:187], v123 offset:96
	ds_read_b128 v[188:191], v123 offset:112
	s_addk_i32 s0, 0x80
	s_waitcnt vmcnt(1) lgkmcnt(7)
	v_fma_f32 v140, v119, v124, v8
	v_fmac_f32_e32 v140, v120, v125
	v_fmac_f32_e32 v140, v116, v126
	v_fmac_f32_e32 v140, v121, v127
	s_waitcnt lgkmcnt(6)
	v_fmac_f32_e32 v140, v117, v128
	v_fmac_f32_e32 v140, v118, v129
	v_pk_mul_f32 v[124:125], v[50:51], v[130:131]
	v_add_f32_e32 v124, v140, v124
	v_add_f32_e32 v126, v124, v125
	s_waitcnt lgkmcnt(5)
; DEVI float logsigf_(float x) { return fminf(x, 0.f) - __logf(1.f + __expf(-fabsf(x))); }
; DEVI float gla_la(const float* gl, int t, const float* w2r, float gb) { float x = gb;
; #pragma unroll
;     for (int r = 0; r < 16; ++r) x += gl[t * 16 + r] * w2r[r];
;     return logsigf_(x) * (1.f / 16.f); }
; template <int KIND>
; DEVI void mix_state_phase(unsigned char* smem, const MixArgs a) {
;     ...
;             const int ch = tid & 127, sg = tid >> 7; float w2r[16];
; #pragma unroll
;             for (int r = 0; r < 16; ++r) w2r[r] = a.w2[r * 512 + h * 128 + ch];
;             const float gb = a.gateb[h * 128 + ch]; float ssum = 0.f;
;             for (int t = sg * 32; t < sg * 32 + 32; ++t) ssum += gla_la(gl, t, w2r, gb);
	v_pk_mul_f32 v[124:125], v[52:53], v[132:133]
	s_nop 0
	v_add_f32_e32 v124, v126, v124
	v_add_f32_e32 v126, v124, v125
	v_pk_mul_f32 v[124:125], v[88:89], v[134:135]
	s_nop 0
	v_add_f32_e32 v124, v126, v124
	v_add_f32_e32 v126, v124, v125
	s_waitcnt lgkmcnt(4)
	v_pk_mul_f32 v[124:125], v[90:91], v[136:137]
	s_nop 0
	v_add_f32_e32 v124, v126, v124
	v_add_f32_e32 v126, v124, v125
	s_waitcnt vmcnt(0)
	v_pk_mul_f32 v[124:125], v[92:93], v[138:139]
	s_nop 0
	v_add_f32_e32 v124, v126, v124
	v_add_f32_e32 v124, v124, v125
	v_min_f32_e32 v125, 0, v124
	v_mul_f32_e64 v124, |v124|, s73
	v_exp_f32_e32 v124, v124
	s_nop 0
	v_add_f32_e32 v124, 1.0, v124
	v_cmp_gt_f32_e32 vcc, s94, v124
	s_nop 1
	v_cndmask_b32_e64 v126, 0, 32, vcc
	v_ldexp_f32 v124, v124, v126
	v_log_f32_e32 v124, v124
	s_nop 0
	v_mul_f32_e32 v126, 0x3f317217, v124
	v_fma_f32 v126, v124, s97, -v126
	v_fmac_f32_e32 v126, 0x3377d1cf, v124
	v_fmac_f32_e32 v126, 0x3f317217, v124
	v_cmp_lt_f32_e64 s[12:13], |v124|, s23
	s_nop 1
	v_cndmask_b32_e64 v124, v124, v126, s[12:13]
	v_cndmask_b32_e32 v126, 0, v211, vcc
	v_sub_f32_e32 v124, v124, v126
	v_sub_f32_e32 v124, v125, v124
	v_fmac_f32_e32 v122, 0x3d800000, v124
	v_mov_b32_e32 v223, v124
	s_waitcnt lgkmcnt(0)
	v_fma_f32 v128, v119, v176, v8
	v_fmac_f32_e32 v128, v120, v177
	v_fmac_f32_e32 v128, v116, v178
	v_fmac_f32_e32 v128, v121, v179
	v_fmac_f32_e32 v128, v117, v180
	v_fmac_f32_e32 v128, v118, v181
	v_pk_mul_f32 v[124:125], v[50:51], v[182:183]
	s_nop 0
	v_add_f32_e32 v124, v128, v124
	v_add_f32_e32 v128, v124, v125
	v_pk_mul_f32 v[124:125], v[52:53], v[184:185]
	s_nop 0
	v_add_f32_e32 v124, v128, v124
	v_add_f32_e32 v128, v124, v125
	v_pk_mul_f32 v[124:125], v[88:89], v[186:187]
	s_nop 0
	v_add_f32_e32 v124, v128, v124
	v_add_f32_e32 v128, v124, v125
	v_pk_mul_f32 v[124:125], v[90:91], v[188:189]
	s_nop 0
	v_add_f32_e32 v123, v128, v124
	v_add_f32_e32 v123, v123, v125
	v_pk_mul_f32 v[124:125], v[92:93], v[190:191]
	s_nop 0
	v_add_f32_e32 v123, v123, v124
	v_add_f32_e32 v123, v123, v125
	v_min_f32_e32 v124, 0, v123
	v_mul_f32_e64 v123, |v123|, s73
	v_exp_f32_e32 v123, v123
	s_nop 0
	v_add_f32_e32 v123, 1.0, v123
	v_cmp_gt_f32_e32 vcc, s94, v123
	s_nop 1
	v_cndmask_b32_e64 v125, 0, 32, vcc
	v_ldexp_f32 v123, v123, v125
	v_log_f32_e32 v123, v123
	s_nop 0
	v_mul_f32_e32 v125, 0x3f317217, v123
	v_fma_f32 v125, v123, s97, -v125
	v_fmac_f32_e32 v125, 0x3377d1cf, v123
	v_fmac_f32_e32 v125, 0x3f317217, v123
	v_cmp_lt_f32_e64 s[12:13], |v123|, s23
	s_nop 1
	v_cndmask_b32_e64 v123, v123, v125, s[12:13]
	v_cndmask_b32_e32 v125, 0, v211, vcc
	v_sub_f32_e32 v123, v123, v125
	v_sub_f32_e32 v123, v124, v123
	v_fmac_f32_e32 v122, 0x3d800000, v123
	v_mov_b32_e32 v224, v123
	v_add_u32_e32 v123, s0, v99
	ds_read_b128 v[124:127], v123
	ds_read_b128 v[128:131], v123 offset:16
	ds_read_b128 v[132:135], v123 offset:32
	ds_read_b128 v[136:139], v123 offset:48
	ds_read_b128 v[176:179], v123 offset:64
	ds_read_b128 v[180:183], v123 offset:80
	ds_read_b128 v[184:187], v123 offset:96
	ds_read_b128 v[188:191], v123 offset:112
	s_addk_i32 s0, 0x80
	s_waitcnt vmcnt(1) lgkmcnt(7)
	v_fma_f32 v140, v119, v124, v8
	v_fmac_f32_e32 v140, v120, v125
	v_fmac_f32_e32 v140, v116, v126
	v_fmac_f32_e32 v140, v121, v127
	s_waitcnt lgkmcnt(6)
	v_fmac_f32_e32 v140, v117, v128
	v_fmac_f32_e32 v140, v118, v129
	v_pk_mul_f32 v[124:125], v[50:51], v[130:131]
	v_add_f32_e32 v124, v140, v124
	v_add_f32_e32 v126, v124, v125
	s_waitcnt lgkmcnt(5)
	v_pk_mul_f32 v[124:125], v[52:53], v[132:133]
	s_nop 0
	v_add_f32_e32 v124, v126, v124
	v_add_f32_e32 v126, v124, v125
	v_pk_mul_f32 v[124:125], v[88:89], v[134:135]
	s_nop 0
	v_add_f32_e32 v124, v126, v124
	v_add_f32_e32 v126, v124, v125
	s_waitcnt lgkmcnt(4)
	v_pk_mul_f32 v[124:125], v[90:91], v[136:137]
	s_nop 0
	v_add_f32_e32 v124, v126, v124
	v_add_f32_e32 v126, v124, v125
	s_waitcnt vmcnt(0)
	v_pk_mul_f32 v[124:125], v[92:93], v[138:139]
	s_nop 0
	v_add_f32_e32 v124, v126, v124
	v_add_f32_e32 v124, v124, v125
	v_min_f32_e32 v125, 0, v124
	v_mul_f32_e64 v124, |v124|, s73
	v_exp_f32_e32 v124, v124
	s_nop 0
	v_add_f32_e32 v124, 1.0, v124
	v_cmp_gt_f32_e32 vcc, s94, v124
	s_nop 1
	v_cndmask_b32_e64 v126, 0, 32, vcc
	v_ldexp_f32 v124, v124, v126
	v_log_f32_e32 v124, v124
	s_nop 0
	v_mul_f32_e32 v126, 0x3f317217, v124
	v_fma_f32 v126, v124, s97, -v126
	v_fmac_f32_e32 v126, 0x3377d1cf, v124
	v_fmac_f32_e32 v126, 0x3f317217, v124
	v_cmp_lt_f32_e64 s[12:13], |v124|, s23
	s_nop 1
	v_cndmask_b32_e64 v124, v124, v126, s[12:13]
	v_cndmask_b32_e32 v126, 0, v211, vcc
	v_sub_f32_e32 v124, v124, v126
	v_sub_f32_e32 v124, v125, v124
	v_fmac_f32_e32 v122, 0x3d800000, v124
	v_mov_b32_e32 v225, v124
	s_waitcnt lgkmcnt(0)
	v_fma_f32 v128, v119, v176, v8
	v_fmac_f32_e32 v128, v120, v177
	v_fmac_f32_e32 v128, v116, v178
	v_fmac_f32_e32 v128, v121, v179
	v_fmac_f32_e32 v128, v117, v180
	v_fmac_f32_e32 v128, v118, v181
	v_pk_mul_f32 v[124:125], v[50:51], v[182:183]
	s_nop 0
	v_add_f32_e32 v124, v128, v124
	v_add_f32_e32 v128, v124, v125
	v_pk_mul_f32 v[124:125], v[52:53], v[184:185]
	s_nop 0
	v_add_f32_e32 v124, v128, v124
	v_add_f32_e32 v128, v124, v125
	v_pk_mul_f32 v[124:125], v[88:89], v[186:187]
	s_nop 0
	v_add_f32_e32 v124, v128, v124
	v_add_f32_e32 v128, v124, v125
	v_pk_mul_f32 v[124:125], v[90:91], v[188:189]
	s_nop 0
	v_add_f32_e32 v123, v128, v124
	v_add_f32_e32 v123, v123, v125
	v_pk_mul_f32 v[124:125], v[92:93], v[190:191]
	s_nop 0
	v_add_f32_e32 v123, v123, v124
	v_add_f32_e32 v123, v123, v125
	v_min_f32_e32 v124, 0, v123
	v_mul_f32_e64 v123, |v123|, s73
	v_exp_f32_e32 v123, v123
	s_nop 0
	v_add_f32_e32 v123, 1.0, v123
	v_cmp_gt_f32_e32 vcc, s94, v123
	s_nop 1
	v_cndmask_b32_e64 v125, 0, 32, vcc
	v_ldexp_f32 v123, v123, v125
	v_log_f32_e32 v123, v123
	s_nop 0
	v_mul_f32_e32 v125, 0x3f317217, v123
	v_fma_f32 v125, v123, s97, -v125
	v_fmac_f32_e32 v125, 0x3377d1cf, v123
	v_fmac_f32_e32 v125, 0x3f317217, v123
	v_cmp_lt_f32_e64 s[12:13], |v123|, s23
	s_nop 1
	v_cndmask_b32_e64 v123, v123, v125, s[12:13]
	v_cndmask_b32_e32 v125, 0, v211, vcc
	v_sub_f32_e32 v123, v123, v125
	v_sub_f32_e32 v123, v124, v123
	v_fmac_f32_e32 v122, 0x3d800000, v123
	v_mov_b32_e32 v226, v123
	v_add_u32_e32 v123, s0, v99
	ds_read_b128 v[124:127], v123
	ds_read_b128 v[128:131], v123 offset:16
	ds_read_b128 v[132:135], v123 offset:32
	ds_read_b128 v[136:139], v123 offset:48
	ds_read_b128 v[176:179], v123 offset:64
	ds_read_b128 v[180:183], v123 offset:80
	ds_read_b128 v[184:187], v123 offset:96
	ds_read_b128 v[188:191], v123 offset:112
	s_addk_i32 s0, 0x80
	s_waitcnt vmcnt(1) lgkmcnt(7)
; DEVI float bf2f(u16 b) { return __uint_as_float(((unsigned)b) << 16); }
; DEVI u16 f2bf(float f) { return (u16)(cvt_pk(f, 0.f) & 0xffffu); }
; DEVI void lds_barrier() { asm volatile("s_waitcnt lgkmcnt(0)\n\ts_barrier" ::: "memory"); }
; template <int KIND>
; DEVI void mix_state_phase(unsigned char* smem, const MixArgs a) {
;     ...
;             for (int t = sg * 32; t < sg * 32 + 32; ++t) ssum += gla_la(gl, t, w2r, gb);
;             seg[sg * 128 + ch] = ssum; lds_barrier();
;             float Bc = 0.f, tot = 0.f;
; #pragma unroll
;             for (int s2 = 0; s2 < 4; ++s2) { const float v = seg[s2 * 128 + ch]; tot += v; if (s2 < sg) Bc += v; }
;             for (int t = sg * 32; t < sg * 32 + 32; ++t) { Bc += gla_la(gl, t, w2r, gb);
;                 const float kv = bf2f(KT[t * LP + ch]); KT[t * LP + ch] = f2bf(kv * __expf(tot - Bc)); }
	v_fma_f32 v140, v119, v124, v8
	v_fmac_f32_e32 v140, v120, v125
	v_fmac_f32_e32 v140, v116, v126
	v_fmac_f32_e32 v140, v121, v127
	s_waitcnt lgkmcnt(6)
	v_fmac_f32_e32 v140, v117, v128
	v_fmac_f32_e32 v140, v118, v129
	v_pk_mul_f32 v[124:125], v[50:51], v[130:131]
	v_add_f32_e32 v124, v140, v124
	v_add_f32_e32 v126, v124, v125
	s_waitcnt lgkmcnt(5)
	v_pk_mul_f32 v[124:125], v[52:53], v[132:133]
	s_nop 0
	v_add_f32_e32 v124, v126, v124
	v_add_f32_e32 v126, v124, v125
	v_pk_mul_f32 v[124:125], v[88:89], v[134:135]
	s_nop 0
	v_add_f32_e32 v124, v126, v124
	v_add_f32_e32 v126, v124, v125
	s_waitcnt lgkmcnt(4)
	v_pk_mul_f32 v[124:125], v[90:91], v[136:137]
	s_nop 0
	v_add_f32_e32 v124, v126, v124
	v_add_f32_e32 v126, v124, v125
	s_waitcnt vmcnt(0)
	v_pk_mul_f32 v[124:125], v[92:93], v[138:139]
	s_nop 0
	v_add_f32_e32 v124, v126, v124
	v_add_f32_e32 v124, v124, v125
	v_min_f32_e32 v125, 0, v124
	v_mul_f32_e64 v124, |v124|, s73
	v_exp_f32_e32 v124, v124
	s_nop 0
	v_add_f32_e32 v124, 1.0, v124
	v_cmp_gt_f32_e32 vcc, s94, v124
	s_nop 1
	v_cndmask_b32_e64 v126, 0, 32, vcc
	v_ldexp_f32 v124, v124, v126
	v_log_f32_e32 v124, v124
	s_nop 0
	v_mul_f32_e32 v126, 0x3f317217, v124
	v_fma_f32 v126, v124, s97, -v126
	v_fmac_f32_e32 v126, 0x3377d1cf, v124
	v_fmac_f32_e32 v126, 0x3f317217, v124
	v_cmp_lt_f32_e64 s[12:13], |v124|, s23
	s_nop 1
	v_cndmask_b32_e64 v124, v124, v126, s[12:13]
	v_cndmask_b32_e32 v126, 0, v211, vcc
	v_sub_f32_e32 v124, v124, v126
	v_sub_f32_e32 v124, v125, v124
	v_fmac_f32_e32 v122, 0x3d800000, v124
	v_mov_b32_e32 v227, v124
	s_waitcnt lgkmcnt(0)
	v_fma_f32 v128, v119, v176, v8
	v_fmac_f32_e32 v128, v120, v177
	v_fmac_f32_e32 v128, v116, v178
	v_fmac_f32_e32 v128, v121, v179
	v_fmac_f32_e32 v128, v117, v180
	v_fmac_f32_e32 v128, v118, v181
	v_pk_mul_f32 v[124:125], v[50:51], v[182:183]
	s_nop 0
	v_add_f32_e32 v124, v128, v124
	v_add_f32_e32 v128, v124, v125
	v_pk_mul_f32 v[124:125], v[52:53], v[184:185]
	s_nop 0
	v_add_f32_e32 v124, v128, v124
	v_add_f32_e32 v128, v124, v125
	v_pk_mul_f32 v[124:125], v[88:89], v[186:187]
	s_nop 0
	v_add_f32_e32 v124, v128, v124
	v_add_f32_e32 v128, v124, v125
	v_pk_mul_f32 v[124:125], v[90:91], v[188:189]
	s_nop 0
	v_add_f32_e32 v123, v128, v124
	v_add_f32_e32 v123, v123, v125
	v_pk_mul_f32 v[124:125], v[92:93], v[190:191]
	s_nop 0
	v_add_f32_e32 v123, v123, v124
	v_add_f32_e32 v123, v123, v125
	v_min_f32_e32 v124, 0, v123
	v_mul_f32_e64 v123, |v123|, s73
	v_exp_f32_e32 v123, v123
	s_nop 0
	v_add_f32_e32 v123, 1.0, v123
	v_cmp_gt_f32_e32 vcc, s94, v123
	s_nop 1
	v_cndmask_b32_e64 v125, 0, 32, vcc
	v_ldexp_f32 v123, v123, v125
	v_log_f32_e32 v123, v123
	s_nop 0
	v_mul_f32_e32 v125, 0x3f317217, v123
	v_fma_f32 v125, v123, s97, -v125
	v_fmac_f32_e32 v125, 0x3377d1cf, v123
	v_fmac_f32_e32 v125, 0x3f317217, v123
	v_cmp_lt_f32_e64 s[12:13], |v123|, s23
	s_nop 1
	v_cndmask_b32_e64 v123, v123, v125, s[12:13]
	v_cndmask_b32_e32 v125, 0, v211, vcc
	v_sub_f32_e32 v123, v123, v125
	v_sub_f32_e32 v123, v124, v123
	v_fmac_f32_e32 v122, 0x3d800000, v123
	v_mov_b32_e32 v228, v123
	ds_write_b32 v95, v122 offset:1536
	s_waitcnt lgkmcnt(0)
	s_barrier
	ds_read2st64_b32 v[122:123], v96 offset0:6 offset1:8
	s_mov_b32 s0, 0
	s_waitcnt lgkmcnt(0)
	v_add_f32_e32 v122, 0, v122
	v_cndmask_b32_e64 v124, 0, v122, s[4:5]
	v_add_f32_e32 v125, v122, v123
	v_add_f32_e32 v122, v123, v124
	v_cndmask_b32_e64 v124, v124, v122, s[6:7]
	ds_read2st64_b32 v[122:123], v96 offset0:10 offset1:12
	s_waitcnt lgkmcnt(0)
	v_add_f32_e32 v125, v125, v122
	v_add_f32_e32 v122, v122, v124
	v_cndmask_b32_e64 v124, v124, v122, s[8:9]
	v_add_f32_e32 v122, v125, v123
	v_add_f32_e32 v123, v123, v124
	v_cndmask_b32_e64 v123, v124, v123, s[10:11]
	v_mov_b32_e32 v124, v100
.LBB0_516:
	v_fmac_f32_e32 v123, 0x3d800000, v192
	v_add_u32_e32 v126, 0xfffffef0, v124
	ds_read_u16 v127, v126
	v_sub_f32_e32 v128, v122, v123
	v_mul_f32_e32 v128, 0x3fb8aa3b, v128
	v_exp_f32_e32 v128, v128
	s_waitcnt lgkmcnt(0)
	v_lshlrev_b32_e32 v127, 16, v127
	v_mul_f32_e32 v127, v128, v127
	v_cvt_pk_bf16_f32 v127, v127, s0
	ds_write_b16 v126, v127
	v_fmac_f32_e32 v123, 0x3d800000, v193
	ds_read_u16 v125, v124
	v_sub_f32_e32 v126, v122, v123
	v_mul_f32_e32 v126, 0x3fb8aa3b, v126
	v_exp_f32_e32 v126, v126
	s_waitcnt lgkmcnt(0)
	v_lshlrev_b32_e32 v125, 16, v125
	v_mul_f32_e32 v125, v126, v125
	v_cvt_pk_bf16_f32 v125, v125, s0
	s_addk_i32 s0, 0x80
	ds_write_b16 v124, v125
	v_add_u32_e32 v124, 0x220, v124
	v_fmac_f32_e32 v123, 0x3d800000, v194
	v_add_u32_e32 v126, 0xfffffef0, v124
	ds_read_u16 v127, v126
	v_sub_f32_e32 v128, v122, v123
	v_mul_f32_e32 v128, 0x3fb8aa3b, v128
	v_exp_f32_e32 v128, v128
	s_waitcnt lgkmcnt(0)
	v_lshlrev_b32_e32 v127, 16, v127
	v_mul_f32_e32 v127, v128, v127
	v_cvt_pk_bf16_f32 v127, v127, s0
	ds_write_b16 v126, v127
	v_fmac_f32_e32 v123, 0x3d800000, v195
	ds_read_u16 v125, v124
	v_sub_f32_e32 v126, v122, v123
	v_mul_f32_e32 v126, 0x3fb8aa3b, v126
	v_exp_f32_e32 v126, v126
	s_waitcnt lgkmcnt(0)
	v_lshlrev_b32_e32 v125, 16, v125
	v_mul_f32_e32 v125, v126, v125
	v_cvt_pk_bf16_f32 v125, v125, s0
	s_addk_i32 s0, 0x80
	ds_write_b16 v124, v125
	v_add_u32_e32 v124, 0x220, v124
	v_fmac_f32_e32 v123, 0x3d800000, v196
	v_add_u32_e32 v126, 0xfffffef0, v124
	ds_read_u16 v127, v126
	v_sub_f32_e32 v128, v122, v123
	v_mul_f32_e32 v128, 0x3fb8aa3b, v128
	v_exp_f32_e32 v128, v128
	s_waitcnt lgkmcnt(0)
	v_lshlrev_b32_e32 v127, 16, v127
	v_mul_f32_e32 v127, v128, v127
	v_cvt_pk_bf16_f32 v127, v127, s0
	ds_write_b16 v126, v127
	v_fmac_f32_e32 v123, 0x3d800000, v197
	ds_read_u16 v125, v124
	v_sub_f32_e32 v126, v122, v123
	v_mul_f32_e32 v126, 0x3fb8aa3b, v126
	v_exp_f32_e32 v126, v126
	s_waitcnt lgkmcnt(0)
; DEVI float bf2f(u16 b) { return __uint_as_float(((unsigned)b) << 16); }
; DEVI u16 f2bf(float f) { return (u16)(cvt_pk(f, 0.f) & 0xffffu); }
; template <int KIND>
; DEVI void mix_state_phase(unsigned char* smem, const MixArgs a) {
;     ...
;             for (int t = sg * 32; t < sg * 32 + 32; ++t) { Bc += gla_la(gl, t, w2r, gb);
;                 const float kv = bf2f(KT[t * LP + ch]); KT[t * LP + ch] = f2bf(kv * __expf(tot - Bc)); }
	v_lshlrev_b32_e32 v125, 16, v125
	v_mul_f32_e32 v125, v126, v125
	v_cvt_pk_bf16_f32 v125, v125, s0
	s_addk_i32 s0, 0x80
	ds_write_b16 v124, v125
	v_add_u32_e32 v124, 0x220, v124
	v_fmac_f32_e32 v123, 0x3d800000, v198
	v_add_u32_e32 v126, 0xfffffef0, v124
	ds_read_u16 v127, v126
	v_sub_f32_e32 v128, v122, v123
	v_mul_f32_e32 v128, 0x3fb8aa3b, v128
	v_exp_f32_e32 v128, v128
	s_waitcnt lgkmcnt(0)
	v_lshlrev_b32_e32 v127, 16, v127
	v_mul_f32_e32 v127, v128, v127
	v_cvt_pk_bf16_f32 v127, v127, s0
	ds_write_b16 v126, v127
	v_fmac_f32_e32 v123, 0x3d800000, v199
	ds_read_u16 v125, v124
	v_sub_f32_e32 v126, v122, v123
	v_mul_f32_e32 v126, 0x3fb8aa3b, v126
	v_exp_f32_e32 v126, v126
	s_waitcnt lgkmcnt(0)
	v_lshlrev_b32_e32 v125, 16, v125
	v_mul_f32_e32 v125, v126, v125
	v_cvt_pk_bf16_f32 v125, v125, s0
	s_addk_i32 s0, 0x80
	ds_write_b16 v124, v125
	v_add_u32_e32 v124, 0x220, v124
	v_fmac_f32_e32 v123, 0x3d800000, v200
	v_add_u32_e32 v126, 0xfffffef0, v124
	ds_read_u16 v127, v126
	v_sub_f32_e32 v128, v122, v123
	v_mul_f32_e32 v128, 0x3fb8aa3b, v128
	v_exp_f32_e32 v128, v128
	s_waitcnt lgkmcnt(0)
	v_lshlrev_b32_e32 v127, 16, v127
	v_mul_f32_e32 v127, v128, v127
	v_cvt_pk_bf16_f32 v127, v127, s0
	ds_write_b16 v126, v127
	v_fmac_f32_e32 v123, 0x3d800000, v201
	ds_read_u16 v125, v124
	v_sub_f32_e32 v126, v122, v123
	v_mul_f32_e32 v126, 0x3fb8aa3b, v126
	v_exp_f32_e32 v126, v126
	s_waitcnt lgkmcnt(0)
	v_lshlrev_b32_e32 v125, 16, v125
	v_mul_f32_e32 v125, v126, v125
	v_cvt_pk_bf16_f32 v125, v125, s0
	s_addk_i32 s0, 0x80
	ds_write_b16 v124, v125
	v_add_u32_e32 v124, 0x220, v124
	v_fmac_f32_e32 v123, 0x3d800000, v202
	v_add_u32_e32 v126, 0xfffffef0, v124
	ds_read_u16 v127, v126
	v_sub_f32_e32 v128, v122, v123
	v_mul_f32_e32 v128, 0x3fb8aa3b, v128
	v_exp_f32_e32 v128, v128
	s_waitcnt lgkmcnt(0)
	v_lshlrev_b32_e32 v127, 16, v127
	v_mul_f32_e32 v127, v128, v127
	v_cvt_pk_bf16_f32 v127, v127, s0
	ds_write_b16 v126, v127
	v_fmac_f32_e32 v123, 0x3d800000, v203
	ds_read_u16 v125, v124
	v_sub_f32_e32 v126, v122, v123
	v_mul_f32_e32 v126, 0x3fb8aa3b, v126
	v_exp_f32_e32 v126, v126
	s_waitcnt lgkmcnt(0)
	v_lshlrev_b32_e32 v125, 16, v125
	v_mul_f32_e32 v125, v126, v125
	v_cvt_pk_bf16_f32 v125, v125, s0
	s_addk_i32 s0, 0x80
	ds_write_b16 v124, v125
	v_add_u32_e32 v124, 0x220, v124
	v_fmac_f32_e32 v123, 0x3d800000, v204
	v_add_u32_e32 v126, 0xfffffef0, v124
	ds_read_u16 v127, v126
	v_sub_f32_e32 v128, v122, v123
	v_mul_f32_e32 v128, 0x3fb8aa3b, v128
	v_exp_f32_e32 v128, v128
	s_waitcnt lgkmcnt(0)
	v_lshlrev_b32_e32 v127, 16, v127
	v_mul_f32_e32 v127, v128, v127
	v_cvt_pk_bf16_f32 v127, v127, s0
	ds_write_b16 v126, v127
	v_fmac_f32_e32 v123, 0x3d800000, v205
	ds_read_u16 v125, v124
	v_sub_f32_e32 v126, v122, v123
	v_mul_f32_e32 v126, 0x3fb8aa3b, v126
	v_exp_f32_e32 v126, v126
	s_waitcnt lgkmcnt(0)
	v_lshlrev_b32_e32 v125, 16, v125
	v_mul_f32_e32 v125, v126, v125
	v_cvt_pk_bf16_f32 v125, v125, s0
	s_addk_i32 s0, 0x80
	ds_write_b16 v124, v125
	v_add_u32_e32 v124, 0x220, v124
	v_fmac_f32_e32 v123, 0x3d800000, v206
	v_add_u32_e32 v126, 0xfffffef0, v124
	ds_read_u16 v127, v126
	v_sub_f32_e32 v128, v122, v123
	v_mul_f32_e32 v128, 0x3fb8aa3b, v128
	v_exp_f32_e32 v128, v128
	s_waitcnt lgkmcnt(0)
	v_lshlrev_b32_e32 v127, 16, v127
	v_mul_f32_e32 v127, v128, v127
	v_cvt_pk_bf16_f32 v127, v127, s0
	ds_write_b16 v126, v127
	v_fmac_f32_e32 v123, 0x3d800000, v207
	ds_read_u16 v125, v124
	v_sub_f32_e32 v126, v122, v123
	v_mul_f32_e32 v126, 0x3fb8aa3b, v126
	v_exp_f32_e32 v126, v126
	s_waitcnt lgkmcnt(0)
	v_lshlrev_b32_e32 v125, 16, v125
	v_mul_f32_e32 v125, v126, v125
	v_cvt_pk_bf16_f32 v125, v125, s0
	s_addk_i32 s0, 0x80
	ds_write_b16 v124, v125
	v_add_u32_e32 v124, 0x220, v124
	v_fmac_f32_e32 v123, 0x3d800000, v213
	v_add_u32_e32 v126, 0xfffffef0, v124
	ds_read_u16 v127, v126
	v_sub_f32_e32 v128, v122, v123
	v_mul_f32_e32 v128, 0x3fb8aa3b, v128
	v_exp_f32_e32 v128, v128
	s_waitcnt lgkmcnt(0)
	v_lshlrev_b32_e32 v127, 16, v127
	v_mul_f32_e32 v127, v128, v127
	v_cvt_pk_bf16_f32 v127, v127, s0
	ds_write_b16 v126, v127
	v_fmac_f32_e32 v123, 0x3d800000, v214
	ds_read_u16 v125, v124
	v_sub_f32_e32 v126, v122, v123
	v_mul_f32_e32 v126, 0x3fb8aa3b, v126
	v_exp_f32_e32 v126, v126
	s_waitcnt lgkmcnt(0)
	v_lshlrev_b32_e32 v125, 16, v125
	v_mul_f32_e32 v125, v126, v125
	v_cvt_pk_bf16_f32 v125, v125, s0
	s_addk_i32 s0, 0x80
	ds_write_b16 v124, v125
	v_add_u32_e32 v124, 0x220, v124
	v_fmac_f32_e32 v123, 0x3d800000, v215
	v_add_u32_e32 v126, 0xfffffef0, v124
	ds_read_u16 v127, v126
	v_sub_f32_e32 v128, v122, v123
	v_mul_f32_e32 v128, 0x3fb8aa3b, v128
	v_exp_f32_e32 v128, v128
	s_waitcnt lgkmcnt(0)
	v_lshlrev_b32_e32 v127, 16, v127
	v_mul_f32_e32 v127, v128, v127
	v_cvt_pk_bf16_f32 v127, v127, s0
	ds_write_b16 v126, v127
	v_fmac_f32_e32 v123, 0x3d800000, v216
	ds_read_u16 v125, v124
	v_sub_f32_e32 v126, v122, v123
	v_mul_f32_e32 v126, 0x3fb8aa3b, v126
	v_exp_f32_e32 v126, v126
	s_waitcnt lgkmcnt(0)
; DEVI float bf2f(u16 b) { return __uint_as_float(((unsigned)b) << 16); }
; DEVI u16 f2bf(float f) { return (u16)(cvt_pk(f, 0.f) & 0xffffu); }
; template <int KIND>
; DEVI void mix_state_phase(unsigned char* smem, const MixArgs a) {
;     ...
;             for (int t = sg * 32; t < sg * 32 + 32; ++t) { Bc += gla_la(gl, t, w2r, gb);
;                 const float kv = bf2f(KT[t * LP + ch]); KT[t * LP + ch] = f2bf(kv * __expf(tot - Bc)); }
;             if (sg == 0) a.dec[(size_t)item * 128 + ch] = __expf(tot);
	v_lshlrev_b32_e32 v125, 16, v125
	v_mul_f32_e32 v125, v126, v125
	v_cvt_pk_bf16_f32 v125, v125, s0
	s_addk_i32 s0, 0x80
	ds_write_b16 v124, v125
	v_add_u32_e32 v124, 0x220, v124
	v_fmac_f32_e32 v123, 0x3d800000, v217
	v_add_u32_e32 v126, 0xfffffef0, v124
	ds_read_u16 v127, v126
	v_sub_f32_e32 v128, v122, v123
	v_mul_f32_e32 v128, 0x3fb8aa3b, v128
	v_exp_f32_e32 v128, v128
	s_waitcnt lgkmcnt(0)
	v_lshlrev_b32_e32 v127, 16, v127
	v_mul_f32_e32 v127, v128, v127
	v_cvt_pk_bf16_f32 v127, v127, s0
	ds_write_b16 v126, v127
	v_fmac_f32_e32 v123, 0x3d800000, v218
	ds_read_u16 v125, v124
	v_sub_f32_e32 v126, v122, v123
	v_mul_f32_e32 v126, 0x3fb8aa3b, v126
	v_exp_f32_e32 v126, v126
	s_waitcnt lgkmcnt(0)
	v_lshlrev_b32_e32 v125, 16, v125
	v_mul_f32_e32 v125, v126, v125
	v_cvt_pk_bf16_f32 v125, v125, s0
	s_addk_i32 s0, 0x80
	ds_write_b16 v124, v125
	v_add_u32_e32 v124, 0x220, v124
	v_fmac_f32_e32 v123, 0x3d800000, v219
	v_add_u32_e32 v126, 0xfffffef0, v124
	ds_read_u16 v127, v126
	v_sub_f32_e32 v128, v122, v123
	v_mul_f32_e32 v128, 0x3fb8aa3b, v128
	v_exp_f32_e32 v128, v128
	s_waitcnt lgkmcnt(0)
	v_lshlrev_b32_e32 v127, 16, v127
	v_mul_f32_e32 v127, v128, v127
	v_cvt_pk_bf16_f32 v127, v127, s0
	ds_write_b16 v126, v127
	v_fmac_f32_e32 v123, 0x3d800000, v220
	ds_read_u16 v125, v124
	v_sub_f32_e32 v126, v122, v123
	v_mul_f32_e32 v126, 0x3fb8aa3b, v126
	v_exp_f32_e32 v126, v126
	s_waitcnt lgkmcnt(0)
	v_lshlrev_b32_e32 v125, 16, v125
	v_mul_f32_e32 v125, v126, v125
	v_cvt_pk_bf16_f32 v125, v125, s0
	s_addk_i32 s0, 0x80
	ds_write_b16 v124, v125
	v_add_u32_e32 v124, 0x220, v124
	v_fmac_f32_e32 v123, 0x3d800000, v221
	v_add_u32_e32 v126, 0xfffffef0, v124
	ds_read_u16 v127, v126
	v_sub_f32_e32 v128, v122, v123
	v_mul_f32_e32 v128, 0x3fb8aa3b, v128
	v_exp_f32_e32 v128, v128
	s_waitcnt lgkmcnt(0)
	v_lshlrev_b32_e32 v127, 16, v127
	v_mul_f32_e32 v127, v128, v127
	v_cvt_pk_bf16_f32 v127, v127, s0
	ds_write_b16 v126, v127
	v_fmac_f32_e32 v123, 0x3d800000, v222
	ds_read_u16 v125, v124
	v_sub_f32_e32 v126, v122, v123
	v_mul_f32_e32 v126, 0x3fb8aa3b, v126
	v_exp_f32_e32 v126, v126
	s_waitcnt lgkmcnt(0)
	v_lshlrev_b32_e32 v125, 16, v125
	v_mul_f32_e32 v125, v126, v125
	v_cvt_pk_bf16_f32 v125, v125, s0
	s_addk_i32 s0, 0x80
	ds_write_b16 v124, v125
	v_add_u32_e32 v124, 0x220, v124
	v_fmac_f32_e32 v123, 0x3d800000, v223
	v_add_u32_e32 v126, 0xfffffef0, v124
	ds_read_u16 v127, v126
	v_sub_f32_e32 v128, v122, v123
	v_mul_f32_e32 v128, 0x3fb8aa3b, v128
	v_exp_f32_e32 v128, v128
	s_waitcnt lgkmcnt(0)
	v_lshlrev_b32_e32 v127, 16, v127
	v_mul_f32_e32 v127, v128, v127
	v_cvt_pk_bf16_f32 v127, v127, s0
	ds_write_b16 v126, v127
	v_fmac_f32_e32 v123, 0x3d800000, v224
	ds_read_u16 v125, v124
	v_sub_f32_e32 v126, v122, v123
	v_mul_f32_e32 v126, 0x3fb8aa3b, v126
	v_exp_f32_e32 v126, v126
	s_waitcnt lgkmcnt(0)
	v_lshlrev_b32_e32 v125, 16, v125
	v_mul_f32_e32 v125, v126, v125
	v_cvt_pk_bf16_f32 v125, v125, s0
	s_addk_i32 s0, 0x80
	ds_write_b16 v124, v125
	v_add_u32_e32 v124, 0x220, v124
	v_fmac_f32_e32 v123, 0x3d800000, v225
	v_add_u32_e32 v126, 0xfffffef0, v124
	ds_read_u16 v127, v126
	v_sub_f32_e32 v128, v122, v123
	v_mul_f32_e32 v128, 0x3fb8aa3b, v128
	v_exp_f32_e32 v128, v128
	s_waitcnt lgkmcnt(0)
	v_lshlrev_b32_e32 v127, 16, v127
	v_mul_f32_e32 v127, v128, v127
	v_cvt_pk_bf16_f32 v127, v127, s0
	ds_write_b16 v126, v127
	v_fmac_f32_e32 v123, 0x3d800000, v226
	ds_read_u16 v125, v124
	v_sub_f32_e32 v126, v122, v123
	v_mul_f32_e32 v126, 0x3fb8aa3b, v126
	v_exp_f32_e32 v126, v126
	s_waitcnt lgkmcnt(0)
	v_lshlrev_b32_e32 v125, 16, v125
	v_mul_f32_e32 v125, v126, v125
	v_cvt_pk_bf16_f32 v125, v125, s0
	s_addk_i32 s0, 0x80
	ds_write_b16 v124, v125
	v_add_u32_e32 v124, 0x220, v124
	v_fmac_f32_e32 v123, 0x3d800000, v227
	v_add_u32_e32 v126, 0xfffffef0, v124
	ds_read_u16 v127, v126
	v_sub_f32_e32 v128, v122, v123
	v_mul_f32_e32 v128, 0x3fb8aa3b, v128
	v_exp_f32_e32 v128, v128
	s_waitcnt lgkmcnt(0)
	v_lshlrev_b32_e32 v127, 16, v127
	v_mul_f32_e32 v127, v128, v127
	v_cvt_pk_bf16_f32 v127, v127, s0
	ds_write_b16 v126, v127
	v_fmac_f32_e32 v123, 0x3d800000, v228
	ds_read_u16 v125, v124
	v_sub_f32_e32 v126, v122, v123
	v_mul_f32_e32 v126, 0x3fb8aa3b, v126
	v_exp_f32_e32 v126, v126
	s_waitcnt lgkmcnt(0)
	v_lshlrev_b32_e32 v125, 16, v125
	v_mul_f32_e32 v125, v126, v125
	v_cvt_pk_bf16_f32 v125, v125, s0
	s_addk_i32 s0, 0x80
	ds_write_b16 v124, v125
	v_add_u32_e32 v124, 0x220, v124
	s_and_saveexec_b64 s[12:13], s[2:3]
	s_cbranch_execz .LBB0_510
	v_mul_f32_e32 v8, 0x3fb8aa3b, v122
	v_exp_f32_e32 v8, v8
	s_lshl_b64 s[0:1], s[14:15], 9
	v_lshl_add_u64 v[50:51], v[80:81], 0, s[0:1]
	global_store_dword v[50:51], v8, off
	s_branch .LBB0_510

; DEVI float logsigf_(float x) { return fminf(x, 0.f) - __logf(1.f + __expf(-fabsf(x))); }
; DEVI float gla_la(const float* gl, int t, const float* w2r, float gb) { float x = gb;
; #pragma unroll
;     for (int r = 0; r < 16; ++r) x += gl[t * 16 + r] * w2r[r];
;     return logsigf_(x) * (1.f / 16.f); }
; template <int KIND>
; DEVI void mix_out_phase(unsigned char* smem, const MixArgs a) {
;     ...
;             const int ch = tid & 127, sg = tid >> 7; float w2r[16];
; #pragma unroll
;             for (int r = 0; r < 16; ++r) w2r[r] = a.w2[r * 512 + h * 128 + ch];
;             const float gb = a.gateb[h * 128 + ch]; float ssum = 0.f;
;             for (int t = sg * 32; t < sg * 32 + 32; ++t) ssum += gla_la(gl, t, w2r, gb);
.LBB0_691:
	v_add_u32_e32 v84, s0, v195
	ds_read_b128 v[68:71], v84
	ds_read_b128 v[72:75], v84 offset:16
	ds_read_b128 v[76:79], v84 offset:32
	ds_read_b128 v[80:83], v84 offset:48
	ds_read_b128 v[100:103], v84 offset:64
	ds_read_b128 v[104:107], v84 offset:80
	ds_read_b128 v[108:111], v84 offset:96
	ds_read_b128 v[112:115], v84 offset:112
	s_addk_i32 s0, 0x80
	s_waitcnt vmcnt(1) lgkmcnt(7)
	v_fma_f32 v85, v63, v68, v66
	v_fmac_f32_e32 v85, v64, v69
	v_fmac_f32_e32 v85, v60, v70
	v_fmac_f32_e32 v85, v65, v71
	s_waitcnt lgkmcnt(6)
	v_fmac_f32_e32 v85, v61, v72
	v_fmac_f32_e32 v85, v62, v73
	v_pk_mul_f32 v[68:69], v[34:35], v[74:75]
	v_add_f32_e32 v68, v85, v68
	v_add_f32_e32 v70, v68, v69
	s_waitcnt lgkmcnt(5)
	v_pk_mul_f32 v[68:69], v[36:37], v[76:77]
	s_nop 0
	v_add_f32_e32 v68, v70, v68
	v_add_f32_e32 v70, v68, v69
	v_pk_mul_f32 v[68:69], v[38:39], v[78:79]
	s_nop 0
	v_add_f32_e32 v68, v70, v68
	v_add_f32_e32 v70, v68, v69
	s_waitcnt lgkmcnt(4)
	v_pk_mul_f32 v[68:69], v[40:41], v[80:81]
	s_nop 0
	v_add_f32_e32 v68, v70, v68
	v_add_f32_e32 v70, v68, v69
	s_waitcnt vmcnt(0)
	v_pk_mul_f32 v[68:69], v[58:59], v[82:83]
	s_nop 0
	v_add_f32_e32 v68, v70, v68
	v_add_f32_e32 v68, v68, v69
	v_min_f32_e32 v69, 0, v68
	v_mul_f32_e64 v68, |v68|, s73
	v_exp_f32_e32 v68, v68
	s_nop 0
	v_add_f32_e32 v68, 1.0, v68
	v_cmp_gt_f32_e32 vcc, s94, v68
	s_nop 1
	v_cndmask_b32_e64 v70, 0, 32, vcc
	v_ldexp_f32 v68, v68, v70
	v_log_f32_e32 v68, v68
	s_nop 0
	v_mul_f32_e32 v70, 0x3f317217, v68
	v_fma_f32 v70, v68, s97, -v70
	v_fmac_f32_e32 v70, 0x3377d1cf, v68
	v_fmac_f32_e32 v70, 0x3f317217, v68
	v_cmp_lt_f32_e64 s[14:15], |v68|, s23
	s_nop 1
	v_cndmask_b32_e64 v68, v68, v70, s[14:15]
	v_cndmask_b32_e32 v70, 0, v211, vcc
	v_sub_f32_e32 v68, v68, v70
	v_sub_f32_e32 v68, v69, v68
	v_fmac_f32_e32 v67, 0x3d800000, v68
	v_mov_b32_e32 v86, v68
	s_waitcnt lgkmcnt(0)
	v_fma_f32 v72, v63, v100, v66
	v_fmac_f32_e32 v72, v64, v101
	v_fmac_f32_e32 v72, v60, v102
	v_fmac_f32_e32 v72, v65, v103
	v_fmac_f32_e32 v72, v61, v104
	v_fmac_f32_e32 v72, v62, v105
	v_pk_mul_f32 v[68:69], v[34:35], v[106:107]
	s_nop 0
	v_add_f32_e32 v68, v72, v68
	v_add_f32_e32 v72, v68, v69
	v_pk_mul_f32 v[68:69], v[36:37], v[108:109]
	s_nop 0
	v_add_f32_e32 v68, v72, v68
	v_add_f32_e32 v72, v68, v69
	v_pk_mul_f32 v[68:69], v[38:39], v[110:111]
	s_nop 0
	v_add_f32_e32 v68, v72, v68
	v_add_f32_e32 v72, v68, v69
	v_pk_mul_f32 v[68:69], v[40:41], v[112:113]
	s_nop 0
	v_add_f32_e32 v68, v72, v68
	v_add_f32_e32 v72, v68, v69
	v_pk_mul_f32 v[68:69], v[58:59], v[114:115]
	s_nop 0
	v_add_f32_e32 v68, v72, v68
	v_add_f32_e32 v68, v68, v69
	v_min_f32_e32 v69, 0, v68
	v_mul_f32_e64 v68, |v68|, s73
	v_exp_f32_e32 v68, v68
	s_nop 0
	v_add_f32_e32 v68, 1.0, v68
	v_cmp_gt_f32_e32 vcc, s94, v68
	s_nop 1
	v_cndmask_b32_e64 v70, 0, 32, vcc
	v_ldexp_f32 v68, v68, v70
	v_log_f32_e32 v68, v68
	s_nop 0
	v_mul_f32_e32 v70, 0x3f317217, v68
	v_fma_f32 v70, v68, s97, -v70
	v_fmac_f32_e32 v70, 0x3377d1cf, v68
	v_fmac_f32_e32 v70, 0x3f317217, v68
	v_cmp_lt_f32_e64 s[14:15], |v68|, s23
	s_nop 1
	v_cndmask_b32_e64 v68, v68, v70, s[14:15]
	v_cndmask_b32_e32 v70, 0, v211, vcc
	v_sub_f32_e32 v68, v68, v70
	v_sub_f32_e32 v68, v69, v68
	v_fmac_f32_e32 v67, 0x3d800000, v68
	v_mov_b32_e32 v87, v68
	v_add_u32_e32 v84, s0, v195
	ds_read_b128 v[68:71], v84
	ds_read_b128 v[72:75], v84 offset:16
	ds_read_b128 v[76:79], v84 offset:32
	ds_read_b128 v[80:83], v84 offset:48
	ds_read_b128 v[100:103], v84 offset:64
	ds_read_b128 v[104:107], v84 offset:80
	ds_read_b128 v[108:111], v84 offset:96
	ds_read_b128 v[112:115], v84 offset:112
	s_addk_i32 s0, 0x80
	s_waitcnt vmcnt(1) lgkmcnt(7)
	v_fma_f32 v85, v63, v68, v66
	v_fmac_f32_e32 v85, v64, v69
	v_fmac_f32_e32 v85, v60, v70
	v_fmac_f32_e32 v85, v65, v71
	s_waitcnt lgkmcnt(6)
	v_fmac_f32_e32 v85, v61, v72
	v_fmac_f32_e32 v85, v62, v73
	v_pk_mul_f32 v[68:69], v[34:35], v[74:75]
	v_add_f32_e32 v68, v85, v68
	v_add_f32_e32 v70, v68, v69
	s_waitcnt lgkmcnt(5)
	v_pk_mul_f32 v[68:69], v[36:37], v[76:77]
	s_nop 0
	v_add_f32_e32 v68, v70, v68
	v_add_f32_e32 v70, v68, v69
	v_pk_mul_f32 v[68:69], v[38:39], v[78:79]
	s_nop 0
	v_add_f32_e32 v68, v70, v68
	v_add_f32_e32 v70, v68, v69
	s_waitcnt lgkmcnt(4)
	v_pk_mul_f32 v[68:69], v[40:41], v[80:81]
	s_nop 0
	v_add_f32_e32 v68, v70, v68
	v_add_f32_e32 v70, v68, v69
	s_waitcnt vmcnt(0)
	v_pk_mul_f32 v[68:69], v[58:59], v[82:83]
	s_nop 0
	v_add_f32_e32 v68, v70, v68
	v_add_f32_e32 v68, v68, v69
	v_min_f32_e32 v69, 0, v68
	v_mul_f32_e64 v68, |v68|, s73
	v_exp_f32_e32 v68, v68
	s_nop 0
	v_add_f32_e32 v68, 1.0, v68
	v_cmp_gt_f32_e32 vcc, s94, v68
	s_nop 1
	v_cndmask_b32_e64 v70, 0, 32, vcc
	v_ldexp_f32 v68, v68, v70
	v_log_f32_e32 v68, v68
	s_nop 0
	v_mul_f32_e32 v70, 0x3f317217, v68
	v_fma_f32 v70, v68, s97, -v70
	v_fmac_f32_e32 v70, 0x3377d1cf, v68
	v_fmac_f32_e32 v70, 0x3f317217, v68
	v_cmp_lt_f32_e64 s[14:15], |v68|, s23
	s_nop 1
	v_cndmask_b32_e64 v68, v68, v70, s[14:15]
	v_cndmask_b32_e32 v70, 0, v211, vcc
	v_sub_f32_e32 v68, v68, v70
	v_sub_f32_e32 v68, v69, v68
	v_fmac_f32_e32 v67, 0x3d800000, v68
	v_mov_b32_e32 v88, v68
	s_waitcnt lgkmcnt(0)
; DEVI float logsigf_(float x) { return fminf(x, 0.f) - __logf(1.f + __expf(-fabsf(x))); }
; DEVI float gla_la(const float* gl, int t, const float* w2r, float gb) { float x = gb;
; #pragma unroll
;     for (int r = 0; r < 16; ++r) x += gl[t * 16 + r] * w2r[r];
;     return logsigf_(x) * (1.f / 16.f); }
; template <int KIND>
; DEVI void mix_out_phase(unsigned char* smem, const MixArgs a) {
;     ...
;             const int ch = tid & 127, sg = tid >> 7; float w2r[16];
; #pragma unroll
;             for (int r = 0; r < 16; ++r) w2r[r] = a.w2[r * 512 + h * 128 + ch];
;             const float gb = a.gateb[h * 128 + ch]; float ssum = 0.f;
;             for (int t = sg * 32; t < sg * 32 + 32; ++t) ssum += gla_la(gl, t, w2r, gb);
	v_fma_f32 v72, v63, v100, v66
	v_fmac_f32_e32 v72, v64, v101
	v_fmac_f32_e32 v72, v60, v102
	v_fmac_f32_e32 v72, v65, v103
	v_fmac_f32_e32 v72, v61, v104
	v_fmac_f32_e32 v72, v62, v105
	v_pk_mul_f32 v[68:69], v[34:35], v[106:107]
	s_nop 0
	v_add_f32_e32 v68, v72, v68
	v_add_f32_e32 v72, v68, v69
	v_pk_mul_f32 v[68:69], v[36:37], v[108:109]
	s_nop 0
	v_add_f32_e32 v68, v72, v68
	v_add_f32_e32 v72, v68, v69
	v_pk_mul_f32 v[68:69], v[38:39], v[110:111]
	s_nop 0
	v_add_f32_e32 v68, v72, v68
	v_add_f32_e32 v72, v68, v69
	v_pk_mul_f32 v[68:69], v[40:41], v[112:113]
	s_nop 0
	v_add_f32_e32 v68, v72, v68
	v_add_f32_e32 v72, v68, v69
	v_pk_mul_f32 v[68:69], v[58:59], v[114:115]
	s_nop 0
	v_add_f32_e32 v68, v72, v68
	v_add_f32_e32 v68, v68, v69
	v_min_f32_e32 v69, 0, v68
	v_mul_f32_e64 v68, |v68|, s73
	v_exp_f32_e32 v68, v68
	s_nop 0
	v_add_f32_e32 v68, 1.0, v68
	v_cmp_gt_f32_e32 vcc, s94, v68
	s_nop 1
	v_cndmask_b32_e64 v70, 0, 32, vcc
	v_ldexp_f32 v68, v68, v70
	v_log_f32_e32 v68, v68
	s_nop 0
	v_mul_f32_e32 v70, 0x3f317217, v68
	v_fma_f32 v70, v68, s97, -v70
	v_fmac_f32_e32 v70, 0x3377d1cf, v68
	v_fmac_f32_e32 v70, 0x3f317217, v68
	v_cmp_lt_f32_e64 s[14:15], |v68|, s23
	s_nop 1
	v_cndmask_b32_e64 v68, v68, v70, s[14:15]
	v_cndmask_b32_e32 v70, 0, v211, vcc
	v_sub_f32_e32 v68, v68, v70
	v_sub_f32_e32 v68, v69, v68
	v_fmac_f32_e32 v67, 0x3d800000, v68
	v_mov_b32_e32 v89, v68
	v_add_u32_e32 v84, s0, v195
	ds_read_b128 v[68:71], v84
	ds_read_b128 v[72:75], v84 offset:16
	ds_read_b128 v[76:79], v84 offset:32
	ds_read_b128 v[80:83], v84 offset:48
	ds_read_b128 v[100:103], v84 offset:64
	ds_read_b128 v[104:107], v84 offset:80
	ds_read_b128 v[108:111], v84 offset:96
	ds_read_b128 v[112:115], v84 offset:112
	s_addk_i32 s0, 0x80
	s_waitcnt vmcnt(1) lgkmcnt(7)
	v_fma_f32 v85, v63, v68, v66
	v_fmac_f32_e32 v85, v64, v69
	v_fmac_f32_e32 v85, v60, v70
	v_fmac_f32_e32 v85, v65, v71
	s_waitcnt lgkmcnt(6)
	v_fmac_f32_e32 v85, v61, v72
	v_fmac_f32_e32 v85, v62, v73
	v_pk_mul_f32 v[68:69], v[34:35], v[74:75]
	v_add_f32_e32 v68, v85, v68
	v_add_f32_e32 v70, v68, v69
	s_waitcnt lgkmcnt(5)
	v_pk_mul_f32 v[68:69], v[36:37], v[76:77]
	s_nop 0
	v_add_f32_e32 v68, v70, v68
	v_add_f32_e32 v70, v68, v69
	v_pk_mul_f32 v[68:69], v[38:39], v[78:79]
	s_nop 0
	v_add_f32_e32 v68, v70, v68
	v_add_f32_e32 v70, v68, v69
	s_waitcnt lgkmcnt(4)
	v_pk_mul_f32 v[68:69], v[40:41], v[80:81]
	s_nop 0
	v_add_f32_e32 v68, v70, v68
	v_add_f32_e32 v70, v68, v69
	s_waitcnt vmcnt(0)
	v_pk_mul_f32 v[68:69], v[58:59], v[82:83]
	s_nop 0
	v_add_f32_e32 v68, v70, v68
	v_add_f32_e32 v68, v68, v69
	v_min_f32_e32 v69, 0, v68
	v_mul_f32_e64 v68, |v68|, s73
	v_exp_f32_e32 v68, v68
	s_nop 0
	v_add_f32_e32 v68, 1.0, v68
	v_cmp_gt_f32_e32 vcc, s94, v68
	s_nop 1
	v_cndmask_b32_e64 v70, 0, 32, vcc
	v_ldexp_f32 v68, v68, v70
	v_log_f32_e32 v68, v68
	s_nop 0
	v_mul_f32_e32 v70, 0x3f317217, v68
	v_fma_f32 v70, v68, s97, -v70
	v_fmac_f32_e32 v70, 0x3377d1cf, v68
	v_fmac_f32_e32 v70, 0x3f317217, v68
	v_cmp_lt_f32_e64 s[14:15], |v68|, s23
	s_nop 1
	v_cndmask_b32_e64 v68, v68, v70, s[14:15]
	v_cndmask_b32_e32 v70, 0, v211, vcc
	v_sub_f32_e32 v68, v68, v70
	v_sub_f32_e32 v68, v69, v68
	v_fmac_f32_e32 v67, 0x3d800000, v68
	v_mov_b32_e32 v90, v68
	s_waitcnt lgkmcnt(0)
	v_fma_f32 v72, v63, v100, v66
	v_fmac_f32_e32 v72, v64, v101
	v_fmac_f32_e32 v72, v60, v102
	v_fmac_f32_e32 v72, v65, v103
	v_fmac_f32_e32 v72, v61, v104
	v_fmac_f32_e32 v72, v62, v105
	v_pk_mul_f32 v[68:69], v[34:35], v[106:107]
	s_nop 0
	v_add_f32_e32 v68, v72, v68
	v_add_f32_e32 v72, v68, v69
	v_pk_mul_f32 v[68:69], v[36:37], v[108:109]
	s_nop 0
	v_add_f32_e32 v68, v72, v68
	v_add_f32_e32 v72, v68, v69
	v_pk_mul_f32 v[68:69], v[38:39], v[110:111]
	s_nop 0
	v_add_f32_e32 v68, v72, v68
	v_add_f32_e32 v72, v68, v69
	v_pk_mul_f32 v[68:69], v[40:41], v[112:113]
	s_nop 0
	v_add_f32_e32 v68, v72, v68
	v_add_f32_e32 v72, v68, v69
	v_pk_mul_f32 v[68:69], v[58:59], v[114:115]
	s_nop 0
	v_add_f32_e32 v68, v72, v68
	v_add_f32_e32 v68, v68, v69
	v_min_f32_e32 v69, 0, v68
	v_mul_f32_e64 v68, |v68|, s73
	v_exp_f32_e32 v68, v68
	s_nop 0
	v_add_f32_e32 v68, 1.0, v68
	v_cmp_gt_f32_e32 vcc, s94, v68
	s_nop 1
	v_cndmask_b32_e64 v70, 0, 32, vcc
	v_ldexp_f32 v68, v68, v70
	v_log_f32_e32 v68, v68
	s_nop 0
	v_mul_f32_e32 v70, 0x3f317217, v68
	v_fma_f32 v70, v68, s97, -v70
	v_fmac_f32_e32 v70, 0x3377d1cf, v68
	v_fmac_f32_e32 v70, 0x3f317217, v68
	v_cmp_lt_f32_e64 s[14:15], |v68|, s23
	s_nop 1
	v_cndmask_b32_e64 v68, v68, v70, s[14:15]
	v_cndmask_b32_e32 v70, 0, v211, vcc
	v_sub_f32_e32 v68, v68, v70
	v_sub_f32_e32 v68, v69, v68
	v_fmac_f32_e32 v67, 0x3d800000, v68
	v_mov_b32_e32 v91, v68
	v_add_u32_e32 v84, s0, v195
	ds_read_b128 v[68:71], v84
	ds_read_b128 v[72:75], v84 offset:16
	ds_read_b128 v[76:79], v84 offset:32
	ds_read_b128 v[80:83], v84 offset:48
	ds_read_b128 v[100:103], v84 offset:64
	ds_read_b128 v[104:107], v84 offset:80
	ds_read_b128 v[108:111], v84 offset:96
	ds_read_b128 v[112:115], v84 offset:112
	s_addk_i32 s0, 0x80
	s_waitcnt vmcnt(1) lgkmcnt(7)
	v_fma_f32 v85, v63, v68, v66
	v_fmac_f32_e32 v85, v64, v69
	v_fmac_f32_e32 v85, v60, v70
	v_fmac_f32_e32 v85, v65, v71
	s_waitcnt lgkmcnt(6)
	v_fmac_f32_e32 v85, v61, v72
	v_fmac_f32_e32 v85, v62, v73
	v_pk_mul_f32 v[68:69], v[34:35], v[74:75]
	v_add_f32_e32 v68, v85, v68
	v_add_f32_e32 v70, v68, v69
	s_waitcnt lgkmcnt(5)
	v_pk_mul_f32 v[68:69], v[36:37], v[76:77]
	s_nop 0
	v_add_f32_e32 v68, v70, v68
	v_add_f32_e32 v70, v68, v69
	v_pk_mul_f32 v[68:69], v[38:39], v[78:79]
	s_nop 0
	v_add_f32_e32 v68, v70, v68
	v_add_f32_e32 v70, v68, v69
	s_waitcnt lgkmcnt(4)
; DEVI float logsigf_(float x) { return fminf(x, 0.f) - __logf(1.f + __expf(-fabsf(x))); }
; DEVI float gla_la(const float* gl, int t, const float* w2r, float gb) { float x = gb;
; #pragma unroll
;     for (int r = 0; r < 16; ++r) x += gl[t * 16 + r] * w2r[r];
;     return logsigf_(x) * (1.f / 16.f); }
; template <int KIND>
; DEVI void mix_out_phase(unsigned char* smem, const MixArgs a) {
;     ...
;             const int ch = tid & 127, sg = tid >> 7; float w2r[16];
; #pragma unroll
;             for (int r = 0; r < 16; ++r) w2r[r] = a.w2[r * 512 + h * 128 + ch];
;             const float gb = a.gateb[h * 128 + ch]; float ssum = 0.f;
;             for (int t = sg * 32; t < sg * 32 + 32; ++t) ssum += gla_la(gl, t, w2r, gb);
	v_pk_mul_f32 v[68:69], v[40:41], v[80:81]
	s_nop 0
	v_add_f32_e32 v68, v70, v68
	v_add_f32_e32 v70, v68, v69
	s_waitcnt vmcnt(0)
	v_pk_mul_f32 v[68:69], v[58:59], v[82:83]
	s_nop 0
	v_add_f32_e32 v68, v70, v68
	v_add_f32_e32 v68, v68, v69
	v_min_f32_e32 v69, 0, v68
	v_mul_f32_e64 v68, |v68|, s73
	v_exp_f32_e32 v68, v68
	s_nop 0
	v_add_f32_e32 v68, 1.0, v68
	v_cmp_gt_f32_e32 vcc, s94, v68
	s_nop 1
	v_cndmask_b32_e64 v70, 0, 32, vcc
	v_ldexp_f32 v68, v68, v70
	v_log_f32_e32 v68, v68
	s_nop 0
	v_mul_f32_e32 v70, 0x3f317217, v68
	v_fma_f32 v70, v68, s97, -v70
	v_fmac_f32_e32 v70, 0x3377d1cf, v68
	v_fmac_f32_e32 v70, 0x3f317217, v68
	v_cmp_lt_f32_e64 s[14:15], |v68|, s23
	s_nop 1
	v_cndmask_b32_e64 v68, v68, v70, s[14:15]
	v_cndmask_b32_e32 v70, 0, v211, vcc
	v_sub_f32_e32 v68, v68, v70
	v_sub_f32_e32 v68, v69, v68
	v_fmac_f32_e32 v67, 0x3d800000, v68
	v_mov_b32_e32 v92, v68
	s_waitcnt lgkmcnt(0)
	v_fma_f32 v72, v63, v100, v66
	v_fmac_f32_e32 v72, v64, v101
	v_fmac_f32_e32 v72, v60, v102
	v_fmac_f32_e32 v72, v65, v103
	v_fmac_f32_e32 v72, v61, v104
	v_fmac_f32_e32 v72, v62, v105
	v_pk_mul_f32 v[68:69], v[34:35], v[106:107]
	s_nop 0
	v_add_f32_e32 v68, v72, v68
	v_add_f32_e32 v72, v68, v69
	v_pk_mul_f32 v[68:69], v[36:37], v[108:109]
	s_nop 0
	v_add_f32_e32 v68, v72, v68
	v_add_f32_e32 v72, v68, v69
	v_pk_mul_f32 v[68:69], v[38:39], v[110:111]
	s_nop 0
	v_add_f32_e32 v68, v72, v68
	v_add_f32_e32 v72, v68, v69
	v_pk_mul_f32 v[68:69], v[40:41], v[112:113]
	s_nop 0
	v_add_f32_e32 v68, v72, v68
	v_add_f32_e32 v72, v68, v69
	v_pk_mul_f32 v[68:69], v[58:59], v[114:115]
	s_nop 0
	v_add_f32_e32 v68, v72, v68
	v_add_f32_e32 v68, v68, v69
	v_min_f32_e32 v69, 0, v68
	v_mul_f32_e64 v68, |v68|, s73
	v_exp_f32_e32 v68, v68
	s_nop 0
	v_add_f32_e32 v68, 1.0, v68
	v_cmp_gt_f32_e32 vcc, s94, v68
	s_nop 1
	v_cndmask_b32_e64 v70, 0, 32, vcc
	v_ldexp_f32 v68, v68, v70
	v_log_f32_e32 v68, v68
	s_nop 0
	v_mul_f32_e32 v70, 0x3f317217, v68
	v_fma_f32 v70, v68, s97, -v70
	v_fmac_f32_e32 v70, 0x3377d1cf, v68
	v_fmac_f32_e32 v70, 0x3f317217, v68
	v_cmp_lt_f32_e64 s[14:15], |v68|, s23
	s_nop 1
	v_cndmask_b32_e64 v68, v68, v70, s[14:15]
	v_cndmask_b32_e32 v70, 0, v211, vcc
	v_sub_f32_e32 v68, v68, v70
	v_sub_f32_e32 v68, v69, v68
	v_fmac_f32_e32 v67, 0x3d800000, v68
	v_mov_b32_e32 v93, v68
	v_add_u32_e32 v84, s0, v195
	ds_read_b128 v[68:71], v84
	ds_read_b128 v[72:75], v84 offset:16
	ds_read_b128 v[76:79], v84 offset:32
	ds_read_b128 v[80:83], v84 offset:48
	ds_read_b128 v[100:103], v84 offset:64
	ds_read_b128 v[104:107], v84 offset:80
	ds_read_b128 v[108:111], v84 offset:96
	ds_read_b128 v[112:115], v84 offset:112
	s_addk_i32 s0, 0x80
	s_waitcnt vmcnt(1) lgkmcnt(7)
	v_fma_f32 v85, v63, v68, v66
	v_fmac_f32_e32 v85, v64, v69
	v_fmac_f32_e32 v85, v60, v70
	v_fmac_f32_e32 v85, v65, v71
	s_waitcnt lgkmcnt(6)
	v_fmac_f32_e32 v85, v61, v72
	v_fmac_f32_e32 v85, v62, v73
	v_pk_mul_f32 v[68:69], v[34:35], v[74:75]
	v_add_f32_e32 v68, v85, v68
	v_add_f32_e32 v70, v68, v69
	s_waitcnt lgkmcnt(5)
	v_pk_mul_f32 v[68:69], v[36:37], v[76:77]
	s_nop 0
	v_add_f32_e32 v68, v70, v68
	v_add_f32_e32 v70, v68, v69
	v_pk_mul_f32 v[68:69], v[38:39], v[78:79]
	s_nop 0
	v_add_f32_e32 v68, v70, v68
	v_add_f32_e32 v70, v68, v69
	s_waitcnt lgkmcnt(4)
	v_pk_mul_f32 v[68:69], v[40:41], v[80:81]
	s_nop 0
	v_add_f32_e32 v68, v70, v68
	v_add_f32_e32 v70, v68, v69
	s_waitcnt vmcnt(0)
	v_pk_mul_f32 v[68:69], v[58:59], v[82:83]
	s_nop 0
	v_add_f32_e32 v68, v70, v68
	v_add_f32_e32 v68, v68, v69
	v_min_f32_e32 v69, 0, v68
	v_mul_f32_e64 v68, |v68|, s73
	v_exp_f32_e32 v68, v68
	s_nop 0
	v_add_f32_e32 v68, 1.0, v68
	v_cmp_gt_f32_e32 vcc, s94, v68
	s_nop 1
	v_cndmask_b32_e64 v70, 0, 32, vcc
	v_ldexp_f32 v68, v68, v70
	v_log_f32_e32 v68, v68
	s_nop 0
	v_mul_f32_e32 v70, 0x3f317217, v68
	v_fma_f32 v70, v68, s97, -v70
	v_fmac_f32_e32 v70, 0x3377d1cf, v68
	v_fmac_f32_e32 v70, 0x3f317217, v68
	v_cmp_lt_f32_e64 s[14:15], |v68|, s23
	s_nop 1
	v_cndmask_b32_e64 v68, v68, v70, s[14:15]
	v_cndmask_b32_e32 v70, 0, v211, vcc
	v_sub_f32_e32 v68, v68, v70
	v_sub_f32_e32 v68, v69, v68
	v_fmac_f32_e32 v67, 0x3d800000, v68
	v_mov_b32_e32 v94, v68
	s_waitcnt lgkmcnt(0)
	v_fma_f32 v72, v63, v100, v66
	v_fmac_f32_e32 v72, v64, v101
	v_fmac_f32_e32 v72, v60, v102
	v_fmac_f32_e32 v72, v65, v103
	v_fmac_f32_e32 v72, v61, v104
	v_fmac_f32_e32 v72, v62, v105
	v_pk_mul_f32 v[68:69], v[34:35], v[106:107]
	s_nop 0
	v_add_f32_e32 v68, v72, v68
	v_add_f32_e32 v72, v68, v69
	v_pk_mul_f32 v[68:69], v[36:37], v[108:109]
	s_nop 0
	v_add_f32_e32 v68, v72, v68
	v_add_f32_e32 v72, v68, v69
	v_pk_mul_f32 v[68:69], v[38:39], v[110:111]
	s_nop 0
	v_add_f32_e32 v68, v72, v68
	v_add_f32_e32 v72, v68, v69
	v_pk_mul_f32 v[68:69], v[40:41], v[112:113]
	s_nop 0
	v_add_f32_e32 v68, v72, v68
	v_add_f32_e32 v72, v68, v69
	v_pk_mul_f32 v[68:69], v[58:59], v[114:115]
	s_nop 0
	v_add_f32_e32 v68, v72, v68
	v_add_f32_e32 v68, v68, v69
	v_min_f32_e32 v69, 0, v68
	v_mul_f32_e64 v68, |v68|, s73
	v_exp_f32_e32 v68, v68
	s_nop 0
	v_add_f32_e32 v68, 1.0, v68
	v_cmp_gt_f32_e32 vcc, s94, v68
	s_nop 1
	v_cndmask_b32_e64 v70, 0, 32, vcc
	v_ldexp_f32 v68, v68, v70
	v_log_f32_e32 v68, v68
	s_nop 0
	v_mul_f32_e32 v70, 0x3f317217, v68
	v_fma_f32 v70, v68, s97, -v70
	v_fmac_f32_e32 v70, 0x3377d1cf, v68
	v_fmac_f32_e32 v70, 0x3f317217, v68
	v_cmp_lt_f32_e64 s[14:15], |v68|, s23
	s_nop 1
	v_cndmask_b32_e64 v68, v68, v70, s[14:15]
	v_cndmask_b32_e32 v70, 0, v211, vcc
	v_sub_f32_e32 v68, v68, v70
	v_sub_f32_e32 v68, v69, v68
	v_fmac_f32_e32 v67, 0x3d800000, v68
	v_mov_b32_e32 v95, v68
	v_add_u32_e32 v84, s0, v195
	ds_read_b128 v[68:71], v84
	ds_read_b128 v[72:75], v84 offset:16
	ds_read_b128 v[76:79], v84 offset:32
	ds_read_b128 v[80:83], v84 offset:48
	ds_read_b128 v[100:103], v84 offset:64
	ds_read_b128 v[104:107], v84 offset:80
	ds_read_b128 v[108:111], v84 offset:96
	ds_read_b128 v[112:115], v84 offset:112
	s_addk_i32 s0, 0x80
	s_waitcnt vmcnt(1) lgkmcnt(7)
; DEVI float logsigf_(float x) { return fminf(x, 0.f) - __logf(1.f + __expf(-fabsf(x))); }
; DEVI float gla_la(const float* gl, int t, const float* w2r, float gb) { float x = gb;
; #pragma unroll
;     for (int r = 0; r < 16; ++r) x += gl[t * 16 + r] * w2r[r];
;     return logsigf_(x) * (1.f / 16.f); }
; template <int KIND>
; DEVI void mix_out_phase(unsigned char* smem, const MixArgs a) {
;     ...
;             const int ch = tid & 127, sg = tid >> 7; float w2r[16];
; #pragma unroll
;             for (int r = 0; r < 16; ++r) w2r[r] = a.w2[r * 512 + h * 128 + ch];
;             const float gb = a.gateb[h * 128 + ch]; float ssum = 0.f;
;             for (int t = sg * 32; t < sg * 32 + 32; ++t) ssum += gla_la(gl, t, w2r, gb);
	v_fma_f32 v85, v63, v68, v66
	v_fmac_f32_e32 v85, v64, v69
	v_fmac_f32_e32 v85, v60, v70
	v_fmac_f32_e32 v85, v65, v71
	s_waitcnt lgkmcnt(6)
	v_fmac_f32_e32 v85, v61, v72
	v_fmac_f32_e32 v85, v62, v73
	v_pk_mul_f32 v[68:69], v[34:35], v[74:75]
	v_add_f32_e32 v68, v85, v68
	v_add_f32_e32 v70, v68, v69
	s_waitcnt lgkmcnt(5)
	v_pk_mul_f32 v[68:69], v[36:37], v[76:77]
	s_nop 0
	v_add_f32_e32 v68, v70, v68
	v_add_f32_e32 v70, v68, v69
	v_pk_mul_f32 v[68:69], v[38:39], v[78:79]
	s_nop 0
	v_add_f32_e32 v68, v70, v68
	v_add_f32_e32 v70, v68, v69
	s_waitcnt lgkmcnt(4)
	v_pk_mul_f32 v[68:69], v[40:41], v[80:81]
	s_nop 0
	v_add_f32_e32 v68, v70, v68
	v_add_f32_e32 v70, v68, v69
	s_waitcnt vmcnt(0)
	v_pk_mul_f32 v[68:69], v[58:59], v[82:83]
	s_nop 0
	v_add_f32_e32 v68, v70, v68
	v_add_f32_e32 v68, v68, v69
	v_min_f32_e32 v69, 0, v68
	v_mul_f32_e64 v68, |v68|, s73
	v_exp_f32_e32 v68, v68
	s_nop 0
	v_add_f32_e32 v68, 1.0, v68
	v_cmp_gt_f32_e32 vcc, s94, v68
	s_nop 1
	v_cndmask_b32_e64 v70, 0, 32, vcc
	v_ldexp_f32 v68, v68, v70
	v_log_f32_e32 v68, v68
	s_nop 0
	v_mul_f32_e32 v70, 0x3f317217, v68
	v_fma_f32 v70, v68, s97, -v70
	v_fmac_f32_e32 v70, 0x3377d1cf, v68
	v_fmac_f32_e32 v70, 0x3f317217, v68
	v_cmp_lt_f32_e64 s[14:15], |v68|, s23
	s_nop 1
	v_cndmask_b32_e64 v68, v68, v70, s[14:15]
	v_cndmask_b32_e32 v70, 0, v211, vcc
	v_sub_f32_e32 v68, v68, v70
	v_sub_f32_e32 v68, v69, v68
	v_fmac_f32_e32 v67, 0x3d800000, v68
	v_mov_b32_e32 v96, v68
	s_waitcnt lgkmcnt(0)
	v_fma_f32 v72, v63, v100, v66
	v_fmac_f32_e32 v72, v64, v101
	v_fmac_f32_e32 v72, v60, v102
	v_fmac_f32_e32 v72, v65, v103
	v_fmac_f32_e32 v72, v61, v104
	v_fmac_f32_e32 v72, v62, v105
	v_pk_mul_f32 v[68:69], v[34:35], v[106:107]
	s_nop 0
	v_add_f32_e32 v68, v72, v68
	v_add_f32_e32 v72, v68, v69
	v_pk_mul_f32 v[68:69], v[36:37], v[108:109]
	s_nop 0
	v_add_f32_e32 v68, v72, v68
	v_add_f32_e32 v72, v68, v69
	v_pk_mul_f32 v[68:69], v[38:39], v[110:111]
	s_nop 0
	v_add_f32_e32 v68, v72, v68
	v_add_f32_e32 v72, v68, v69
	v_pk_mul_f32 v[68:69], v[40:41], v[112:113]
	s_nop 0
	v_add_f32_e32 v68, v72, v68
	v_add_f32_e32 v72, v68, v69
	v_pk_mul_f32 v[68:69], v[58:59], v[114:115]
	s_nop 0
	v_add_f32_e32 v68, v72, v68
	v_add_f32_e32 v68, v68, v69
	v_min_f32_e32 v69, 0, v68
	v_mul_f32_e64 v68, |v68|, s73
	v_exp_f32_e32 v68, v68
	s_nop 0
	v_add_f32_e32 v68, 1.0, v68
	v_cmp_gt_f32_e32 vcc, s94, v68
	s_nop 1
	v_cndmask_b32_e64 v70, 0, 32, vcc
	v_ldexp_f32 v68, v68, v70
	v_log_f32_e32 v68, v68
	s_nop 0
	v_mul_f32_e32 v70, 0x3f317217, v68
	v_fma_f32 v70, v68, s97, -v70
	v_fmac_f32_e32 v70, 0x3377d1cf, v68
	v_fmac_f32_e32 v70, 0x3f317217, v68
	v_cmp_lt_f32_e64 s[14:15], |v68|, s23
	s_nop 1
	v_cndmask_b32_e64 v68, v68, v70, s[14:15]
	v_cndmask_b32_e32 v70, 0, v211, vcc
	v_sub_f32_e32 v68, v68, v70
	v_sub_f32_e32 v68, v69, v68
	v_fmac_f32_e32 v67, 0x3d800000, v68
	v_mov_b32_e32 v97, v68
	v_add_u32_e32 v84, s0, v195
	ds_read_b128 v[68:71], v84
	ds_read_b128 v[72:75], v84 offset:16
	ds_read_b128 v[76:79], v84 offset:32
	ds_read_b128 v[80:83], v84 offset:48
	ds_read_b128 v[100:103], v84 offset:64
	ds_read_b128 v[104:107], v84 offset:80
	ds_read_b128 v[108:111], v84 offset:96
	ds_read_b128 v[112:115], v84 offset:112
	s_addk_i32 s0, 0x80
	s_waitcnt vmcnt(1) lgkmcnt(7)
	v_fma_f32 v85, v63, v68, v66
	v_fmac_f32_e32 v85, v64, v69
	v_fmac_f32_e32 v85, v60, v70
	v_fmac_f32_e32 v85, v65, v71
	s_waitcnt lgkmcnt(6)
	v_fmac_f32_e32 v85, v61, v72
	v_fmac_f32_e32 v85, v62, v73
	v_pk_mul_f32 v[68:69], v[34:35], v[74:75]
	v_add_f32_e32 v68, v85, v68
	v_add_f32_e32 v70, v68, v69
	s_waitcnt lgkmcnt(5)
	v_pk_mul_f32 v[68:69], v[36:37], v[76:77]
	s_nop 0
	v_add_f32_e32 v68, v70, v68
	v_add_f32_e32 v70, v68, v69
	v_pk_mul_f32 v[68:69], v[38:39], v[78:79]
	s_nop 0
	v_add_f32_e32 v68, v70, v68
	v_add_f32_e32 v70, v68, v69
	s_waitcnt lgkmcnt(4)
	v_pk_mul_f32 v[68:69], v[40:41], v[80:81]
	s_nop 0
	v_add_f32_e32 v68, v70, v68
	v_add_f32_e32 v70, v68, v69
	s_waitcnt vmcnt(0)
	v_pk_mul_f32 v[68:69], v[58:59], v[82:83]
	s_nop 0
	v_add_f32_e32 v68, v70, v68
	v_add_f32_e32 v68, v68, v69
	v_min_f32_e32 v69, 0, v68
	v_mul_f32_e64 v68, |v68|, s73
	v_exp_f32_e32 v68, v68
	s_nop 0
	v_add_f32_e32 v68, 1.0, v68
	v_cmp_gt_f32_e32 vcc, s94, v68
	s_nop 1
	v_cndmask_b32_e64 v70, 0, 32, vcc
	v_ldexp_f32 v68, v68, v70
	v_log_f32_e32 v68, v68
	s_nop 0
	v_mul_f32_e32 v70, 0x3f317217, v68
	v_fma_f32 v70, v68, s97, -v70
	v_fmac_f32_e32 v70, 0x3377d1cf, v68
	v_fmac_f32_e32 v70, 0x3f317217, v68
	v_cmp_lt_f32_e64 s[14:15], |v68|, s23
	s_nop 1
	v_cndmask_b32_e64 v68, v68, v70, s[14:15]
	v_cndmask_b32_e32 v70, 0, v211, vcc
	v_sub_f32_e32 v68, v68, v70
	v_sub_f32_e32 v68, v69, v68
	v_fmac_f32_e32 v67, 0x3d800000, v68
	v_mov_b32_e32 v98, v68
	s_waitcnt lgkmcnt(0)
	v_fma_f32 v72, v63, v100, v66
	v_fmac_f32_e32 v72, v64, v101
	v_fmac_f32_e32 v72, v60, v102
	v_fmac_f32_e32 v72, v65, v103
	v_fmac_f32_e32 v72, v61, v104
	v_fmac_f32_e32 v72, v62, v105
	v_pk_mul_f32 v[68:69], v[34:35], v[106:107]
	s_nop 0
	v_add_f32_e32 v68, v72, v68
	v_add_f32_e32 v72, v68, v69
	v_pk_mul_f32 v[68:69], v[36:37], v[108:109]
	s_nop 0
	v_add_f32_e32 v68, v72, v68
	v_add_f32_e32 v72, v68, v69
	v_pk_mul_f32 v[68:69], v[38:39], v[110:111]
	s_nop 0
	v_add_f32_e32 v68, v72, v68
	v_add_f32_e32 v72, v68, v69
	v_pk_mul_f32 v[68:69], v[40:41], v[112:113]
	s_nop 0
	v_add_f32_e32 v68, v72, v68
	v_add_f32_e32 v72, v68, v69
	v_pk_mul_f32 v[68:69], v[58:59], v[114:115]
	s_nop 0
	v_add_f32_e32 v68, v72, v68
	v_add_f32_e32 v68, v68, v69
	v_min_f32_e32 v69, 0, v68
	v_mul_f32_e64 v68, |v68|, s73
	v_exp_f32_e32 v68, v68
	s_nop 0
	v_add_f32_e32 v68, 1.0, v68
	v_cmp_gt_f32_e32 vcc, s94, v68
	s_nop 1
	v_cndmask_b32_e64 v70, 0, 32, vcc
	v_ldexp_f32 v68, v68, v70
	v_log_f32_e32 v68, v68
	s_nop 0
	v_mul_f32_e32 v70, 0x3f317217, v68
	v_fma_f32 v70, v68, s97, -v70
	v_fmac_f32_e32 v70, 0x3377d1cf, v68
	v_fmac_f32_e32 v70, 0x3f317217, v68
	v_cmp_lt_f32_e64 s[14:15], |v68|, s23
	s_nop 1
	v_cndmask_b32_e64 v68, v68, v70, s[14:15]
	v_cndmask_b32_e32 v70, 0, v211, vcc
	v_sub_f32_e32 v68, v68, v70
	v_sub_f32_e32 v68, v69, v68
	v_fmac_f32_e32 v67, 0x3d800000, v68
	v_mov_b32_e32 v99, v68
	v_add_u32_e32 v84, s0, v195
	ds_read_b128 v[68:71], v84
	ds_read_b128 v[72:75], v84 offset:16
	ds_read_b128 v[76:79], v84 offset:32
	ds_read_b128 v[80:83], v84 offset:48
	ds_read_b128 v[100:103], v84 offset:64
	ds_read_b128 v[104:107], v84 offset:80
	ds_read_b128 v[108:111], v84 offset:96
	ds_read_b128 v[112:115], v84 offset:112
	s_addk_i32 s0, 0x80
	s_waitcnt vmcnt(1) lgkmcnt(7)
; DEVI float logsigf_(float x) { return fminf(x, 0.f) - __logf(1.f + __expf(-fabsf(x))); }
; DEVI void lds_barrier() { asm volatile("s_waitcnt lgkmcnt(0)\n\ts_barrier" ::: "memory"); }
; DEVI float gla_la(const float* gl, int t, const float* w2r, float gb) { float x = gb;
; #pragma unroll
;     for (int r = 0; r < 16; ++r) x += gl[t * 16 + r] * w2r[r];
;     return logsigf_(x) * (1.f / 16.f); }
; template <int KIND>
; DEVI void mix_out_phase(unsigned char* smem, const MixArgs a) {
;     ...
;             for (int t = sg * 32; t < sg * 32 + 32; ++t) ssum += gla_la(gl, t, w2r, gb);
;             seg[sg * 128 + ch] = ssum; lds_barrier();
	v_fma_f32 v85, v63, v68, v66
	v_fmac_f32_e32 v85, v64, v69
	v_fmac_f32_e32 v85, v60, v70
	v_fmac_f32_e32 v85, v65, v71
	s_waitcnt lgkmcnt(6)
	v_fmac_f32_e32 v85, v61, v72
	v_fmac_f32_e32 v85, v62, v73
	v_pk_mul_f32 v[68:69], v[34:35], v[74:75]
	v_add_f32_e32 v68, v85, v68
	v_add_f32_e32 v70, v68, v69
	s_waitcnt lgkmcnt(5)
	v_pk_mul_f32 v[68:69], v[36:37], v[76:77]
	s_nop 0
	v_add_f32_e32 v68, v70, v68
	v_add_f32_e32 v70, v68, v69
	v_pk_mul_f32 v[68:69], v[38:39], v[78:79]
	s_nop 0
	v_add_f32_e32 v68, v70, v68
	v_add_f32_e32 v70, v68, v69
	s_waitcnt lgkmcnt(4)
	v_pk_mul_f32 v[68:69], v[40:41], v[80:81]
	s_nop 0
	v_add_f32_e32 v68, v70, v68
	v_add_f32_e32 v70, v68, v69
	s_waitcnt vmcnt(0)
	v_pk_mul_f32 v[68:69], v[58:59], v[82:83]
	s_nop 0
	v_add_f32_e32 v68, v70, v68
	v_add_f32_e32 v68, v68, v69
	v_min_f32_e32 v69, 0, v68
	v_mul_f32_e64 v68, |v68|, s73
	v_exp_f32_e32 v68, v68
	s_nop 0
	v_add_f32_e32 v68, 1.0, v68
	v_cmp_gt_f32_e32 vcc, s94, v68
	s_nop 1
	v_cndmask_b32_e64 v70, 0, 32, vcc
	v_ldexp_f32 v68, v68, v70
	v_log_f32_e32 v68, v68
	s_nop 0
	v_mul_f32_e32 v70, 0x3f317217, v68
	v_fma_f32 v70, v68, s97, -v70
	v_fmac_f32_e32 v70, 0x3377d1cf, v68
	v_fmac_f32_e32 v70, 0x3f317217, v68
	v_cmp_lt_f32_e64 s[14:15], |v68|, s23
	s_nop 1
	v_cndmask_b32_e64 v68, v68, v70, s[14:15]
	v_cndmask_b32_e32 v70, 0, v211, vcc
	v_sub_f32_e32 v68, v68, v70
	v_sub_f32_e32 v68, v69, v68
	v_fmac_f32_e32 v67, 0x3d800000, v68
	v_mov_b32_e32 v116, v68
	s_waitcnt lgkmcnt(0)
	v_fma_f32 v72, v63, v100, v66
	v_fmac_f32_e32 v72, v64, v101
	v_fmac_f32_e32 v72, v60, v102
	v_fmac_f32_e32 v72, v65, v103
	v_fmac_f32_e32 v72, v61, v104
	v_fmac_f32_e32 v72, v62, v105
	v_pk_mul_f32 v[68:69], v[34:35], v[106:107]
	s_nop 0
	v_add_f32_e32 v68, v72, v68
	v_add_f32_e32 v72, v68, v69
	v_pk_mul_f32 v[68:69], v[36:37], v[108:109]
	s_nop 0
	v_add_f32_e32 v68, v72, v68
	v_add_f32_e32 v72, v68, v69
	v_pk_mul_f32 v[68:69], v[38:39], v[110:111]
	s_nop 0
	v_add_f32_e32 v68, v72, v68
	v_add_f32_e32 v72, v68, v69
	v_pk_mul_f32 v[68:69], v[40:41], v[112:113]
	s_nop 0
	v_add_f32_e32 v68, v72, v68
	v_add_f32_e32 v72, v68, v69
	v_pk_mul_f32 v[68:69], v[58:59], v[114:115]
	s_nop 0
	v_add_f32_e32 v68, v72, v68
	v_add_f32_e32 v68, v68, v69
	v_min_f32_e32 v69, 0, v68
	v_mul_f32_e64 v68, |v68|, s73
	v_exp_f32_e32 v68, v68
	s_nop 0
	v_add_f32_e32 v68, 1.0, v68
	v_cmp_gt_f32_e32 vcc, s94, v68
	s_nop 1
	v_cndmask_b32_e64 v70, 0, 32, vcc
	v_ldexp_f32 v68, v68, v70
	v_log_f32_e32 v68, v68
	s_nop 0
	v_mul_f32_e32 v70, 0x3f317217, v68
	v_fma_f32 v70, v68, s97, -v70
	v_fmac_f32_e32 v70, 0x3377d1cf, v68
	v_fmac_f32_e32 v70, 0x3f317217, v68
	v_cmp_lt_f32_e64 s[14:15], |v68|, s23
	s_nop 1
	v_cndmask_b32_e64 v68, v68, v70, s[14:15]
	v_cndmask_b32_e32 v70, 0, v211, vcc
	v_sub_f32_e32 v68, v68, v70
	v_sub_f32_e32 v68, v69, v68
	v_fmac_f32_e32 v67, 0x3d800000, v68
	v_mov_b32_e32 v117, v68
	v_add_u32_e32 v84, s0, v195
	ds_read_b128 v[68:71], v84
	ds_read_b128 v[72:75], v84 offset:16
	ds_read_b128 v[76:79], v84 offset:32
	ds_read_b128 v[80:83], v84 offset:48
	ds_read_b128 v[100:103], v84 offset:64
	ds_read_b128 v[104:107], v84 offset:80
	ds_read_b128 v[108:111], v84 offset:96
	ds_read_b128 v[112:115], v84 offset:112
	s_addk_i32 s0, 0x80
	s_waitcnt vmcnt(1) lgkmcnt(7)
	v_fma_f32 v85, v63, v68, v66
	v_fmac_f32_e32 v85, v64, v69
	v_fmac_f32_e32 v85, v60, v70
	v_fmac_f32_e32 v85, v65, v71
	s_waitcnt lgkmcnt(6)
	v_fmac_f32_e32 v85, v61, v72
	v_fmac_f32_e32 v85, v62, v73
	v_pk_mul_f32 v[68:69], v[34:35], v[74:75]
	v_add_f32_e32 v68, v85, v68
	v_add_f32_e32 v70, v68, v69
	s_waitcnt lgkmcnt(5)
	v_pk_mul_f32 v[68:69], v[36:37], v[76:77]
	s_nop 0
	v_add_f32_e32 v68, v70, v68
	v_add_f32_e32 v70, v68, v69
	v_pk_mul_f32 v[68:69], v[38:39], v[78:79]
	s_nop 0
	v_add_f32_e32 v68, v70, v68
	v_add_f32_e32 v70, v68, v69
	s_waitcnt lgkmcnt(4)
	v_pk_mul_f32 v[68:69], v[40:41], v[80:81]
	s_nop 0
	v_add_f32_e32 v68, v70, v68
	v_add_f32_e32 v70, v68, v69
	s_waitcnt vmcnt(0)
	v_pk_mul_f32 v[68:69], v[58:59], v[82:83]
	s_nop 0
	v_add_f32_e32 v68, v70, v68
	v_add_f32_e32 v68, v68, v69
	v_min_f32_e32 v69, 0, v68
	v_mul_f32_e64 v68, |v68|, s73
	v_exp_f32_e32 v68, v68
	s_nop 0
	v_add_f32_e32 v68, 1.0, v68
	v_cmp_gt_f32_e32 vcc, s94, v68
	s_nop 1
	v_cndmask_b32_e64 v70, 0, 32, vcc
	v_ldexp_f32 v68, v68, v70
	v_log_f32_e32 v68, v68
	s_nop 0
	v_mul_f32_e32 v70, 0x3f317217, v68
	v_fma_f32 v70, v68, s97, -v70
	v_fmac_f32_e32 v70, 0x3377d1cf, v68
	v_fmac_f32_e32 v70, 0x3f317217, v68
	v_cmp_lt_f32_e64 s[14:15], |v68|, s23
	s_nop 1
	v_cndmask_b32_e64 v68, v68, v70, s[14:15]
	v_cndmask_b32_e32 v70, 0, v211, vcc
	v_sub_f32_e32 v68, v68, v70
	v_sub_f32_e32 v68, v69, v68
	v_fmac_f32_e32 v67, 0x3d800000, v68
	v_mov_b32_e32 v118, v68
	s_waitcnt lgkmcnt(0)
	v_fma_f32 v72, v63, v100, v66
	v_fmac_f32_e32 v72, v64, v101
	v_fmac_f32_e32 v72, v60, v102
	v_fmac_f32_e32 v72, v65, v103
	v_fmac_f32_e32 v72, v61, v104
	v_fmac_f32_e32 v72, v62, v105
	v_pk_mul_f32 v[68:69], v[34:35], v[106:107]
	s_nop 0
	v_add_f32_e32 v68, v72, v68
	v_add_f32_e32 v72, v68, v69
	v_pk_mul_f32 v[68:69], v[36:37], v[108:109]
	s_nop 0
	v_add_f32_e32 v68, v72, v68
	v_add_f32_e32 v72, v68, v69
	v_pk_mul_f32 v[68:69], v[38:39], v[110:111]
	s_nop 0
	v_add_f32_e32 v68, v72, v68
	v_add_f32_e32 v72, v68, v69
	v_pk_mul_f32 v[68:69], v[40:41], v[112:113]
	s_nop 0
	v_add_f32_e32 v68, v72, v68
	v_add_f32_e32 v72, v68, v69
	v_pk_mul_f32 v[68:69], v[58:59], v[114:115]
	s_nop 0
	v_add_f32_e32 v68, v72, v68
	v_add_f32_e32 v68, v68, v69
	v_min_f32_e32 v69, 0, v68
	v_mul_f32_e64 v68, |v68|, s73
	v_exp_f32_e32 v68, v68
	s_nop 0
	v_add_f32_e32 v68, 1.0, v68
	v_cmp_gt_f32_e32 vcc, s94, v68
	s_nop 1
	v_cndmask_b32_e64 v70, 0, 32, vcc
	v_ldexp_f32 v68, v68, v70
	v_log_f32_e32 v68, v68
	s_nop 0
	v_mul_f32_e32 v70, 0x3f317217, v68
	v_fma_f32 v70, v68, s97, -v70
	v_fmac_f32_e32 v70, 0x3377d1cf, v68
	v_fmac_f32_e32 v70, 0x3f317217, v68
	v_cmp_lt_f32_e64 s[14:15], |v68|, s23
	s_nop 1
	v_cndmask_b32_e64 v68, v68, v70, s[14:15]
	v_cndmask_b32_e32 v70, 0, v211, vcc
	v_sub_f32_e32 v68, v68, v70
	v_sub_f32_e32 v68, v69, v68
	v_fmac_f32_e32 v67, 0x3d800000, v68
	v_mov_b32_e32 v119, v68
	v_add_u32_e32 v84, s0, v195
	ds_read_b128 v[68:71], v84
	ds_read_b128 v[72:75], v84 offset:16
	ds_read_b128 v[76:79], v84 offset:32
	ds_read_b128 v[80:83], v84 offset:48
	ds_read_b128 v[100:103], v84 offset:64
	ds_read_b128 v[104:107], v84 offset:80
	ds_read_b128 v[108:111], v84 offset:96
	ds_read_b128 v[112:115], v84 offset:112
	s_addk_i32 s0, 0x80
	s_waitcnt vmcnt(1) lgkmcnt(7)
; DEVI float logsigf_(float x) { return fminf(x, 0.f) - __logf(1.f + __expf(-fabsf(x))); }
; DEVI void lds_barrier() { asm volatile("s_waitcnt lgkmcnt(0)\n\ts_barrier" ::: "memory"); }
; DEVI float gla_la(const float* gl, int t, const float* w2r, float gb) { float x = gb;
; #pragma unroll
;     for (int r = 0; r < 16; ++r) x += gl[t * 16 + r] * w2r[r];
;     return logsigf_(x) * (1.f / 16.f); }
; template <int KIND>
; DEVI void mix_out_phase(unsigned char* smem, const MixArgs a) {
;     ...
;             for (int t = sg * 32; t < sg * 32 + 32; ++t) ssum += gla_la(gl, t, w2r, gb);
;             seg[sg * 128 + ch] = ssum; lds_barrier();
	v_fma_f32 v85, v63, v68, v66
	v_fmac_f32_e32 v85, v64, v69
	v_fmac_f32_e32 v85, v60, v70
	v_fmac_f32_e32 v85, v65, v71
	s_waitcnt lgkmcnt(6)
	v_fmac_f32_e32 v85, v61, v72
	v_fmac_f32_e32 v85, v62, v73
	v_pk_mul_f32 v[68:69], v[34:35], v[74:75]
	v_add_f32_e32 v68, v85, v68
	v_add_f32_e32 v70, v68, v69
	s_waitcnt lgkmcnt(5)
	v_pk_mul_f32 v[68:69], v[36:37], v[76:77]
	s_nop 0
	v_add_f32_e32 v68, v70, v68
	v_add_f32_e32 v70, v68, v69
	v_pk_mul_f32 v[68:69], v[38:39], v[78:79]
	s_nop 0
	v_add_f32_e32 v68, v70, v68
	v_add_f32_e32 v70, v68, v69
	s_waitcnt lgkmcnt(4)
	v_pk_mul_f32 v[68:69], v[40:41], v[80:81]
	s_nop 0
	v_add_f32_e32 v68, v70, v68
	v_add_f32_e32 v70, v68, v69
	s_waitcnt vmcnt(0)
	v_pk_mul_f32 v[68:69], v[58:59], v[82:83]
	s_nop 0
	v_add_f32_e32 v68, v70, v68
	v_add_f32_e32 v68, v68, v69
	v_min_f32_e32 v69, 0, v68
	v_mul_f32_e64 v68, |v68|, s73
	v_exp_f32_e32 v68, v68
	s_nop 0
	v_add_f32_e32 v68, 1.0, v68
	v_cmp_gt_f32_e32 vcc, s94, v68
	s_nop 1
	v_cndmask_b32_e64 v70, 0, 32, vcc
	v_ldexp_f32 v68, v68, v70
	v_log_f32_e32 v68, v68
	s_nop 0
	v_mul_f32_e32 v70, 0x3f317217, v68
	v_fma_f32 v70, v68, s97, -v70
	v_fmac_f32_e32 v70, 0x3377d1cf, v68
	v_fmac_f32_e32 v70, 0x3f317217, v68
	v_cmp_lt_f32_e64 s[14:15], |v68|, s23
	s_nop 1
	v_cndmask_b32_e64 v68, v68, v70, s[14:15]
	v_cndmask_b32_e32 v70, 0, v211, vcc
	v_sub_f32_e32 v68, v68, v70
	v_sub_f32_e32 v68, v69, v68
	v_fmac_f32_e32 v67, 0x3d800000, v68
	v_mov_b32_e32 v120, v68
	s_waitcnt lgkmcnt(0)
	v_fma_f32 v72, v63, v100, v66
	v_fmac_f32_e32 v72, v64, v101
	v_fmac_f32_e32 v72, v60, v102
	v_fmac_f32_e32 v72, v65, v103
	v_fmac_f32_e32 v72, v61, v104
	v_fmac_f32_e32 v72, v62, v105
	v_pk_mul_f32 v[68:69], v[34:35], v[106:107]
	s_nop 0
	v_add_f32_e32 v68, v72, v68
	v_add_f32_e32 v72, v68, v69
	v_pk_mul_f32 v[68:69], v[36:37], v[108:109]
	s_nop 0
	v_add_f32_e32 v68, v72, v68
	v_add_f32_e32 v72, v68, v69
	v_pk_mul_f32 v[68:69], v[38:39], v[110:111]
	s_nop 0
	v_add_f32_e32 v68, v72, v68
	v_add_f32_e32 v72, v68, v69
	v_pk_mul_f32 v[68:69], v[40:41], v[112:113]
	s_nop 0
	v_add_f32_e32 v68, v72, v68
	v_add_f32_e32 v72, v68, v69
	v_pk_mul_f32 v[68:69], v[58:59], v[114:115]
	s_nop 0
	v_add_f32_e32 v68, v72, v68
	v_add_f32_e32 v68, v68, v69
	v_min_f32_e32 v69, 0, v68
	v_mul_f32_e64 v68, |v68|, s73
	v_exp_f32_e32 v68, v68
	s_nop 0
	v_add_f32_e32 v68, 1.0, v68
	v_cmp_gt_f32_e32 vcc, s94, v68
	s_nop 1
	v_cndmask_b32_e64 v70, 0, 32, vcc
	v_ldexp_f32 v68, v68, v70
	v_log_f32_e32 v68, v68
	s_nop 0
	v_mul_f32_e32 v70, 0x3f317217, v68
	v_fma_f32 v70, v68, s97, -v70
	v_fmac_f32_e32 v70, 0x3377d1cf, v68
	v_fmac_f32_e32 v70, 0x3f317217, v68
	v_cmp_lt_f32_e64 s[14:15], |v68|, s23
	s_nop 1
	v_cndmask_b32_e64 v68, v68, v70, s[14:15]
	v_cndmask_b32_e32 v70, 0, v211, vcc
	v_sub_f32_e32 v68, v68, v70
	v_sub_f32_e32 v68, v69, v68
	v_fmac_f32_e32 v67, 0x3d800000, v68
	v_mov_b32_e32 v121, v68
	v_add_u32_e32 v84, s0, v195
	ds_read_b128 v[68:71], v84
	ds_read_b128 v[72:75], v84 offset:16
	ds_read_b128 v[76:79], v84 offset:32
	ds_read_b128 v[80:83], v84 offset:48
	ds_read_b128 v[100:103], v84 offset:64
	ds_read_b128 v[104:107], v84 offset:80
	ds_read_b128 v[108:111], v84 offset:96
	ds_read_b128 v[112:115], v84 offset:112
	s_addk_i32 s0, 0x80
	s_waitcnt vmcnt(1) lgkmcnt(7)
	v_fma_f32 v85, v63, v68, v66
	v_fmac_f32_e32 v85, v64, v69
	v_fmac_f32_e32 v85, v60, v70
	v_fmac_f32_e32 v85, v65, v71
	s_waitcnt lgkmcnt(6)
	v_fmac_f32_e32 v85, v61, v72
	v_fmac_f32_e32 v85, v62, v73
	v_pk_mul_f32 v[68:69], v[34:35], v[74:75]
	v_add_f32_e32 v68, v85, v68
	v_add_f32_e32 v70, v68, v69
	s_waitcnt lgkmcnt(5)
	v_pk_mul_f32 v[68:69], v[36:37], v[76:77]
	s_nop 0
	v_add_f32_e32 v68, v70, v68
	v_add_f32_e32 v70, v68, v69
	v_pk_mul_f32 v[68:69], v[38:39], v[78:79]
	s_nop 0
	v_add_f32_e32 v68, v70, v68
	v_add_f32_e32 v70, v68, v69
	s_waitcnt lgkmcnt(4)
	v_pk_mul_f32 v[68:69], v[40:41], v[80:81]
	s_nop 0
	v_add_f32_e32 v68, v70, v68
	v_add_f32_e32 v70, v68, v69
	s_waitcnt vmcnt(0)
	v_pk_mul_f32 v[68:69], v[58:59], v[82:83]
	s_nop 0
	v_add_f32_e32 v68, v70, v68
	v_add_f32_e32 v68, v68, v69
	v_min_f32_e32 v69, 0, v68
	v_mul_f32_e64 v68, |v68|, s73
	v_exp_f32_e32 v68, v68
	s_nop 0
	v_add_f32_e32 v68, 1.0, v68
	v_cmp_gt_f32_e32 vcc, s94, v68
	s_nop 1
	v_cndmask_b32_e64 v70, 0, 32, vcc
	v_ldexp_f32 v68, v68, v70
	v_log_f32_e32 v68, v68
	s_nop 0
	v_mul_f32_e32 v70, 0x3f317217, v68
	v_fma_f32 v70, v68, s97, -v70
	v_fmac_f32_e32 v70, 0x3377d1cf, v68
	v_fmac_f32_e32 v70, 0x3f317217, v68
	v_cmp_lt_f32_e64 s[14:15], |v68|, s23
	s_nop 1
	v_cndmask_b32_e64 v68, v68, v70, s[14:15]
	v_cndmask_b32_e32 v70, 0, v211, vcc
	v_sub_f32_e32 v68, v68, v70
	v_sub_f32_e32 v68, v69, v68
	v_fmac_f32_e32 v67, 0x3d800000, v68
	v_mov_b32_e32 v122, v68
	s_waitcnt lgkmcnt(0)
	v_fma_f32 v72, v63, v100, v66
	v_fmac_f32_e32 v72, v64, v101
	v_fmac_f32_e32 v72, v60, v102
	v_fmac_f32_e32 v72, v65, v103
	v_fmac_f32_e32 v72, v61, v104
	v_fmac_f32_e32 v72, v62, v105
	v_pk_mul_f32 v[68:69], v[34:35], v[106:107]
	s_nop 0
	v_add_f32_e32 v68, v72, v68
	v_add_f32_e32 v72, v68, v69
	v_pk_mul_f32 v[68:69], v[36:37], v[108:109]
	s_nop 0
	v_add_f32_e32 v68, v72, v68
	v_add_f32_e32 v72, v68, v69
	v_pk_mul_f32 v[68:69], v[38:39], v[110:111]
	s_nop 0
	v_add_f32_e32 v68, v72, v68
	v_add_f32_e32 v72, v68, v69
	v_pk_mul_f32 v[68:69], v[40:41], v[112:113]
	s_nop 0
	v_add_f32_e32 v68, v72, v68
	v_add_f32_e32 v72, v68, v69
	v_pk_mul_f32 v[68:69], v[58:59], v[114:115]
	s_nop 0
	v_add_f32_e32 v68, v72, v68
	v_add_f32_e32 v68, v68, v69
	v_min_f32_e32 v69, 0, v68
	v_mul_f32_e64 v68, |v68|, s73
	v_exp_f32_e32 v68, v68
	s_nop 0
	v_add_f32_e32 v68, 1.0, v68
	v_cmp_gt_f32_e32 vcc, s94, v68
	s_nop 1
	v_cndmask_b32_e64 v70, 0, 32, vcc
	v_ldexp_f32 v68, v68, v70
	v_log_f32_e32 v68, v68
	s_nop 0
	v_mul_f32_e32 v70, 0x3f317217, v68
	v_fma_f32 v70, v68, s97, -v70
	v_fmac_f32_e32 v70, 0x3377d1cf, v68
	v_fmac_f32_e32 v70, 0x3f317217, v68
	v_cmp_lt_f32_e64 s[14:15], |v68|, s23
	s_nop 1
	v_cndmask_b32_e64 v68, v68, v70, s[14:15]
	v_cndmask_b32_e32 v70, 0, v211, vcc
	v_sub_f32_e32 v68, v68, v70
	v_sub_f32_e32 v68, v69, v68
	v_fmac_f32_e32 v67, 0x3d800000, v68
	v_mov_b32_e32 v123, v68
	v_add_u32_e32 v84, s0, v195
	ds_read_b128 v[68:71], v84
	ds_read_b128 v[72:75], v84 offset:16
	ds_read_b128 v[76:79], v84 offset:32
	ds_read_b128 v[80:83], v84 offset:48
	ds_read_b128 v[100:103], v84 offset:64
	ds_read_b128 v[104:107], v84 offset:80
	ds_read_b128 v[108:111], v84 offset:96
	ds_read_b128 v[112:115], v84 offset:112
	s_addk_i32 s0, 0x80
	s_waitcnt vmcnt(1) lgkmcnt(7)
; DEVI float logsigf_(float x) { return fminf(x, 0.f) - __logf(1.f + __expf(-fabsf(x))); }
; DEVI void lds_barrier() { asm volatile("s_waitcnt lgkmcnt(0)\n\ts_barrier" ::: "memory"); }
; DEVI float gla_la(const float* gl, int t, const float* w2r, float gb) { float x = gb;
; #pragma unroll
;     for (int r = 0; r < 16; ++r) x += gl[t * 16 + r] * w2r[r];
;     return logsigf_(x) * (1.f / 16.f); }
; template <int KIND>
; DEVI void mix_out_phase(unsigned char* smem, const MixArgs a) {
;     ...
;             for (int t = sg * 32; t < sg * 32 + 32; ++t) ssum += gla_la(gl, t, w2r, gb);
;             seg[sg * 128 + ch] = ssum; lds_barrier();
	v_fma_f32 v85, v63, v68, v66
	v_fmac_f32_e32 v85, v64, v69
	v_fmac_f32_e32 v85, v60, v70
	v_fmac_f32_e32 v85, v65, v71
	s_waitcnt lgkmcnt(6)
	v_fmac_f32_e32 v85, v61, v72
	v_fmac_f32_e32 v85, v62, v73
	v_pk_mul_f32 v[68:69], v[34:35], v[74:75]
	v_add_f32_e32 v68, v85, v68
	v_add_f32_e32 v70, v68, v69
	s_waitcnt lgkmcnt(5)
	v_pk_mul_f32 v[68:69], v[36:37], v[76:77]
	s_nop 0
	v_add_f32_e32 v68, v70, v68
	v_add_f32_e32 v70, v68, v69
	v_pk_mul_f32 v[68:69], v[38:39], v[78:79]
	s_nop 0
	v_add_f32_e32 v68, v70, v68
	v_add_f32_e32 v70, v68, v69
	s_waitcnt lgkmcnt(4)
	v_pk_mul_f32 v[68:69], v[40:41], v[80:81]
	s_nop 0
	v_add_f32_e32 v68, v70, v68
	v_add_f32_e32 v70, v68, v69
	s_waitcnt vmcnt(0)
	v_pk_mul_f32 v[68:69], v[58:59], v[82:83]
	s_nop 0
	v_add_f32_e32 v68, v70, v68
	v_add_f32_e32 v68, v68, v69
	v_min_f32_e32 v69, 0, v68
	v_mul_f32_e64 v68, |v68|, s73
	v_exp_f32_e32 v68, v68
	s_nop 0
	v_add_f32_e32 v68, 1.0, v68
	v_cmp_gt_f32_e32 vcc, s94, v68
	s_nop 1
	v_cndmask_b32_e64 v70, 0, 32, vcc
	v_ldexp_f32 v68, v68, v70
	v_log_f32_e32 v68, v68
	s_nop 0
	v_mul_f32_e32 v70, 0x3f317217, v68
	v_fma_f32 v70, v68, s97, -v70
	v_fmac_f32_e32 v70, 0x3377d1cf, v68
	v_fmac_f32_e32 v70, 0x3f317217, v68
	v_cmp_lt_f32_e64 s[14:15], |v68|, s23
	s_nop 1
	v_cndmask_b32_e64 v68, v68, v70, s[14:15]
	v_cndmask_b32_e32 v70, 0, v211, vcc
	v_sub_f32_e32 v68, v68, v70
	v_sub_f32_e32 v68, v69, v68
	v_fmac_f32_e32 v67, 0x3d800000, v68
	v_mov_b32_e32 v124, v68
	s_waitcnt lgkmcnt(0)
	v_fma_f32 v72, v63, v100, v66
	v_fmac_f32_e32 v72, v64, v101
	v_fmac_f32_e32 v72, v60, v102
	v_fmac_f32_e32 v72, v65, v103
	v_fmac_f32_e32 v72, v61, v104
	v_fmac_f32_e32 v72, v62, v105
	v_pk_mul_f32 v[68:69], v[34:35], v[106:107]
	s_nop 0
	v_add_f32_e32 v68, v72, v68
	v_add_f32_e32 v72, v68, v69
	v_pk_mul_f32 v[68:69], v[36:37], v[108:109]
	s_nop 0
	v_add_f32_e32 v68, v72, v68
	v_add_f32_e32 v72, v68, v69
	v_pk_mul_f32 v[68:69], v[38:39], v[110:111]
	s_nop 0
	v_add_f32_e32 v68, v72, v68
	v_add_f32_e32 v72, v68, v69
	v_pk_mul_f32 v[68:69], v[40:41], v[112:113]
	s_nop 0
	v_add_f32_e32 v68, v72, v68
	v_add_f32_e32 v72, v68, v69
	v_pk_mul_f32 v[68:69], v[58:59], v[114:115]
	s_nop 0
	v_add_f32_e32 v68, v72, v68
	v_add_f32_e32 v68, v68, v69
	v_min_f32_e32 v69, 0, v68
	v_mul_f32_e64 v68, |v68|, s73
	v_exp_f32_e32 v68, v68
	s_nop 0
	v_add_f32_e32 v68, 1.0, v68
	v_cmp_gt_f32_e32 vcc, s94, v68
	s_nop 1
	v_cndmask_b32_e64 v70, 0, 32, vcc
	v_ldexp_f32 v68, v68, v70
	v_log_f32_e32 v68, v68
	s_nop 0
	v_mul_f32_e32 v70, 0x3f317217, v68
	v_fma_f32 v70, v68, s97, -v70
	v_fmac_f32_e32 v70, 0x3377d1cf, v68
	v_fmac_f32_e32 v70, 0x3f317217, v68
	v_cmp_lt_f32_e64 s[14:15], |v68|, s23
	s_nop 1
	v_cndmask_b32_e64 v68, v68, v70, s[14:15]
	v_cndmask_b32_e32 v70, 0, v211, vcc
	v_sub_f32_e32 v68, v68, v70
	v_sub_f32_e32 v68, v69, v68
	v_fmac_f32_e32 v67, 0x3d800000, v68
	v_mov_b32_e32 v125, v68
	v_add_u32_e32 v84, s0, v195
	ds_read_b128 v[68:71], v84
	ds_read_b128 v[72:75], v84 offset:16
	ds_read_b128 v[76:79], v84 offset:32
	ds_read_b128 v[80:83], v84 offset:48
	ds_read_b128 v[100:103], v84 offset:64
	ds_read_b128 v[104:107], v84 offset:80
	ds_read_b128 v[108:111], v84 offset:96
	ds_read_b128 v[112:115], v84 offset:112
	s_addk_i32 s0, 0x80
	s_waitcnt vmcnt(1) lgkmcnt(7)
	v_fma_f32 v85, v63, v68, v66
	v_fmac_f32_e32 v85, v64, v69
	v_fmac_f32_e32 v85, v60, v70
	v_fmac_f32_e32 v85, v65, v71
	s_waitcnt lgkmcnt(6)
	v_fmac_f32_e32 v85, v61, v72
	v_fmac_f32_e32 v85, v62, v73
	v_pk_mul_f32 v[68:69], v[34:35], v[74:75]
	v_add_f32_e32 v68, v85, v68
	v_add_f32_e32 v70, v68, v69
	s_waitcnt lgkmcnt(5)
	v_pk_mul_f32 v[68:69], v[36:37], v[76:77]
	s_nop 0
	v_add_f32_e32 v68, v70, v68
	v_add_f32_e32 v70, v68, v69
	v_pk_mul_f32 v[68:69], v[38:39], v[78:79]
	s_nop 0
	v_add_f32_e32 v68, v70, v68
	v_add_f32_e32 v70, v68, v69
	s_waitcnt lgkmcnt(4)
	v_pk_mul_f32 v[68:69], v[40:41], v[80:81]
	s_nop 0
	v_add_f32_e32 v68, v70, v68
	v_add_f32_e32 v70, v68, v69
	s_waitcnt vmcnt(0)
	v_pk_mul_f32 v[68:69], v[58:59], v[82:83]
	s_nop 0
	v_add_f32_e32 v68, v70, v68
	v_add_f32_e32 v68, v68, v69
	v_min_f32_e32 v69, 0, v68
	v_mul_f32_e64 v68, |v68|, s73
	v_exp_f32_e32 v68, v68
	s_nop 0
	v_add_f32_e32 v68, 1.0, v68
	v_cmp_gt_f32_e32 vcc, s94, v68
	s_nop 1
	v_cndmask_b32_e64 v70, 0, 32, vcc
	v_ldexp_f32 v68, v68, v70
	v_log_f32_e32 v68, v68
	s_nop 0
	v_mul_f32_e32 v70, 0x3f317217, v68
	v_fma_f32 v70, v68, s97, -v70
	v_fmac_f32_e32 v70, 0x3377d1cf, v68
	v_fmac_f32_e32 v70, 0x3f317217, v68
	v_cmp_lt_f32_e64 s[14:15], |v68|, s23
	s_nop 1
	v_cndmask_b32_e64 v68, v68, v70, s[14:15]
	v_cndmask_b32_e32 v70, 0, v211, vcc
	v_sub_f32_e32 v68, v68, v70
	v_sub_f32_e32 v68, v69, v68
	v_fmac_f32_e32 v67, 0x3d800000, v68
	v_mov_b32_e32 v126, v68
	s_waitcnt lgkmcnt(0)
	v_fma_f32 v72, v63, v100, v66
	v_fmac_f32_e32 v72, v64, v101
	v_fmac_f32_e32 v72, v60, v102
	v_fmac_f32_e32 v72, v65, v103
	v_fmac_f32_e32 v72, v61, v104
	v_fmac_f32_e32 v72, v62, v105
	v_pk_mul_f32 v[68:69], v[34:35], v[106:107]
	s_nop 0
	v_add_f32_e32 v68, v72, v68
	v_add_f32_e32 v72, v68, v69
	v_pk_mul_f32 v[68:69], v[36:37], v[108:109]
	s_nop 0
	v_add_f32_e32 v68, v72, v68
	v_add_f32_e32 v72, v68, v69
	v_pk_mul_f32 v[68:69], v[38:39], v[110:111]
	s_nop 0
	v_add_f32_e32 v68, v72, v68
	v_add_f32_e32 v72, v68, v69
	v_pk_mul_f32 v[68:69], v[40:41], v[112:113]
	s_nop 0
	v_add_f32_e32 v68, v72, v68
	v_add_f32_e32 v72, v68, v69
	v_pk_mul_f32 v[68:69], v[58:59], v[114:115]
	s_nop 0
	v_add_f32_e32 v68, v72, v68
	v_add_f32_e32 v68, v68, v69
	v_min_f32_e32 v69, 0, v68
	v_mul_f32_e64 v68, |v68|, s73
	v_exp_f32_e32 v68, v68
	s_nop 0
	v_add_f32_e32 v68, 1.0, v68
	v_cmp_gt_f32_e32 vcc, s94, v68
	s_nop 1
	v_cndmask_b32_e64 v70, 0, 32, vcc
	v_ldexp_f32 v68, v68, v70
	v_log_f32_e32 v68, v68
	s_nop 0
	v_mul_f32_e32 v70, 0x3f317217, v68
	v_fma_f32 v70, v68, s97, -v70
	v_fmac_f32_e32 v70, 0x3377d1cf, v68
	v_fmac_f32_e32 v70, 0x3f317217, v68
	v_cmp_lt_f32_e64 s[14:15], |v68|, s23
	s_nop 1
	v_cndmask_b32_e64 v68, v68, v70, s[14:15]
	v_cndmask_b32_e32 v70, 0, v211, vcc
	v_sub_f32_e32 v68, v68, v70
	v_sub_f32_e32 v68, v69, v68
	v_fmac_f32_e32 v67, 0x3d800000, v68
	v_mov_b32_e32 v127, v68
	v_add_u32_e32 v84, s0, v195
	ds_read_b128 v[68:71], v84
	ds_read_b128 v[72:75], v84 offset:16
	ds_read_b128 v[76:79], v84 offset:32
	ds_read_b128 v[80:83], v84 offset:48
	ds_read_b128 v[100:103], v84 offset:64
	ds_read_b128 v[104:107], v84 offset:80
	ds_read_b128 v[108:111], v84 offset:96
	ds_read_b128 v[112:115], v84 offset:112
	s_addk_i32 s0, 0x80
	s_waitcnt vmcnt(1) lgkmcnt(7)
; DEVI float logsigf_(float x) { return fminf(x, 0.f) - __logf(1.f + __expf(-fabsf(x))); }
; DEVI void lds_barrier() { asm volatile("s_waitcnt lgkmcnt(0)\n\ts_barrier" ::: "memory"); }
; DEVI float gla_la(const float* gl, int t, const float* w2r, float gb) { float x = gb;
; #pragma unroll
;     for (int r = 0; r < 16; ++r) x += gl[t * 16 + r] * w2r[r];
;     return logsigf_(x) * (1.f / 16.f); }
; template <int KIND>
; DEVI void mix_out_phase(unsigned char* smem, const MixArgs a) {
;     ...
;             for (int t = sg * 32; t < sg * 32 + 32; ++t) ssum += gla_la(gl, t, w2r, gb);
;             seg[sg * 128 + ch] = ssum; lds_barrier();
	v_fma_f32 v85, v63, v68, v66
	v_fmac_f32_e32 v85, v64, v69
	v_fmac_f32_e32 v85, v60, v70
	v_fmac_f32_e32 v85, v65, v71
	s_waitcnt lgkmcnt(6)
	v_fmac_f32_e32 v85, v61, v72
	v_fmac_f32_e32 v85, v62, v73
	v_pk_mul_f32 v[68:69], v[34:35], v[74:75]
	v_add_f32_e32 v68, v85, v68
	v_add_f32_e32 v70, v68, v69
	s_waitcnt lgkmcnt(5)
	v_pk_mul_f32 v[68:69], v[36:37], v[76:77]
	s_nop 0
	v_add_f32_e32 v68, v70, v68
	v_add_f32_e32 v70, v68, v69
	v_pk_mul_f32 v[68:69], v[38:39], v[78:79]
	s_nop 0
	v_add_f32_e32 v68, v70, v68
	v_add_f32_e32 v70, v68, v69
	s_waitcnt lgkmcnt(4)
	v_pk_mul_f32 v[68:69], v[40:41], v[80:81]
	s_nop 0
	v_add_f32_e32 v68, v70, v68
	v_add_f32_e32 v70, v68, v69
	s_waitcnt vmcnt(0)
	v_pk_mul_f32 v[68:69], v[58:59], v[82:83]
	s_nop 0
	v_add_f32_e32 v68, v70, v68
	v_add_f32_e32 v68, v68, v69
	v_min_f32_e32 v69, 0, v68
	v_mul_f32_e64 v68, |v68|, s73
	v_exp_f32_e32 v68, v68
	s_nop 0
	v_add_f32_e32 v68, 1.0, v68
	v_cmp_gt_f32_e32 vcc, s94, v68
	s_nop 1
	v_cndmask_b32_e64 v70, 0, 32, vcc
	v_ldexp_f32 v68, v68, v70
	v_log_f32_e32 v68, v68
	s_nop 0
	v_mul_f32_e32 v70, 0x3f317217, v68
	v_fma_f32 v70, v68, s97, -v70
	v_fmac_f32_e32 v70, 0x3377d1cf, v68
	v_fmac_f32_e32 v70, 0x3f317217, v68
	v_cmp_lt_f32_e64 s[14:15], |v68|, s23
	s_nop 1
	v_cndmask_b32_e64 v68, v68, v70, s[14:15]
	v_cndmask_b32_e32 v70, 0, v211, vcc
	v_sub_f32_e32 v68, v68, v70
	v_sub_f32_e32 v68, v69, v68
	v_fmac_f32_e32 v67, 0x3d800000, v68
	v_mov_b32_e32 v128, v68
	s_waitcnt lgkmcnt(0)
	v_fma_f32 v72, v63, v100, v66
	v_fmac_f32_e32 v72, v64, v101
	v_fmac_f32_e32 v72, v60, v102
	v_fmac_f32_e32 v72, v65, v103
	v_fmac_f32_e32 v72, v61, v104
	v_fmac_f32_e32 v72, v62, v105
	v_pk_mul_f32 v[68:69], v[34:35], v[106:107]
	s_nop 0
	v_add_f32_e32 v68, v72, v68
	v_add_f32_e32 v72, v68, v69
	v_pk_mul_f32 v[68:69], v[36:37], v[108:109]
	s_nop 0
	v_add_f32_e32 v68, v72, v68
	v_add_f32_e32 v72, v68, v69
	v_pk_mul_f32 v[68:69], v[38:39], v[110:111]
	s_nop 0
	v_add_f32_e32 v68, v72, v68
	v_add_f32_e32 v72, v68, v69
	v_pk_mul_f32 v[68:69], v[40:41], v[112:113]
	s_nop 0
	v_add_f32_e32 v68, v72, v68
	v_add_f32_e32 v72, v68, v69
	v_pk_mul_f32 v[68:69], v[58:59], v[114:115]
	s_nop 0
	v_add_f32_e32 v68, v72, v68
	v_add_f32_e32 v68, v68, v69
	v_min_f32_e32 v69, 0, v68
	v_mul_f32_e64 v68, |v68|, s73
	v_exp_f32_e32 v68, v68
	s_nop 0
	v_add_f32_e32 v68, 1.0, v68
	v_cmp_gt_f32_e32 vcc, s94, v68
	s_nop 1
	v_cndmask_b32_e64 v70, 0, 32, vcc
	v_ldexp_f32 v68, v68, v70
	v_log_f32_e32 v68, v68
	s_nop 0
	v_mul_f32_e32 v70, 0x3f317217, v68
	v_fma_f32 v70, v68, s97, -v70
	v_fmac_f32_e32 v70, 0x3377d1cf, v68
	v_fmac_f32_e32 v70, 0x3f317217, v68
	v_cmp_lt_f32_e64 s[14:15], |v68|, s23
	s_nop 1
	v_cndmask_b32_e64 v68, v68, v70, s[14:15]
	v_cndmask_b32_e32 v70, 0, v211, vcc
	v_sub_f32_e32 v68, v68, v70
	v_sub_f32_e32 v68, v69, v68
	v_fmac_f32_e32 v67, 0x3d800000, v68
	v_mov_b32_e32 v129, v68
	v_add_u32_e32 v84, s0, v195
	ds_read_b128 v[68:71], v84
	ds_read_b128 v[72:75], v84 offset:16
	ds_read_b128 v[76:79], v84 offset:32
	ds_read_b128 v[80:83], v84 offset:48
	ds_read_b128 v[100:103], v84 offset:64
	ds_read_b128 v[104:107], v84 offset:80
	ds_read_b128 v[108:111], v84 offset:96
	ds_read_b128 v[112:115], v84 offset:112
	s_addk_i32 s0, 0x80
	s_waitcnt vmcnt(1) lgkmcnt(7)
	v_fma_f32 v85, v63, v68, v66
	v_fmac_f32_e32 v85, v64, v69
	v_fmac_f32_e32 v85, v60, v70
	v_fmac_f32_e32 v85, v65, v71
	s_waitcnt lgkmcnt(6)
	v_fmac_f32_e32 v85, v61, v72
	v_fmac_f32_e32 v85, v62, v73
	v_pk_mul_f32 v[68:69], v[34:35], v[74:75]
	v_add_f32_e32 v68, v85, v68
	v_add_f32_e32 v70, v68, v69
	s_waitcnt lgkmcnt(5)
	v_pk_mul_f32 v[68:69], v[36:37], v[76:77]
	s_nop 0
	v_add_f32_e32 v68, v70, v68
	v_add_f32_e32 v70, v68, v69
	v_pk_mul_f32 v[68:69], v[38:39], v[78:79]
	s_nop 0
	v_add_f32_e32 v68, v70, v68
	v_add_f32_e32 v70, v68, v69
	s_waitcnt lgkmcnt(4)
	v_pk_mul_f32 v[68:69], v[40:41], v[80:81]
	s_nop 0
	v_add_f32_e32 v68, v70, v68
	v_add_f32_e32 v70, v68, v69
	s_waitcnt vmcnt(0)
	v_pk_mul_f32 v[68:69], v[58:59], v[82:83]
	s_nop 0
	v_add_f32_e32 v68, v70, v68
	v_add_f32_e32 v68, v68, v69
	v_min_f32_e32 v69, 0, v68
	v_mul_f32_e64 v68, |v68|, s73
	v_exp_f32_e32 v68, v68
	s_nop 0
	v_add_f32_e32 v68, 1.0, v68
	v_cmp_gt_f32_e32 vcc, s94, v68
	s_nop 1
	v_cndmask_b32_e64 v70, 0, 32, vcc
	v_ldexp_f32 v68, v68, v70
	v_log_f32_e32 v68, v68
	s_nop 0
	v_mul_f32_e32 v70, 0x3f317217, v68
	v_fma_f32 v70, v68, s97, -v70
	v_fmac_f32_e32 v70, 0x3377d1cf, v68
	v_fmac_f32_e32 v70, 0x3f317217, v68
	v_cmp_lt_f32_e64 s[14:15], |v68|, s23
	s_nop 1
	v_cndmask_b32_e64 v68, v68, v70, s[14:15]
	v_cndmask_b32_e32 v70, 0, v211, vcc
	v_sub_f32_e32 v68, v68, v70
	v_sub_f32_e32 v68, v69, v68
	v_fmac_f32_e32 v67, 0x3d800000, v68
	v_mov_b32_e32 v136, v68
	s_waitcnt lgkmcnt(0)
; DEVI float logsigf_(float x) { return fminf(x, 0.f) - __logf(1.f + __expf(-fabsf(x))); }
; DEVI void lds_barrier() { asm volatile("s_waitcnt lgkmcnt(0)\n\ts_barrier" ::: "memory"); }
; DEVI float gla_la(const float* gl, int t, const float* w2r, float gb) { float x = gb;
; #pragma unroll
;     for (int r = 0; r < 16; ++r) x += gl[t * 16 + r] * w2r[r];
;     return logsigf_(x) * (1.f / 16.f); }
; template <int KIND>
; DEVI void mix_out_phase(unsigned char* smem, const MixArgs a) {
;     ...
;             for (int t = sg * 32; t < sg * 32 + 32; ++t) ssum += gla_la(gl, t, w2r, gb);
;             seg[sg * 128 + ch] = ssum; lds_barrier();
;             float Bc = 0.f;
; #pragma unroll
;             for (int s2 = 0; s2 < 4; ++s2) { const float v = seg[s2 * 128 + ch]; if (s2 < sg) Bc += v; }
	v_fma_f32 v72, v63, v100, v66
	v_fmac_f32_e32 v72, v64, v101
	v_fmac_f32_e32 v72, v60, v102
	v_fmac_f32_e32 v72, v65, v103
	v_fmac_f32_e32 v72, v61, v104
	v_fmac_f32_e32 v72, v62, v105
	v_pk_mul_f32 v[68:69], v[34:35], v[106:107]
	s_nop 0
	v_add_f32_e32 v68, v72, v68
	v_add_f32_e32 v72, v68, v69
	v_pk_mul_f32 v[68:69], v[36:37], v[108:109]
	s_nop 0
	v_add_f32_e32 v68, v72, v68
	v_add_f32_e32 v72, v68, v69
	v_pk_mul_f32 v[68:69], v[38:39], v[110:111]
	s_nop 0
	v_add_f32_e32 v68, v72, v68
	v_add_f32_e32 v72, v68, v69
	v_pk_mul_f32 v[68:69], v[40:41], v[112:113]
	s_nop 0
	v_add_f32_e32 v68, v72, v68
	v_add_f32_e32 v72, v68, v69
	v_pk_mul_f32 v[68:69], v[58:59], v[114:115]
	s_nop 0
	v_add_f32_e32 v68, v72, v68
	v_add_f32_e32 v68, v68, v69
	v_min_f32_e32 v69, 0, v68
	v_mul_f32_e64 v68, |v68|, s73
	v_exp_f32_e32 v68, v68
	s_nop 0
	v_add_f32_e32 v68, 1.0, v68
	v_cmp_gt_f32_e32 vcc, s94, v68
	s_nop 1
	v_cndmask_b32_e64 v70, 0, 32, vcc
	v_ldexp_f32 v68, v68, v70
	v_log_f32_e32 v68, v68
	s_nop 0
	v_mul_f32_e32 v70, 0x3f317217, v68
	v_fma_f32 v70, v68, s97, -v70
	v_fmac_f32_e32 v70, 0x3377d1cf, v68
	v_fmac_f32_e32 v70, 0x3f317217, v68
	v_cmp_lt_f32_e64 s[14:15], |v68|, s23
	s_nop 1
	v_cndmask_b32_e64 v68, v68, v70, s[14:15]
	v_cndmask_b32_e32 v70, 0, v211, vcc
	v_sub_f32_e32 v68, v68, v70
	v_sub_f32_e32 v68, v69, v68
	v_fmac_f32_e32 v67, 0x3d800000, v68
	v_mov_b32_e32 v137, v68
	v_add_u32_e32 v84, s0, v195
	ds_read_b128 v[68:71], v84
	ds_read_b128 v[72:75], v84 offset:16
	ds_read_b128 v[76:79], v84 offset:32
	ds_read_b128 v[80:83], v84 offset:48
	ds_read_b128 v[100:103], v84 offset:64
	ds_read_b128 v[104:107], v84 offset:80
	ds_read_b128 v[108:111], v84 offset:96
	ds_read_b128 v[112:115], v84 offset:112
	s_addk_i32 s0, 0x80
	s_waitcnt vmcnt(1) lgkmcnt(7)
	v_fma_f32 v85, v63, v68, v66
	v_fmac_f32_e32 v85, v64, v69
	v_fmac_f32_e32 v85, v60, v70
	v_fmac_f32_e32 v85, v65, v71
	s_waitcnt lgkmcnt(6)
	v_fmac_f32_e32 v85, v61, v72
	v_fmac_f32_e32 v85, v62, v73
	v_pk_mul_f32 v[68:69], v[34:35], v[74:75]
	v_add_f32_e32 v68, v85, v68
	v_add_f32_e32 v70, v68, v69
	s_waitcnt lgkmcnt(5)
	v_pk_mul_f32 v[68:69], v[36:37], v[76:77]
	s_nop 0
	v_add_f32_e32 v68, v70, v68
	v_add_f32_e32 v70, v68, v69
	v_pk_mul_f32 v[68:69], v[38:39], v[78:79]
	s_nop 0
	v_add_f32_e32 v68, v70, v68
	v_add_f32_e32 v70, v68, v69
	s_waitcnt lgkmcnt(4)
	v_pk_mul_f32 v[68:69], v[40:41], v[80:81]
	s_nop 0
	v_add_f32_e32 v68, v70, v68
	v_add_f32_e32 v70, v68, v69
	s_waitcnt vmcnt(0)
	v_pk_mul_f32 v[68:69], v[58:59], v[82:83]
	s_nop 0
	v_add_f32_e32 v68, v70, v68
	v_add_f32_e32 v68, v68, v69
	v_min_f32_e32 v69, 0, v68
	v_mul_f32_e64 v68, |v68|, s73
	v_exp_f32_e32 v68, v68
	s_nop 0
	v_add_f32_e32 v68, 1.0, v68
	v_cmp_gt_f32_e32 vcc, s94, v68
	s_nop 1
	v_cndmask_b32_e64 v70, 0, 32, vcc
	v_ldexp_f32 v68, v68, v70
	v_log_f32_e32 v68, v68
	s_nop 0
	v_mul_f32_e32 v70, 0x3f317217, v68
	v_fma_f32 v70, v68, s97, -v70
	v_fmac_f32_e32 v70, 0x3377d1cf, v68
	v_fmac_f32_e32 v70, 0x3f317217, v68
	v_cmp_lt_f32_e64 s[14:15], |v68|, s23
	s_nop 1
	v_cndmask_b32_e64 v68, v68, v70, s[14:15]
	v_cndmask_b32_e32 v70, 0, v211, vcc
	v_sub_f32_e32 v68, v68, v70
	v_sub_f32_e32 v68, v69, v68
	v_fmac_f32_e32 v67, 0x3d800000, v68
	v_mov_b32_e32 v138, v68
	s_waitcnt lgkmcnt(0)
	v_fma_f32 v72, v63, v100, v66
	v_fmac_f32_e32 v72, v64, v101
	v_fmac_f32_e32 v72, v60, v102
	v_fmac_f32_e32 v72, v65, v103
	v_fmac_f32_e32 v72, v61, v104
	v_fmac_f32_e32 v72, v62, v105
	v_pk_mul_f32 v[68:69], v[34:35], v[106:107]
	s_nop 0
	v_add_f32_e32 v68, v72, v68
	v_add_f32_e32 v72, v68, v69
	v_pk_mul_f32 v[68:69], v[36:37], v[108:109]
	s_nop 0
	v_add_f32_e32 v68, v72, v68
	v_add_f32_e32 v72, v68, v69
	v_pk_mul_f32 v[68:69], v[38:39], v[110:111]
	s_nop 0
	v_add_f32_e32 v68, v72, v68
	v_add_f32_e32 v72, v68, v69
	v_pk_mul_f32 v[68:69], v[40:41], v[112:113]
	s_nop 0
	v_add_f32_e32 v68, v72, v68
	v_add_f32_e32 v72, v68, v69
	v_pk_mul_f32 v[68:69], v[58:59], v[114:115]
	s_nop 0
	v_add_f32_e32 v68, v72, v68
	v_add_f32_e32 v68, v68, v69
	v_min_f32_e32 v69, 0, v68
	v_mul_f32_e64 v68, |v68|, s73
	v_exp_f32_e32 v68, v68
	s_nop 0
	v_add_f32_e32 v68, 1.0, v68
	v_cmp_gt_f32_e32 vcc, s94, v68
	s_nop 1
	v_cndmask_b32_e64 v70, 0, 32, vcc
	v_ldexp_f32 v68, v68, v70
	v_log_f32_e32 v68, v68
	s_nop 0
	v_mul_f32_e32 v70, 0x3f317217, v68
	v_fma_f32 v70, v68, s97, -v70
	v_fmac_f32_e32 v70, 0x3377d1cf, v68
	v_fmac_f32_e32 v70, 0x3f317217, v68
	v_cmp_lt_f32_e64 s[14:15], |v68|, s23
	s_nop 1
	v_cndmask_b32_e64 v68, v68, v70, s[14:15]
	v_cndmask_b32_e32 v70, 0, v211, vcc
	v_sub_f32_e32 v68, v68, v70
	v_sub_f32_e32 v68, v69, v68
	v_fmac_f32_e32 v67, 0x3d800000, v68
	v_mov_b32_e32 v139, v68
	ds_write_b32 v204, v67 offset:1536
	s_waitcnt lgkmcnt(0)
	s_barrier
	v_mov_b32_e32 v67, 0
	s_and_saveexec_b64 s[14:15], s[6:7]
	s_cbranch_execz .LBB0_696
	ds_read_b32 v67, v205 offset:1536
	s_waitcnt lgkmcnt(0)
	v_add_f32_e32 v67, 0, v67
	s_or_b64 exec, exec, s[14:15]
	s_and_saveexec_b64 s[14:15], s[8:9]
	s_cbranch_execnz .LBB0_697

; DEVI float bf2f(u16 b) { return __uint_as_float(((unsigned)b) << 16); }
; DEVI u16 f2bf(float f) { return (u16)(cvt_pk(f, 0.f) & 0xffffu); }
; template <int KIND>
; DEVI void mix_out_phase(unsigned char* smem, const MixArgs a) {
;     ...
;             float Bc = 0.f;
; #pragma unroll
;             for (int s2 = 0; s2 < 4; ++s2) { const float v = seg[s2 * 128 + ch]; if (s2 < sg) Bc += v; }
;             for (int t = sg * 32; t < sg * 32 + 32; ++t) { Bc += gla_la(gl, t, w2r, gb);
;                 QS[t * LP + ch] = f2bf(bf2f(QS[t * LP + ch]) * 0.08838834764831845f * __expf(Bc)); KS[t * LP + ch] = f2bf(bf2f(KS[t * LP + ch]) * __expf(-Bc)); }
.LBB0_701:
	v_fmac_f32_e32 v67, 0x3d800000, v86
	ds_read_u16 v70, v68
	v_mul_f32_e32 v71, 0x3fb8aa3b, v67
	v_exp_f32_e32 v71, v71
	s_waitcnt lgkmcnt(0)
	v_lshlrev_b32_e32 v70, 16, v70
	v_mul_f32_e32 v70, 0x3db504f3, v70
	v_mul_f32_e32 v70, v70, v71
	v_cvt_pk_bf16_f32 v70, v70, s0
	ds_write_b16 v68, v70
	ds_read_u16 v70, v68 offset:34816
	v_mul_f32_e32 v71, 0xbfb8aa3b, v67
	v_exp_f32_e32 v71, v71
	s_waitcnt lgkmcnt(0)
	v_lshlrev_b32_e32 v70, 16, v70
	v_mul_f32_e32 v70, v71, v70
	v_cvt_pk_bf16_f32 v70, v70, s0
	ds_write_b16 v68, v70 offset:34816
	v_fmac_f32_e32 v67, 0x3d800000, v87
	ds_read_u16 v69, v68 offset:272
	v_mul_f32_e32 v70, 0x3fb8aa3b, v67
	v_exp_f32_e32 v70, v70
	s_waitcnt lgkmcnt(0)
	v_lshlrev_b32_e32 v69, 16, v69
	v_mul_f32_e32 v69, 0x3db504f3, v69
	v_mul_f32_e32 v69, v69, v70
	v_cvt_pk_bf16_f32 v69, v69, s0
	ds_write_b16 v68, v69 offset:272
	ds_read_u16 v69, v68 offset:35088
	v_mul_f32_e32 v70, 0xbfb8aa3b, v67
	v_exp_f32_e32 v70, v70
	s_waitcnt lgkmcnt(0)
	v_lshlrev_b32_e32 v69, 16, v69
	v_mul_f32_e32 v69, v70, v69
	v_cvt_pk_bf16_f32 v69, v69, s0
	s_addk_i32 s0, 0x80
	ds_write_b16 v68, v69 offset:35088
	v_add_u32_e32 v68, 0x220, v68
	v_fmac_f32_e32 v67, 0x3d800000, v88
	ds_read_u16 v70, v68
	v_mul_f32_e32 v71, 0x3fb8aa3b, v67
	v_exp_f32_e32 v71, v71
	s_waitcnt lgkmcnt(0)
	v_lshlrev_b32_e32 v70, 16, v70
	v_mul_f32_e32 v70, 0x3db504f3, v70
	v_mul_f32_e32 v70, v70, v71
	v_cvt_pk_bf16_f32 v70, v70, s0
	ds_write_b16 v68, v70
	ds_read_u16 v70, v68 offset:34816
	v_mul_f32_e32 v71, 0xbfb8aa3b, v67
	v_exp_f32_e32 v71, v71
	s_waitcnt lgkmcnt(0)
	v_lshlrev_b32_e32 v70, 16, v70
	v_mul_f32_e32 v70, v71, v70
	v_cvt_pk_bf16_f32 v70, v70, s0
	ds_write_b16 v68, v70 offset:34816
	v_fmac_f32_e32 v67, 0x3d800000, v89
	ds_read_u16 v69, v68 offset:272
	v_mul_f32_e32 v70, 0x3fb8aa3b, v67
	v_exp_f32_e32 v70, v70
	s_waitcnt lgkmcnt(0)
	v_lshlrev_b32_e32 v69, 16, v69
	v_mul_f32_e32 v69, 0x3db504f3, v69
	v_mul_f32_e32 v69, v69, v70
	v_cvt_pk_bf16_f32 v69, v69, s0
	ds_write_b16 v68, v69 offset:272
	ds_read_u16 v69, v68 offset:35088
	v_mul_f32_e32 v70, 0xbfb8aa3b, v67
	v_exp_f32_e32 v70, v70
	s_waitcnt lgkmcnt(0)
	v_lshlrev_b32_e32 v69, 16, v69
	v_mul_f32_e32 v69, v70, v69
	v_cvt_pk_bf16_f32 v69, v69, s0
	s_addk_i32 s0, 0x80
	ds_write_b16 v68, v69 offset:35088
	v_add_u32_e32 v68, 0x220, v68
	v_fmac_f32_e32 v67, 0x3d800000, v90
	ds_read_u16 v70, v68
	v_mul_f32_e32 v71, 0x3fb8aa3b, v67
	v_exp_f32_e32 v71, v71
	s_waitcnt lgkmcnt(0)
	v_lshlrev_b32_e32 v70, 16, v70
	v_mul_f32_e32 v70, 0x3db504f3, v70
	v_mul_f32_e32 v70, v70, v71
	v_cvt_pk_bf16_f32 v70, v70, s0
	ds_write_b16 v68, v70
	ds_read_u16 v70, v68 offset:34816
	v_mul_f32_e32 v71, 0xbfb8aa3b, v67
	v_exp_f32_e32 v71, v71
	s_waitcnt lgkmcnt(0)
	v_lshlrev_b32_e32 v70, 16, v70
	v_mul_f32_e32 v70, v71, v70
	v_cvt_pk_bf16_f32 v70, v70, s0
	ds_write_b16 v68, v70 offset:34816
	v_fmac_f32_e32 v67, 0x3d800000, v91
	ds_read_u16 v69, v68 offset:272
	v_mul_f32_e32 v70, 0x3fb8aa3b, v67
	v_exp_f32_e32 v70, v70
	s_waitcnt lgkmcnt(0)
	v_lshlrev_b32_e32 v69, 16, v69
	v_mul_f32_e32 v69, 0x3db504f3, v69
	v_mul_f32_e32 v69, v69, v70
	v_cvt_pk_bf16_f32 v69, v69, s0
	ds_write_b16 v68, v69 offset:272
	ds_read_u16 v69, v68 offset:35088
	v_mul_f32_e32 v70, 0xbfb8aa3b, v67
	v_exp_f32_e32 v70, v70
	s_waitcnt lgkmcnt(0)
	v_lshlrev_b32_e32 v69, 16, v69
	v_mul_f32_e32 v69, v70, v69
	v_cvt_pk_bf16_f32 v69, v69, s0
	s_addk_i32 s0, 0x80
	ds_write_b16 v68, v69 offset:35088
	v_add_u32_e32 v68, 0x220, v68
	v_fmac_f32_e32 v67, 0x3d800000, v92
	ds_read_u16 v70, v68
	v_mul_f32_e32 v71, 0x3fb8aa3b, v67
	v_exp_f32_e32 v71, v71
	s_waitcnt lgkmcnt(0)
	v_lshlrev_b32_e32 v70, 16, v70
	v_mul_f32_e32 v70, 0x3db504f3, v70
	v_mul_f32_e32 v70, v70, v71
	v_cvt_pk_bf16_f32 v70, v70, s0
	ds_write_b16 v68, v70
	ds_read_u16 v70, v68 offset:34816
	v_mul_f32_e32 v71, 0xbfb8aa3b, v67
	v_exp_f32_e32 v71, v71
	s_waitcnt lgkmcnt(0)
	v_lshlrev_b32_e32 v70, 16, v70
	v_mul_f32_e32 v70, v71, v70
	v_cvt_pk_bf16_f32 v70, v70, s0
	ds_write_b16 v68, v70 offset:34816
	v_fmac_f32_e32 v67, 0x3d800000, v93
	ds_read_u16 v69, v68 offset:272
	v_mul_f32_e32 v70, 0x3fb8aa3b, v67
	v_exp_f32_e32 v70, v70
	s_waitcnt lgkmcnt(0)
	v_lshlrev_b32_e32 v69, 16, v69
	v_mul_f32_e32 v69, 0x3db504f3, v69
	v_mul_f32_e32 v69, v69, v70
	v_cvt_pk_bf16_f32 v69, v69, s0
	ds_write_b16 v68, v69 offset:272
	ds_read_u16 v69, v68 offset:35088
	v_mul_f32_e32 v70, 0xbfb8aa3b, v67
	v_exp_f32_e32 v70, v70
	s_waitcnt lgkmcnt(0)
	v_lshlrev_b32_e32 v69, 16, v69
	v_mul_f32_e32 v69, v70, v69
	v_cvt_pk_bf16_f32 v69, v69, s0
	s_addk_i32 s0, 0x80
	ds_write_b16 v68, v69 offset:35088
	v_add_u32_e32 v68, 0x220, v68
	v_fmac_f32_e32 v67, 0x3d800000, v94
	ds_read_u16 v70, v68
	v_mul_f32_e32 v71, 0x3fb8aa3b, v67
	v_exp_f32_e32 v71, v71
	s_waitcnt lgkmcnt(0)
	v_lshlrev_b32_e32 v70, 16, v70
	v_mul_f32_e32 v70, 0x3db504f3, v70
	v_mul_f32_e32 v70, v70, v71
	v_cvt_pk_bf16_f32 v70, v70, s0
	ds_write_b16 v68, v70
	ds_read_u16 v70, v68 offset:34816
	v_mul_f32_e32 v71, 0xbfb8aa3b, v67
	v_exp_f32_e32 v71, v71
	s_waitcnt lgkmcnt(0)
	v_lshlrev_b32_e32 v70, 16, v70
	v_mul_f32_e32 v70, v71, v70
	v_cvt_pk_bf16_f32 v70, v70, s0
	ds_write_b16 v68, v70 offset:34816
	v_fmac_f32_e32 v67, 0x3d800000, v95
	ds_read_u16 v69, v68 offset:272
	v_mul_f32_e32 v70, 0x3fb8aa3b, v67
	v_exp_f32_e32 v70, v70
	s_waitcnt lgkmcnt(0)
	v_lshlrev_b32_e32 v69, 16, v69
	v_mul_f32_e32 v69, 0x3db504f3, v69
	v_mul_f32_e32 v69, v69, v70
	v_cvt_pk_bf16_f32 v69, v69, s0
	ds_write_b16 v68, v69 offset:272
	ds_read_u16 v69, v68 offset:35088
	v_mul_f32_e32 v70, 0xbfb8aa3b, v67
	v_exp_f32_e32 v70, v70
	s_waitcnt lgkmcnt(0)
; DEVI float bf2f(u16 b) { return __uint_as_float(((unsigned)b) << 16); }
; DEVI u16 f2bf(float f) { return (u16)(cvt_pk(f, 0.f) & 0xffffu); }
; template <int KIND>
; DEVI void mix_out_phase(unsigned char* smem, const MixArgs a) {
;     ...
;             for (int t = sg * 32; t < sg * 32 + 32; ++t) { Bc += gla_la(gl, t, w2r, gb);
;                 QS[t * LP + ch] = f2bf(bf2f(QS[t * LP + ch]) * 0.08838834764831845f * __expf(Bc)); KS[t * LP + ch] = f2bf(bf2f(KS[t * LP + ch]) * __expf(-Bc)); }
	v_lshlrev_b32_e32 v69, 16, v69
	v_mul_f32_e32 v69, v70, v69
	v_cvt_pk_bf16_f32 v69, v69, s0
	s_addk_i32 s0, 0x80
	ds_write_b16 v68, v69 offset:35088
	v_add_u32_e32 v68, 0x220, v68
	v_fmac_f32_e32 v67, 0x3d800000, v96
	ds_read_u16 v70, v68
	v_mul_f32_e32 v71, 0x3fb8aa3b, v67
	v_exp_f32_e32 v71, v71
	s_waitcnt lgkmcnt(0)
	v_lshlrev_b32_e32 v70, 16, v70
	v_mul_f32_e32 v70, 0x3db504f3, v70
	v_mul_f32_e32 v70, v70, v71
	v_cvt_pk_bf16_f32 v70, v70, s0
	ds_write_b16 v68, v70
	ds_read_u16 v70, v68 offset:34816
	v_mul_f32_e32 v71, 0xbfb8aa3b, v67
	v_exp_f32_e32 v71, v71
	s_waitcnt lgkmcnt(0)
	v_lshlrev_b32_e32 v70, 16, v70
	v_mul_f32_e32 v70, v71, v70
	v_cvt_pk_bf16_f32 v70, v70, s0
	ds_write_b16 v68, v70 offset:34816
	v_fmac_f32_e32 v67, 0x3d800000, v97
	ds_read_u16 v69, v68 offset:272
	v_mul_f32_e32 v70, 0x3fb8aa3b, v67
	v_exp_f32_e32 v70, v70
	s_waitcnt lgkmcnt(0)
	v_lshlrev_b32_e32 v69, 16, v69
	v_mul_f32_e32 v69, 0x3db504f3, v69
	v_mul_f32_e32 v69, v69, v70
	v_cvt_pk_bf16_f32 v69, v69, s0
	ds_write_b16 v68, v69 offset:272
	ds_read_u16 v69, v68 offset:35088
	v_mul_f32_e32 v70, 0xbfb8aa3b, v67
	v_exp_f32_e32 v70, v70
	s_waitcnt lgkmcnt(0)
	v_lshlrev_b32_e32 v69, 16, v69
	v_mul_f32_e32 v69, v70, v69
	v_cvt_pk_bf16_f32 v69, v69, s0
	s_addk_i32 s0, 0x80
	ds_write_b16 v68, v69 offset:35088
	v_add_u32_e32 v68, 0x220, v68
	v_fmac_f32_e32 v67, 0x3d800000, v98
	ds_read_u16 v70, v68
	v_mul_f32_e32 v71, 0x3fb8aa3b, v67
	v_exp_f32_e32 v71, v71
	s_waitcnt lgkmcnt(0)
	v_lshlrev_b32_e32 v70, 16, v70
	v_mul_f32_e32 v70, 0x3db504f3, v70
	v_mul_f32_e32 v70, v70, v71
	v_cvt_pk_bf16_f32 v70, v70, s0
	ds_write_b16 v68, v70
	ds_read_u16 v70, v68 offset:34816
	v_mul_f32_e32 v71, 0xbfb8aa3b, v67
	v_exp_f32_e32 v71, v71
	s_waitcnt lgkmcnt(0)
	v_lshlrev_b32_e32 v70, 16, v70
	v_mul_f32_e32 v70, v71, v70
	v_cvt_pk_bf16_f32 v70, v70, s0
	ds_write_b16 v68, v70 offset:34816
	v_fmac_f32_e32 v67, 0x3d800000, v99
	ds_read_u16 v69, v68 offset:272
	v_mul_f32_e32 v70, 0x3fb8aa3b, v67
	v_exp_f32_e32 v70, v70
	s_waitcnt lgkmcnt(0)
	v_lshlrev_b32_e32 v69, 16, v69
	v_mul_f32_e32 v69, 0x3db504f3, v69
	v_mul_f32_e32 v69, v69, v70
	v_cvt_pk_bf16_f32 v69, v69, s0
	ds_write_b16 v68, v69 offset:272
	ds_read_u16 v69, v68 offset:35088
	v_mul_f32_e32 v70, 0xbfb8aa3b, v67
	v_exp_f32_e32 v70, v70
	s_waitcnt lgkmcnt(0)
	v_lshlrev_b32_e32 v69, 16, v69
	v_mul_f32_e32 v69, v70, v69
	v_cvt_pk_bf16_f32 v69, v69, s0
	s_addk_i32 s0, 0x80
	ds_write_b16 v68, v69 offset:35088
	v_add_u32_e32 v68, 0x220, v68
	v_fmac_f32_e32 v67, 0x3d800000, v116
	ds_read_u16 v70, v68
	v_mul_f32_e32 v71, 0x3fb8aa3b, v67
	v_exp_f32_e32 v71, v71
	s_waitcnt lgkmcnt(0)
	v_lshlrev_b32_e32 v70, 16, v70
	v_mul_f32_e32 v70, 0x3db504f3, v70
	v_mul_f32_e32 v70, v70, v71
	v_cvt_pk_bf16_f32 v70, v70, s0
	ds_write_b16 v68, v70
	ds_read_u16 v70, v68 offset:34816
	v_mul_f32_e32 v71, 0xbfb8aa3b, v67
	v_exp_f32_e32 v71, v71
	s_waitcnt lgkmcnt(0)
	v_lshlrev_b32_e32 v70, 16, v70
	v_mul_f32_e32 v70, v71, v70
	v_cvt_pk_bf16_f32 v70, v70, s0
	ds_write_b16 v68, v70 offset:34816
	v_fmac_f32_e32 v67, 0x3d800000, v117
	ds_read_u16 v69, v68 offset:272
	v_mul_f32_e32 v70, 0x3fb8aa3b, v67
	v_exp_f32_e32 v70, v70
	s_waitcnt lgkmcnt(0)
	v_lshlrev_b32_e32 v69, 16, v69
	v_mul_f32_e32 v69, 0x3db504f3, v69
	v_mul_f32_e32 v69, v69, v70
	v_cvt_pk_bf16_f32 v69, v69, s0
	ds_write_b16 v68, v69 offset:272
	ds_read_u16 v69, v68 offset:35088
	v_mul_f32_e32 v70, 0xbfb8aa3b, v67
	v_exp_f32_e32 v70, v70
	s_waitcnt lgkmcnt(0)
	v_lshlrev_b32_e32 v69, 16, v69
	v_mul_f32_e32 v69, v70, v69
	v_cvt_pk_bf16_f32 v69, v69, s0
	s_addk_i32 s0, 0x80
	ds_write_b16 v68, v69 offset:35088
	v_add_u32_e32 v68, 0x220, v68
	v_fmac_f32_e32 v67, 0x3d800000, v118
	ds_read_u16 v70, v68
	v_mul_f32_e32 v71, 0x3fb8aa3b, v67
	v_exp_f32_e32 v71, v71
	s_waitcnt lgkmcnt(0)
	v_lshlrev_b32_e32 v70, 16, v70
	v_mul_f32_e32 v70, 0x3db504f3, v70
	v_mul_f32_e32 v70, v70, v71
	v_cvt_pk_bf16_f32 v70, v70, s0
	ds_write_b16 v68, v70
	ds_read_u16 v70, v68 offset:34816
	v_mul_f32_e32 v71, 0xbfb8aa3b, v67
	v_exp_f32_e32 v71, v71
	s_waitcnt lgkmcnt(0)
	v_lshlrev_b32_e32 v70, 16, v70
	v_mul_f32_e32 v70, v71, v70
	v_cvt_pk_bf16_f32 v70, v70, s0
	ds_write_b16 v68, v70 offset:34816
	v_fmac_f32_e32 v67, 0x3d800000, v119
	ds_read_u16 v69, v68 offset:272
	v_mul_f32_e32 v70, 0x3fb8aa3b, v67
	v_exp_f32_e32 v70, v70
	s_waitcnt lgkmcnt(0)
	v_lshlrev_b32_e32 v69, 16, v69
	v_mul_f32_e32 v69, 0x3db504f3, v69
	v_mul_f32_e32 v69, v69, v70
	v_cvt_pk_bf16_f32 v69, v69, s0
	ds_write_b16 v68, v69 offset:272
	ds_read_u16 v69, v68 offset:35088
	v_mul_f32_e32 v70, 0xbfb8aa3b, v67
	v_exp_f32_e32 v70, v70
	s_waitcnt lgkmcnt(0)
	v_lshlrev_b32_e32 v69, 16, v69
	v_mul_f32_e32 v69, v70, v69
	v_cvt_pk_bf16_f32 v69, v69, s0
	s_addk_i32 s0, 0x80
	ds_write_b16 v68, v69 offset:35088
	v_add_u32_e32 v68, 0x220, v68
	v_fmac_f32_e32 v67, 0x3d800000, v120
	ds_read_u16 v70, v68
	v_mul_f32_e32 v71, 0x3fb8aa3b, v67
	v_exp_f32_e32 v71, v71
	s_waitcnt lgkmcnt(0)
	v_lshlrev_b32_e32 v70, 16, v70
	v_mul_f32_e32 v70, 0x3db504f3, v70
	v_mul_f32_e32 v70, v70, v71
	v_cvt_pk_bf16_f32 v70, v70, s0
	ds_write_b16 v68, v70
	ds_read_u16 v70, v68 offset:34816
	v_mul_f32_e32 v71, 0xbfb8aa3b, v67
	v_exp_f32_e32 v71, v71
	s_waitcnt lgkmcnt(0)
	v_lshlrev_b32_e32 v70, 16, v70
	v_mul_f32_e32 v70, v71, v70
	v_cvt_pk_bf16_f32 v70, v70, s0
	ds_write_b16 v68, v70 offset:34816
	v_fmac_f32_e32 v67, 0x3d800000, v121
	ds_read_u16 v69, v68 offset:272
	v_mul_f32_e32 v70, 0x3fb8aa3b, v67
	v_exp_f32_e32 v70, v70
	s_waitcnt lgkmcnt(0)
	v_lshlrev_b32_e32 v69, 16, v69
	v_mul_f32_e32 v69, 0x3db504f3, v69
	v_mul_f32_e32 v69, v69, v70
	v_cvt_pk_bf16_f32 v69, v69, s0
	ds_write_b16 v68, v69 offset:272
	ds_read_u16 v69, v68 offset:35088
	v_mul_f32_e32 v70, 0xbfb8aa3b, v67
	v_exp_f32_e32 v70, v70
	s_waitcnt lgkmcnt(0)
; DEVI float bf2f(u16 b) { return __uint_as_float(((unsigned)b) << 16); }
; DEVI u16 f2bf(float f) { return (u16)(cvt_pk(f, 0.f) & 0xffffu); }
; template <int KIND>
; DEVI void mix_out_phase(unsigned char* smem, const MixArgs a) {
;     ...
;             for (int t = sg * 32; t < sg * 32 + 32; ++t) { Bc += gla_la(gl, t, w2r, gb);
;                 QS[t * LP + ch] = f2bf(bf2f(QS[t * LP + ch]) * 0.08838834764831845f * __expf(Bc)); KS[t * LP + ch] = f2bf(bf2f(KS[t * LP + ch]) * __expf(-Bc)); }
	v_lshlrev_b32_e32 v69, 16, v69
	v_mul_f32_e32 v69, v70, v69
	v_cvt_pk_bf16_f32 v69, v69, s0
	s_addk_i32 s0, 0x80
	ds_write_b16 v68, v69 offset:35088
	v_add_u32_e32 v68, 0x220, v68
	v_fmac_f32_e32 v67, 0x3d800000, v122
	ds_read_u16 v70, v68
	v_mul_f32_e32 v71, 0x3fb8aa3b, v67
	v_exp_f32_e32 v71, v71
	s_waitcnt lgkmcnt(0)
	v_lshlrev_b32_e32 v70, 16, v70
	v_mul_f32_e32 v70, 0x3db504f3, v70
	v_mul_f32_e32 v70, v70, v71
	v_cvt_pk_bf16_f32 v70, v70, s0
	ds_write_b16 v68, v70
	ds_read_u16 v70, v68 offset:34816
	v_mul_f32_e32 v71, 0xbfb8aa3b, v67
	v_exp_f32_e32 v71, v71
	s_waitcnt lgkmcnt(0)
	v_lshlrev_b32_e32 v70, 16, v70
	v_mul_f32_e32 v70, v71, v70
	v_cvt_pk_bf16_f32 v70, v70, s0
	ds_write_b16 v68, v70 offset:34816
	v_fmac_f32_e32 v67, 0x3d800000, v123
	ds_read_u16 v69, v68 offset:272
	v_mul_f32_e32 v70, 0x3fb8aa3b, v67
	v_exp_f32_e32 v70, v70
	s_waitcnt lgkmcnt(0)
	v_lshlrev_b32_e32 v69, 16, v69
	v_mul_f32_e32 v69, 0x3db504f3, v69
	v_mul_f32_e32 v69, v69, v70
	v_cvt_pk_bf16_f32 v69, v69, s0
	ds_write_b16 v68, v69 offset:272
	ds_read_u16 v69, v68 offset:35088
	v_mul_f32_e32 v70, 0xbfb8aa3b, v67
	v_exp_f32_e32 v70, v70
	s_waitcnt lgkmcnt(0)
	v_lshlrev_b32_e32 v69, 16, v69
	v_mul_f32_e32 v69, v70, v69
	v_cvt_pk_bf16_f32 v69, v69, s0
	s_addk_i32 s0, 0x80
	ds_write_b16 v68, v69 offset:35088
	v_add_u32_e32 v68, 0x220, v68
	v_fmac_f32_e32 v67, 0x3d800000, v124
	ds_read_u16 v70, v68
	v_mul_f32_e32 v71, 0x3fb8aa3b, v67
	v_exp_f32_e32 v71, v71
	s_waitcnt lgkmcnt(0)
	v_lshlrev_b32_e32 v70, 16, v70
	v_mul_f32_e32 v70, 0x3db504f3, v70
	v_mul_f32_e32 v70, v70, v71
	v_cvt_pk_bf16_f32 v70, v70, s0
	ds_write_b16 v68, v70
	ds_read_u16 v70, v68 offset:34816
	v_mul_f32_e32 v71, 0xbfb8aa3b, v67
	v_exp_f32_e32 v71, v71
	s_waitcnt lgkmcnt(0)
	v_lshlrev_b32_e32 v70, 16, v70
	v_mul_f32_e32 v70, v71, v70
	v_cvt_pk_bf16_f32 v70, v70, s0
	ds_write_b16 v68, v70 offset:34816
	v_fmac_f32_e32 v67, 0x3d800000, v125
	ds_read_u16 v69, v68 offset:272
	v_mul_f32_e32 v70, 0x3fb8aa3b, v67
	v_exp_f32_e32 v70, v70
	s_waitcnt lgkmcnt(0)
	v_lshlrev_b32_e32 v69, 16, v69
	v_mul_f32_e32 v69, 0x3db504f3, v69
	v_mul_f32_e32 v69, v69, v70
	v_cvt_pk_bf16_f32 v69, v69, s0
	ds_write_b16 v68, v69 offset:272
	ds_read_u16 v69, v68 offset:35088
	v_mul_f32_e32 v70, 0xbfb8aa3b, v67
	v_exp_f32_e32 v70, v70
	s_waitcnt lgkmcnt(0)
	v_lshlrev_b32_e32 v69, 16, v69
	v_mul_f32_e32 v69, v70, v69
	v_cvt_pk_bf16_f32 v69, v69, s0
	s_addk_i32 s0, 0x80
	ds_write_b16 v68, v69 offset:35088
	v_add_u32_e32 v68, 0x220, v68
	v_fmac_f32_e32 v67, 0x3d800000, v126
	ds_read_u16 v70, v68
	v_mul_f32_e32 v71, 0x3fb8aa3b, v67
	v_exp_f32_e32 v71, v71
	s_waitcnt lgkmcnt(0)
	v_lshlrev_b32_e32 v70, 16, v70
	v_mul_f32_e32 v70, 0x3db504f3, v70
	v_mul_f32_e32 v70, v70, v71
	v_cvt_pk_bf16_f32 v70, v70, s0
	ds_write_b16 v68, v70
	ds_read_u16 v70, v68 offset:34816
	v_mul_f32_e32 v71, 0xbfb8aa3b, v67
	v_exp_f32_e32 v71, v71
	s_waitcnt lgkmcnt(0)
	v_lshlrev_b32_e32 v70, 16, v70
	v_mul_f32_e32 v70, v71, v70
	v_cvt_pk_bf16_f32 v70, v70, s0
	ds_write_b16 v68, v70 offset:34816
	v_fmac_f32_e32 v67, 0x3d800000, v127
	ds_read_u16 v69, v68 offset:272
	v_mul_f32_e32 v70, 0x3fb8aa3b, v67
	v_exp_f32_e32 v70, v70
	s_waitcnt lgkmcnt(0)
	v_lshlrev_b32_e32 v69, 16, v69
	v_mul_f32_e32 v69, 0x3db504f3, v69
	v_mul_f32_e32 v69, v69, v70
	v_cvt_pk_bf16_f32 v69, v69, s0
	ds_write_b16 v68, v69 offset:272
	ds_read_u16 v69, v68 offset:35088
	v_mul_f32_e32 v70, 0xbfb8aa3b, v67
	v_exp_f32_e32 v70, v70
	s_waitcnt lgkmcnt(0)
	v_lshlrev_b32_e32 v69, 16, v69
	v_mul_f32_e32 v69, v70, v69
	v_cvt_pk_bf16_f32 v69, v69, s0
	s_addk_i32 s0, 0x80
	ds_write_b16 v68, v69 offset:35088
	v_add_u32_e32 v68, 0x220, v68
	v_fmac_f32_e32 v67, 0x3d800000, v128
	ds_read_u16 v70, v68
	v_mul_f32_e32 v71, 0x3fb8aa3b, v67
	v_exp_f32_e32 v71, v71
	s_waitcnt lgkmcnt(0)
; DEVI float bf2f(u16 b) { return __uint_as_float(((unsigned)b) << 16); }
; DEVI u16 f2bf(float f) { return (u16)(cvt_pk(f, 0.f) & 0xffffu); }
; DEVI void lds_barrier() { asm volatile("s_waitcnt lgkmcnt(0)\n\ts_barrier" ::: "memory"); }
; template <int KIND>
; DEVI void mix_out_phase(unsigned char* smem, const MixArgs a) {
;     ...
;             for (int t = sg * 32; t < sg * 32 + 32; ++t) { Bc += gla_la(gl, t, w2r, gb);
;                 QS[t * LP + ch] = f2bf(bf2f(QS[t * LP + ch]) * 0.08838834764831845f * __expf(Bc)); KS[t * LP + ch] = f2bf(bf2f(KS[t * LP + ch]) * __expf(-Bc)); }
;         }
;         lds_barrier();
;         bf16x8 qa[4];
; #pragma unroll
;         for (int ks = 0; ks < 4; ++ks) qa[ks] = *(const bf16x8*)(QS + trow * LP + ks * 32 + fq * 8);
;         float rowsum = 0.f; const float bt = (KIND == 0) ? fB[trow] : 0.f;
;         const int nmax = wid | 1;
;         for (int n = 0; n <= nmax; ++n) { f32x4 s = (f32x4){0.f, 0.f, 0.f, 0.f};
	v_lshlrev_b32_e32 v70, 16, v70
	v_mul_f32_e32 v70, 0x3db504f3, v70
	v_mul_f32_e32 v70, v70, v71
	v_cvt_pk_bf16_f32 v70, v70, s0
	ds_write_b16 v68, v70
	ds_read_u16 v70, v68 offset:34816
	v_mul_f32_e32 v71, 0xbfb8aa3b, v67
	v_exp_f32_e32 v71, v71
	s_waitcnt lgkmcnt(0)
	v_lshlrev_b32_e32 v70, 16, v70
	v_mul_f32_e32 v70, v71, v70
	v_cvt_pk_bf16_f32 v70, v70, s0
	ds_write_b16 v68, v70 offset:34816
	v_fmac_f32_e32 v67, 0x3d800000, v129
	ds_read_u16 v69, v68 offset:272
	v_mul_f32_e32 v70, 0x3fb8aa3b, v67
	v_exp_f32_e32 v70, v70
	s_waitcnt lgkmcnt(0)
	v_lshlrev_b32_e32 v69, 16, v69
	v_mul_f32_e32 v69, 0x3db504f3, v69
	v_mul_f32_e32 v69, v69, v70
	v_cvt_pk_bf16_f32 v69, v69, s0
	ds_write_b16 v68, v69 offset:272
	ds_read_u16 v69, v68 offset:35088
	v_mul_f32_e32 v70, 0xbfb8aa3b, v67
	v_exp_f32_e32 v70, v70
	s_waitcnt lgkmcnt(0)
	v_lshlrev_b32_e32 v69, 16, v69
	v_mul_f32_e32 v69, v70, v69
	v_cvt_pk_bf16_f32 v69, v69, s0
	s_addk_i32 s0, 0x80
	ds_write_b16 v68, v69 offset:35088
	v_add_u32_e32 v68, 0x220, v68
	v_fmac_f32_e32 v67, 0x3d800000, v136
	ds_read_u16 v70, v68
	v_mul_f32_e32 v71, 0x3fb8aa3b, v67
	v_exp_f32_e32 v71, v71
	s_waitcnt lgkmcnt(0)
	v_lshlrev_b32_e32 v70, 16, v70
	v_mul_f32_e32 v70, 0x3db504f3, v70
	v_mul_f32_e32 v70, v70, v71
	v_cvt_pk_bf16_f32 v70, v70, s0
	ds_write_b16 v68, v70
	ds_read_u16 v70, v68 offset:34816
	v_mul_f32_e32 v71, 0xbfb8aa3b, v67
	v_exp_f32_e32 v71, v71
	s_waitcnt lgkmcnt(0)
	v_lshlrev_b32_e32 v70, 16, v70
	v_mul_f32_e32 v70, v71, v70
	v_cvt_pk_bf16_f32 v70, v70, s0
	ds_write_b16 v68, v70 offset:34816
	v_fmac_f32_e32 v67, 0x3d800000, v137
	ds_read_u16 v69, v68 offset:272
	v_mul_f32_e32 v70, 0x3fb8aa3b, v67
	v_exp_f32_e32 v70, v70
	s_waitcnt lgkmcnt(0)
	v_lshlrev_b32_e32 v69, 16, v69
	v_mul_f32_e32 v69, 0x3db504f3, v69
	v_mul_f32_e32 v69, v69, v70
	v_cvt_pk_bf16_f32 v69, v69, s0
	ds_write_b16 v68, v69 offset:272
	ds_read_u16 v69, v68 offset:35088
	v_mul_f32_e32 v70, 0xbfb8aa3b, v67
	v_exp_f32_e32 v70, v70
	s_waitcnt lgkmcnt(0)
	v_lshlrev_b32_e32 v69, 16, v69
	v_mul_f32_e32 v69, v70, v69
	v_cvt_pk_bf16_f32 v69, v69, s0
	s_addk_i32 s0, 0x80
	ds_write_b16 v68, v69 offset:35088
	v_add_u32_e32 v68, 0x220, v68
	v_fmac_f32_e32 v67, 0x3d800000, v138
	ds_read_u16 v70, v68
	v_mul_f32_e32 v71, 0x3fb8aa3b, v67
	v_exp_f32_e32 v71, v71
	s_waitcnt lgkmcnt(0)
	v_lshlrev_b32_e32 v70, 16, v70
	v_mul_f32_e32 v70, 0x3db504f3, v70
	v_mul_f32_e32 v70, v70, v71
	v_cvt_pk_bf16_f32 v70, v70, s0
	ds_write_b16 v68, v70
	ds_read_u16 v70, v68 offset:34816
	v_mul_f32_e32 v71, 0xbfb8aa3b, v67
	v_exp_f32_e32 v71, v71
	s_waitcnt lgkmcnt(0)
	v_lshlrev_b32_e32 v70, 16, v70
	v_mul_f32_e32 v70, v71, v70
	v_cvt_pk_bf16_f32 v70, v70, s0
	ds_write_b16 v68, v70 offset:34816
	v_fmac_f32_e32 v67, 0x3d800000, v139
	ds_read_u16 v69, v68 offset:272
	v_mul_f32_e32 v70, 0x3fb8aa3b, v67
	v_exp_f32_e32 v70, v70
	s_waitcnt lgkmcnt(0)
	v_lshlrev_b32_e32 v69, 16, v69
	v_mul_f32_e32 v69, 0x3db504f3, v69
	v_mul_f32_e32 v69, v69, v70
	v_cvt_pk_bf16_f32 v69, v69, s0
	ds_write_b16 v68, v69 offset:272
	ds_read_u16 v69, v68 offset:35088
	v_mul_f32_e32 v70, 0xbfb8aa3b, v67
	v_exp_f32_e32 v70, v70
	s_waitcnt lgkmcnt(0)
	v_lshlrev_b32_e32 v69, 16, v69
	v_mul_f32_e32 v69, v70, v69
	v_cvt_pk_bf16_f32 v69, v69, s0
	s_addk_i32 s0, 0x80
	ds_write_b16 v68, v69 offset:35088
	v_add_u32_e32 v68, 0x220, v68
	s_waitcnt lgkmcnt(0)
	s_barrier
	ds_read_b128 v[94:97], v225 offset:16384
	ds_read_b128 v[90:93], v225 offset:16448
	ds_read_b128 v[86:89], v225 offset:16512
	ds_read_b128 v[82:85], v225 offset:16576
	s_and_saveexec_b64 s[14:15], s[2:3]
	s_cbranch_execz .LBB0_707
	s_mov_b32 s0, 0
	s_mov_b64 s[82:83], 0
	v_mov_b32_e32 v34, v218
	v_mov_b32_e32 v35, v216
	v_mov_b32_e32 v36, v206
	s_branch .LBB0_705
